# plus weight-conversion load loops unrolled x2 with renamed registers: 32 loads in flight per wave
# speedup vs baseline: 1.0018x; 1.0018x over previous
; #define LAS __attribute__((address_space(3)))
; __device__ __forceinline__ void cvt_item(gfp W, int N, bf16* WT, int Kd, int k0, int n0, int drow0, LAS float* scr, int lane, gfp gk) {
; #pragma unroll 8
;     for (int i = 0; i < 32; ++i) { const int kk = 2 * i + (lane >> 5); scr[kk * 33 + (lane & 31)] = W[(size_t)(k0 + kk) * N + n0 + (lane & 31)]; }
.LBB0_123:
	v_mov_b32_e32 v103, v1
	s_lshl_b32 s30, s25, 1
	s_lshl_b32 s27, s23, 1
	v_or_b32_e32 v136, s30, v10
	s_add_i32 s33, s30, 4
	s_add_i32 s31, s27, 4
	s_add_i32 s34, s27, 8
	s_add_i32 s35, s30, 8
	v_add_u32_e32 v102, s0, v136
	v_or_b32_e32 v127, s33, v10
	v_or_b32_e32 v101, s27, v11
	s_add_i32 s36, s27, 12
	s_add_i32 s37, s30, 12
	s_add_i32 s38, s27, 16
	s_add_i32 s40, s27, 20
	s_add_i32 s42, s27, 24
	s_add_i32 s27, s27, 28
	v_or_b32_e32 v126, s31, v11
	v_or_b32_e32 v128, s34, v11
	v_or_b32_e32 v129, s35, v10
	v_lshlrev_b64 v[120:121], 13, v[102:103]
	v_add_u32_e32 v102, s0, v127
	v_mov_b32_e32 v105, v103
	v_mov_b32_e32 v107, v103
	v_mov_b32_e32 v109, v103
	s_add_i32 s39, s30, 16
	v_add_u32_e32 v104, s22, v101
	v_or_b32_e32 v130, s36, v11
	v_or_b32_e32 v131, s37, v10
	v_or_b32_e32 v132, s38, v11
	v_or_b32_e32 v134, s40, v11
	v_or_b32_e32 v137, s42, v11
	v_or_b32_e32 v139, s27, v11
	v_add_u32_e32 v106, s22, v126
	v_add_u32_e32 v108, s22, v128
	v_lshlrev_b64 v[122:123], 13, v[102:103]
	v_add_u32_e32 v102, s0, v129
	v_mov_b32_e32 v111, v103
	v_mov_b32_e32 v113, v103
	v_mov_b32_e32 v115, v103
	v_mov_b32_e32 v117, v103
	v_mov_b32_e32 v119, v103
	s_add_i32 s41, s30, 20
	v_or_b32_e32 v133, s39, v10
	v_lshlrev_b64 v[104:105], 13, v[104:105]
	v_add_u32_e32 v110, s22, v130
	v_add_u32_e32 v112, s22, v132
	v_add_u32_e32 v114, s22, v134
	v_add_u32_e32 v116, s22, v137
	v_add_u32_e32 v118, s22, v139
	v_lshl_add_u64 v[120:121], v[2:3], 0, v[120:121]
	v_lshlrev_b64 v[106:107], 13, v[106:107]
	v_lshlrev_b64 v[108:109], 13, v[108:109]
	v_lshlrev_b64 v[124:125], 13, v[102:103]
	v_add_u32_e32 v102, s0, v131
	s_add_i32 s43, s30, 24
	v_or_b32_e32 v135, s41, v10
	v_lshl_add_u64 v[104:105], v[2:3], 0, v[104:105]
	v_lshlrev_b64 v[110:111], 13, v[110:111]
	v_lshlrev_b64 v[112:113], 13, v[112:113]
	v_lshlrev_b64 v[114:115], 13, v[114:115]
	v_lshlrev_b64 v[116:117], 13, v[116:117]
	v_lshlrev_b64 v[118:119], 13, v[118:119]
	v_lshl_add_u64 v[122:123], v[2:3], 0, v[122:123]
	v_lshl_add_u64 v[106:107], v[2:3], 0, v[106:107]
	v_lshl_add_u64 v[108:109], v[2:3], 0, v[108:109]
	global_load_dword v141, v[120:121], off
	global_load_dword v142, v[104:105], off
	v_lshlrev_b64 v[120:121], 13, v[102:103]
	v_add_u32_e32 v102, s0, v133
	s_add_i32 s30, s30, 28
	v_or_b32_e32 v138, s43, v10
	v_lshl_add_u64 v[110:111], v[2:3], 0, v[110:111]
	v_lshl_add_u64 v[112:113], v[2:3], 0, v[112:113]
	v_lshl_add_u64 v[114:115], v[2:3], 0, v[114:115]
	v_lshl_add_u64 v[116:117], v[2:3], 0, v[116:117]
	v_lshl_add_u64 v[118:119], v[2:3], 0, v[118:119]
	global_load_dword v143, v[122:123], off
	global_load_dword v144, v[106:107], off
	global_load_dword v145, v[108:109], off
	global_load_dword v146, v[110:111], off
	global_load_dword v147, v[112:113], off
	global_load_dword v148, v[114:115], off
	global_load_dword v149, v[116:117], off
	global_load_dword v150, v[118:119], off
	v_lshl_add_u64 v[106:107], v[2:3], 0, v[120:121]
	v_lshlrev_b64 v[108:109], 13, v[102:103]
	v_add_u32_e32 v102, s0, v135
	v_or_b32_e32 v140, s30, v10
	v_lshl_add_u64 v[104:105], v[2:3], 0, v[124:125]
	global_load_dword v151, v[106:107], off
	global_load_dword v152, v[104:105], off
	v_lshlrev_b64 v[106:107], 13, v[102:103]
	v_add_u32_e32 v102, s0, v138
	v_lshl_add_u64 v[104:105], v[2:3], 0, v[108:109]
	v_lshlrev_b64 v[108:109], 13, v[102:103]
	v_add_u32_e32 v102, s0, v140
	v_lshlrev_b64 v[110:111], 13, v[102:103]
	v_lshl_add_u64 v[110:111], v[2:3], 0, v[110:111]
	v_lshl_add_u64 v[106:107], v[2:3], 0, v[106:107]
	v_lshl_add_u64 v[108:109], v[2:3], 0, v[108:109]
	global_load_dword v102, v[110:111], off
	global_load_dword v153, v[108:109], off
	global_load_dword v154, v[106:107], off
	global_load_dword v155, v[104:105], off
	s_add_i32 s25, s25, 16
	s_add_i32 s23, s23, 16
	s_add_i32 s26, s26, -16
	s_cmp_lg_u32 s26, 0
	s_lshl_b32 s30, s25, 1
	s_lshl_b32 s27, s23, 1
	v_or_b32_e32 v45, s30, v10
	s_add_i32 s33, s30, 4
	s_add_i32 s31, s27, 4
	s_add_i32 s34, s27, 8
	s_add_i32 s35, s30, 8
	v_add_u32_e32 v0, s0, v45
	v_or_b32_e32 v63, s33, v10
	v_or_b32_e32 v39, s27, v11
	s_add_i32 s36, s27, 12
	s_add_i32 s37, s30, 12
	s_add_i32 s38, s27, 16
	s_add_i32 s40, s27, 20
	s_add_i32 s42, s27, 24
	s_add_i32 s27, s27, 28
	v_or_b32_e32 v62, s31, v11
	v_or_b32_e32 v64, s34, v11
	v_or_b32_e32 v65, s35, v10
	v_lshlrev_b64 v[56:57], 13, v[0:1]
	v_add_u32_e32 v0, s0, v63
	v_mov_b32_e32 v5, v1
	v_mov_b32_e32 v7, v1
	v_mov_b32_e32 v9, v1
	s_add_i32 s39, s30, 16
	v_add_u32_e32 v4, s22, v39
	v_or_b32_e32 v66, s36, v11
	v_or_b32_e32 v67, s37, v10
	v_or_b32_e32 v68, s38, v11
	v_or_b32_e32 v70, s40, v11
	v_or_b32_e32 v72, s42, v11
	v_or_b32_e32 v74, s27, v11
	v_add_u32_e32 v6, s22, v62
	v_add_u32_e32 v8, s22, v64
	v_lshlrev_b64 v[58:59], 13, v[0:1]
	v_add_u32_e32 v0, s0, v65
	v_mov_b32_e32 v47, v1
	v_mov_b32_e32 v49, v1
	v_mov_b32_e32 v51, v1
	v_mov_b32_e32 v53, v1
	v_mov_b32_e32 v55, v1
	s_add_i32 s41, s30, 20
	v_or_b32_e32 v69, s39, v10
	v_lshlrev_b64 v[4:5], 13, v[4:5]
	v_add_u32_e32 v46, s22, v66
	v_add_u32_e32 v48, s22, v68
	v_add_u32_e32 v50, s22, v70
	v_add_u32_e32 v52, s22, v72
	v_add_u32_e32 v54, s22, v74
	v_lshl_add_u64 v[56:57], v[2:3], 0, v[56:57]
	v_lshlrev_b64 v[6:7], 13, v[6:7]
	v_lshlrev_b64 v[8:9], 13, v[8:9]
	v_lshlrev_b64 v[60:61], 13, v[0:1]
	v_add_u32_e32 v0, s0, v67
	s_add_i32 s43, s30, 24
	v_or_b32_e32 v71, s41, v10
	v_lshl_add_u64 v[4:5], v[2:3], 0, v[4:5]
	v_lshlrev_b64 v[46:47], 13, v[46:47]
	v_lshlrev_b64 v[48:49], 13, v[48:49]
	v_lshlrev_b64 v[50:51], 13, v[50:51]
	v_lshlrev_b64 v[52:53], 13, v[52:53]
	v_lshlrev_b64 v[54:55], 13, v[54:55]
	v_lshl_add_u64 v[58:59], v[2:3], 0, v[58:59]
	v_lshl_add_u64 v[6:7], v[2:3], 0, v[6:7]
; #define GAS __attribute__((address_space(1)))
; #define LAS __attribute__((address_space(3)))
; #define LDS_WAIT() asm volatile("s_waitcnt lgkmcnt(0)" ::: "memory")
; __device__ __forceinline__ unsigned pk2(float lo, float hi) { unsigned r; asm("v_cvt_pk_bf16_f32 %0, %1, %2" : "=v"(r) : "v"(lo), "v"(hi)); return r; }
; __device__ __forceinline__ void cvt_item(gfp W, int N, bf16* WT, int Kd, int k0, int n0, int drow0, LAS float* scr, int lane, gfp gk) {
;     ...
;     for (int i = 0; i < 32; ++i) { const int kk = 2 * i + (lane >> 5); scr[kk * 33 + (lane & 31)] = W[(size_t)(k0 + kk) * N + n0 + (lane & 31)]; }
;     const int c = lane & 7;
;     f32x4 ga = (f32x4){1.f, 1.f, 1.f, 1.f}, gb = ga;
;     if (gk != nullptr) { ga = *(const GAS f32x4*)(gk + k0 + 8 * c); gb = *(const GAS f32x4*)(gk + k0 + 8 * c + 4); }
;     LDS_WAIT(); asm volatile("" ::: "memory");
; #pragma unroll
;     for (int j = 0; j < 4; ++j) { const int n = (lane >> 3) + 8 * j; const LAS float* s = scr + (8 * c) * 33 + n;
;         v4u o; o.x = pk2(s[0 * 33] * ga[0], s[1 * 33] * ga[1]); o.y = pk2(s[2 * 33] * ga[2], s[3 * 33] * ga[3]); o.z = pk2(s[4 * 33] * gb[0], s[5 * 33] * gb[1]); o.w = pk2(s[6 * 33] * gb[2], s[7 * 33] * gb[3]);
;         *(GAS v4u*)(WT + (size_t)(drow0 + n) * Kd + k0 + 8 * c) = o; }
;     LDS_WAIT(); asm volatile("" ::: "memory");
	v_lshl_add_u64 v[8:9], v[2:3], 0, v[8:9]
	global_load_dword v76, v[56:57], off
	global_load_dword v77, v[4:5], off
	v_lshlrev_b64 v[56:57], 13, v[0:1]
	v_add_u32_e32 v0, s0, v69
	s_add_i32 s30, s30, 28
	v_or_b32_e32 v73, s43, v10
	v_lshl_add_u64 v[46:47], v[2:3], 0, v[46:47]
	v_lshl_add_u64 v[48:49], v[2:3], 0, v[48:49]
	v_lshl_add_u64 v[50:51], v[2:3], 0, v[50:51]
	v_lshl_add_u64 v[52:53], v[2:3], 0, v[52:53]
	v_lshl_add_u64 v[54:55], v[2:3], 0, v[54:55]
	global_load_dword v78, v[58:59], off
	global_load_dword v79, v[6:7], off
	global_load_dword v80, v[8:9], off
	global_load_dword v81, v[46:47], off
	global_load_dword v82, v[48:49], off
	global_load_dword v83, v[50:51], off
	global_load_dword v84, v[52:53], off
	global_load_dword v85, v[54:55], off
	v_lshl_add_u64 v[6:7], v[2:3], 0, v[56:57]
	v_lshlrev_b64 v[8:9], 13, v[0:1]
	v_add_u32_e32 v0, s0, v71
	v_or_b32_e32 v75, s30, v10
	v_lshl_add_u64 v[4:5], v[2:3], 0, v[60:61]
	global_load_dword v86, v[6:7], off
	global_load_dword v87, v[4:5], off
	v_lshlrev_b64 v[6:7], 13, v[0:1]
	v_add_u32_e32 v0, s0, v73
	v_lshl_add_u64 v[4:5], v[2:3], 0, v[8:9]
	v_lshlrev_b64 v[8:9], 13, v[0:1]
	v_add_u32_e32 v0, s0, v75
	v_lshlrev_b64 v[46:47], 13, v[0:1]
	v_lshl_add_u64 v[46:47], v[2:3], 0, v[46:47]
	v_lshl_add_u64 v[6:7], v[2:3], 0, v[6:7]
	v_lshl_add_u64 v[8:9], v[2:3], 0, v[8:9]
	global_load_dword v0, v[46:47], off
	global_load_dword v88, v[8:9], off
	global_load_dword v89, v[6:7], off
	global_load_dword v90, v[4:5], off
	v_mad_u64_u32 v[104:105], s[30:31], v136, s81, v[12:13]
	v_mad_u64_u32 v[106:107], s[30:31], v101, s81, v[12:13]
	v_mad_u64_u32 v[108:109], s[30:31], v127, s81, v[12:13]
	v_mad_u64_u32 v[110:111], s[30:31], v126, s81, v[12:13]
	v_mad_u64_u32 v[112:113], s[30:31], v129, s81, v[12:13]
	v_mad_u64_u32 v[114:115], s[30:31], v128, s81, v[12:13]
	v_mad_u64_u32 v[116:117], s[30:31], v131, s81, v[12:13]
	v_mad_u64_u32 v[118:119], s[30:31], v130, s81, v[12:13]
	v_mad_u64_u32 v[120:121], s[30:31], v133, s81, v[12:13]
	v_mad_u64_u32 v[122:123], s[30:31], v132, s81, v[12:13]
	v_mad_u64_u32 v[124:125], s[30:31], v135, s81, v[12:13]
	v_mad_u64_u32 v[126:127], s[30:31], v134, s81, v[12:13]
	v_mad_u64_u32 v[128:129], s[30:31], v138, s81, v[12:13]
	v_mad_u64_u32 v[130:131], s[30:31], v137, s81, v[12:13]
	v_mad_u64_u32 v[132:133], s[30:31], v140, s81, v[12:13]
	v_mad_u64_u32 v[134:135], s[30:31], v139, s81, v[12:13]
	s_waitcnt vmcnt(31)
	ds_write_b32 v104, v141
	s_waitcnt vmcnt(30)
	ds_write_b32 v106, v142
	s_waitcnt vmcnt(29)
	ds_write_b32 v108, v143
	s_waitcnt vmcnt(28)
	ds_write_b32 v110, v144
	s_waitcnt vmcnt(20)
	ds_write_b32 v112, v152
	ds_write_b32 v114, v145
	ds_write_b32 v116, v151
	ds_write_b32 v118, v146
	s_waitcnt vmcnt(16)
	ds_write_b32 v120, v155
	ds_write_b32 v122, v147
	ds_write_b32 v124, v154
	ds_write_b32 v126, v148
	ds_write_b32 v128, v153
	ds_write_b32 v130, v149
	ds_write_b32 v132, v102
	ds_write_b32 v134, v150
	v_mad_u64_u32 v[4:5], s[30:31], v45, s81, v[12:13]
	v_mad_u64_u32 v[6:7], s[30:31], v39, s81, v[12:13]
	v_mad_u64_u32 v[8:9], s[30:31], v63, s81, v[12:13]
	v_mad_u64_u32 v[46:47], s[30:31], v62, s81, v[12:13]
	v_mad_u64_u32 v[48:49], s[30:31], v65, s81, v[12:13]
	v_mad_u64_u32 v[50:51], s[30:31], v64, s81, v[12:13]
	v_mad_u64_u32 v[52:53], s[30:31], v67, s81, v[12:13]
	v_mad_u64_u32 v[54:55], s[30:31], v66, s81, v[12:13]
	v_mad_u64_u32 v[56:57], s[30:31], v69, s81, v[12:13]
	v_mad_u64_u32 v[58:59], s[30:31], v68, s81, v[12:13]
	v_mad_u64_u32 v[60:61], s[30:31], v71, s81, v[12:13]
	v_mad_u64_u32 v[62:63], s[30:31], v70, s81, v[12:13]
	v_mad_u64_u32 v[64:65], s[30:31], v73, s81, v[12:13]
	v_mad_u64_u32 v[66:67], s[30:31], v72, s81, v[12:13]
	v_mad_u64_u32 v[68:69], s[30:31], v75, s81, v[12:13]
	v_mad_u64_u32 v[70:71], s[30:31], v74, s81, v[12:13]
	s_waitcnt vmcnt(15)
	ds_write_b32 v4, v76
	s_waitcnt vmcnt(14)
	ds_write_b32 v6, v77
	s_waitcnt vmcnt(13)
	ds_write_b32 v8, v78
	s_waitcnt vmcnt(12)
	ds_write_b32 v46, v79
	s_waitcnt vmcnt(4)
	ds_write_b32 v48, v87
	ds_write_b32 v50, v80
	ds_write_b32 v52, v86
	ds_write_b32 v54, v81
	s_waitcnt vmcnt(0)
	ds_write_b32 v56, v90
	ds_write_b32 v58, v82
	ds_write_b32 v60, v89
	ds_write_b32 v62, v83
	ds_write_b32 v64, v88
	ds_write_b32 v66, v84
	ds_write_b32 v68, v0
	ds_write_b32 v70, v85
	s_add_i32 s25, s25, 16
	s_add_i32 s23, s23, 16
	s_add_i32 s26, s26, -16
	s_cmp_lg_u32 s26, 0
	s_waitcnt lgkmcnt(0)
	ds_read2_b32 v[6:7], v41 offset0:33 offset1:41
	ds_read2_b32 v[8:9], v41 offset1:8
	ds_read2_b32 v[46:47], v41 offset0:66 offset1:74
	ds_read2_b32 v[48:49], v41 offset0:99 offset1:107
	ds_read2_b32 v[50:51], v41 offset0:132 offset1:140
	ds_read2_b32 v[52:53], v41 offset0:165 offset1:173
	ds_read2_b32 v[54:55], v41 offset0:198 offset1:206
	ds_read2_b32 v[56:57], v41 offset0:231 offset1:239
	s_lshl_b32 s0, s0, 1
	v_or_b32_e32 v0, s24, v40
	v_lshl_add_u64 v[58:59], v[16:17], 0, s[0:1]
	v_lshlrev_b32_e32 v0, 12, v0
	v_lshl_add_u64 v[60:61], v[58:59], 0, v[0:1]
	s_waitcnt lgkmcnt(6)
	v_cvt_pk_bf16_f32 v2, v8, v6
	s_waitcnt lgkmcnt(4)
	v_cvt_pk_bf16_f32 v3, v46, v48
	s_waitcnt lgkmcnt(2)
	v_cvt_pk_bf16_f32 v4, v50, v52
	s_waitcnt lgkmcnt(0)
	v_cvt_pk_bf16_f32 v5, v54, v56
	global_store_dwordx4 v[60:61], v[2:5], off
	v_or_b32_e32 v0, s24, v42
	v_lshlrev_b32_e32 v0, 12, v0
	v_cvt_pk_bf16_f32 v2, v9, v7
	v_cvt_pk_bf16_f32 v3, v47, v49
	v_cvt_pk_bf16_f32 v4, v51, v53
	v_cvt_pk_bf16_f32 v5, v55, v57
	ds_read2_b32 v[8:9], v41 offset0:16 offset1:24
	ds_read2_b32 v[46:47], v41 offset0:49 offset1:57
	ds_read2_b32 v[48:49], v41 offset0:82 offset1:90
	ds_read2_b32 v[50:51], v41 offset0:115 offset1:123
	ds_read2_b32 v[52:53], v41 offset0:148 offset1:156
	ds_read2_b32 v[54:55], v41 offset0:181 offset1:189
	ds_read2_b32 v[56:57], v41 offset0:214 offset1:222
	ds_read2_b32 v[60:61], v41 offset0:247 offset1:255
	v_lshl_add_u64 v[6:7], v[58:59], 0, v[0:1]
	v_or_b32_e32 v0, s24, v43
	v_lshlrev_b32_e32 v0, 12, v0
	global_store_dwordx4 v[6:7], v[2:5], off
	v_lshl_add_u64 v[6:7], v[58:59], 0, v[0:1]
	v_or_b32_e32 v0, s24, v44
	v_lshlrev_b32_e32 v0, 12, v0
	s_waitcnt lgkmcnt(6)
	v_cvt_pk_bf16_f32 v2, v8, v46
	s_waitcnt lgkmcnt(4)
	v_cvt_pk_bf16_f32 v3, v48, v50
	s_waitcnt lgkmcnt(2)
	v_cvt_pk_bf16_f32 v4, v52, v54
	s_waitcnt lgkmcnt(0)
	v_cvt_pk_bf16_f32 v5, v56, v60
	global_store_dwordx4 v[6:7], v[2:5], off
	v_lshl_add_u64 v[6:7], v[58:59], 0, v[0:1]
	s_mov_b64 s[22:23], 0
	v_cvt_pk_bf16_f32 v2, v9, v47
	v_cvt_pk_bf16_f32 v3, v49, v51
	v_cvt_pk_bf16_f32 v4, v53, v55
	v_cvt_pk_bf16_f32 v5, v57, v61
	global_store_dwordx4 v[6:7], v[2:5], off
	s_waitcnt lgkmcnt(0)

; #define LAS __attribute__((address_space(3)))
; __device__ __forceinline__ void cvt_item(gfp W, int N, bf16* WT, int Kd, int k0, int n0, int drow0, LAS float* scr, int lane, gfp gk) {
; #pragma unroll 8
;     for (int i = 0; i < 32; ++i) { const int kk = 2 * i + (lane >> 5); scr[kk * 33 + (lane & 31)] = W[(size_t)(k0 + kk) * N + n0 + (lane & 31)]; }
.LBB0_127:
	v_mov_b32_e32 v103, v1
	s_lshl_b32 s30, s25, 1
	s_lshl_b32 s27, s23, 1
	v_or_b32_e32 v136, s30, v10
	s_add_i32 s33, s30, 4
	s_add_i32 s31, s27, 4
	s_add_i32 s34, s27, 8
	s_add_i32 s35, s30, 8
	v_add_u32_e32 v102, s0, v136
	v_or_b32_e32 v127, s33, v10
	v_or_b32_e32 v101, s27, v11
	s_add_i32 s36, s27, 12
	s_add_i32 s37, s30, 12
	s_add_i32 s38, s27, 16
	s_add_i32 s40, s27, 20
	s_add_i32 s42, s27, 24
	s_add_i32 s27, s27, 28
	v_or_b32_e32 v126, s31, v11
	v_or_b32_e32 v128, s34, v11
	v_or_b32_e32 v129, s35, v10
	v_lshlrev_b64 v[120:121], 13, v[102:103]
	v_add_u32_e32 v102, s0, v127
	v_mov_b32_e32 v105, v103
	v_mov_b32_e32 v107, v103
	v_mov_b32_e32 v109, v103
	s_add_i32 s39, s30, 16
	v_add_u32_e32 v104, s22, v101
	v_or_b32_e32 v130, s36, v11
	v_or_b32_e32 v131, s37, v10
	v_or_b32_e32 v132, s38, v11
	v_or_b32_e32 v134, s40, v11
	v_or_b32_e32 v137, s42, v11
	v_or_b32_e32 v139, s27, v11
	v_add_u32_e32 v106, s22, v126
	v_add_u32_e32 v108, s22, v128
	v_lshlrev_b64 v[122:123], 13, v[102:103]
	v_add_u32_e32 v102, s0, v129
	v_mov_b32_e32 v111, v103
	v_mov_b32_e32 v113, v103
	v_mov_b32_e32 v115, v103
	v_mov_b32_e32 v117, v103
	v_mov_b32_e32 v119, v103
	s_add_i32 s41, s30, 20
	v_or_b32_e32 v133, s39, v10
	v_lshlrev_b64 v[104:105], 13, v[104:105]
	v_add_u32_e32 v110, s22, v130
	v_add_u32_e32 v112, s22, v132
	v_add_u32_e32 v114, s22, v134
	v_add_u32_e32 v116, s22, v137
	v_add_u32_e32 v118, s22, v139
	v_lshl_add_u64 v[120:121], v[2:3], 0, v[120:121]
	v_lshlrev_b64 v[106:107], 13, v[106:107]
	v_lshlrev_b64 v[108:109], 13, v[108:109]
	v_lshlrev_b64 v[124:125], 13, v[102:103]
	v_add_u32_e32 v102, s0, v131
	s_add_i32 s43, s30, 24
	v_or_b32_e32 v135, s41, v10
	v_lshl_add_u64 v[104:105], v[2:3], 0, v[104:105]
	v_lshlrev_b64 v[110:111], 13, v[110:111]
	v_lshlrev_b64 v[112:113], 13, v[112:113]
	v_lshlrev_b64 v[114:115], 13, v[114:115]
	v_lshlrev_b64 v[116:117], 13, v[116:117]
	v_lshlrev_b64 v[118:119], 13, v[118:119]
	v_lshl_add_u64 v[122:123], v[2:3], 0, v[122:123]
	v_lshl_add_u64 v[106:107], v[2:3], 0, v[106:107]
	v_lshl_add_u64 v[108:109], v[2:3], 0, v[108:109]
	global_load_dword v141, v[120:121], off
	global_load_dword v142, v[104:105], off
	v_lshlrev_b64 v[120:121], 13, v[102:103]
	v_add_u32_e32 v102, s0, v133
	s_add_i32 s30, s30, 28
	v_or_b32_e32 v138, s43, v10
	v_lshl_add_u64 v[110:111], v[2:3], 0, v[110:111]
	v_lshl_add_u64 v[112:113], v[2:3], 0, v[112:113]
	v_lshl_add_u64 v[114:115], v[2:3], 0, v[114:115]
	v_lshl_add_u64 v[116:117], v[2:3], 0, v[116:117]
	v_lshl_add_u64 v[118:119], v[2:3], 0, v[118:119]
	global_load_dword v143, v[122:123], off
	global_load_dword v144, v[106:107], off
	global_load_dword v145, v[108:109], off
	global_load_dword v146, v[110:111], off
	global_load_dword v147, v[112:113], off
	global_load_dword v148, v[114:115], off
	global_load_dword v149, v[116:117], off
	global_load_dword v150, v[118:119], off
	v_lshl_add_u64 v[106:107], v[2:3], 0, v[120:121]
	v_lshlrev_b64 v[108:109], 13, v[102:103]
	v_add_u32_e32 v102, s0, v135
	v_or_b32_e32 v140, s30, v10
	v_lshl_add_u64 v[104:105], v[2:3], 0, v[124:125]
	global_load_dword v151, v[106:107], off
	global_load_dword v152, v[104:105], off
	v_lshlrev_b64 v[106:107], 13, v[102:103]
	v_add_u32_e32 v102, s0, v138
	v_lshl_add_u64 v[104:105], v[2:3], 0, v[108:109]
	v_lshlrev_b64 v[108:109], 13, v[102:103]
	v_add_u32_e32 v102, s0, v140
	v_lshlrev_b64 v[110:111], 13, v[102:103]
	v_lshl_add_u64 v[110:111], v[2:3], 0, v[110:111]
	v_lshl_add_u64 v[106:107], v[2:3], 0, v[106:107]
	v_lshl_add_u64 v[108:109], v[2:3], 0, v[108:109]
	global_load_dword v102, v[110:111], off
	global_load_dword v153, v[108:109], off
	global_load_dword v154, v[106:107], off
	global_load_dword v155, v[104:105], off
	s_add_i32 s25, s25, 16
	s_add_i32 s23, s23, 16
	s_add_i32 s26, s26, -16
	s_cmp_lg_u32 s26, 0
	s_lshl_b32 s30, s25, 1
	s_lshl_b32 s27, s23, 1
	v_or_b32_e32 v45, s30, v10
	s_add_i32 s33, s30, 4
	s_add_i32 s31, s27, 4
	s_add_i32 s34, s27, 8
	s_add_i32 s35, s30, 8
	v_add_u32_e32 v0, s0, v45
	v_or_b32_e32 v63, s33, v10
	v_or_b32_e32 v39, s27, v11
	s_add_i32 s36, s27, 12
	s_add_i32 s37, s30, 12
	s_add_i32 s38, s27, 16
	s_add_i32 s40, s27, 20
	s_add_i32 s42, s27, 24
	s_add_i32 s27, s27, 28
	v_or_b32_e32 v62, s31, v11
	v_or_b32_e32 v64, s34, v11
	v_or_b32_e32 v65, s35, v10
	v_lshlrev_b64 v[56:57], 13, v[0:1]
	v_add_u32_e32 v0, s0, v63
	v_mov_b32_e32 v5, v1
	v_mov_b32_e32 v7, v1
	v_mov_b32_e32 v9, v1
	s_add_i32 s39, s30, 16
	v_add_u32_e32 v4, s22, v39
	v_or_b32_e32 v66, s36, v11
	v_or_b32_e32 v67, s37, v10
	v_or_b32_e32 v68, s38, v11
	v_or_b32_e32 v70, s40, v11
	v_or_b32_e32 v72, s42, v11
	v_or_b32_e32 v74, s27, v11
	v_add_u32_e32 v6, s22, v62
	v_add_u32_e32 v8, s22, v64
	v_lshlrev_b64 v[58:59], 13, v[0:1]
	v_add_u32_e32 v0, s0, v65
	v_mov_b32_e32 v47, v1
	v_mov_b32_e32 v49, v1
	v_mov_b32_e32 v51, v1
	v_mov_b32_e32 v53, v1
	v_mov_b32_e32 v55, v1
	s_add_i32 s41, s30, 20
	v_or_b32_e32 v69, s39, v10
	v_lshlrev_b64 v[4:5], 13, v[4:5]
	v_add_u32_e32 v46, s22, v66
	v_add_u32_e32 v48, s22, v68
	v_add_u32_e32 v50, s22, v70
	v_add_u32_e32 v52, s22, v72
	v_add_u32_e32 v54, s22, v74
	v_lshl_add_u64 v[56:57], v[2:3], 0, v[56:57]
	v_lshlrev_b64 v[6:7], 13, v[6:7]
	v_lshlrev_b64 v[8:9], 13, v[8:9]
	v_lshlrev_b64 v[60:61], 13, v[0:1]
	v_add_u32_e32 v0, s0, v67
	s_add_i32 s43, s30, 24
	v_or_b32_e32 v71, s41, v10
	v_lshl_add_u64 v[4:5], v[2:3], 0, v[4:5]
	v_lshlrev_b64 v[46:47], 13, v[46:47]
	v_lshlrev_b64 v[48:49], 13, v[48:49]
	v_lshlrev_b64 v[50:51], 13, v[50:51]
	v_lshlrev_b64 v[52:53], 13, v[52:53]
	v_lshlrev_b64 v[54:55], 13, v[54:55]
	v_lshl_add_u64 v[58:59], v[2:3], 0, v[58:59]
	v_lshl_add_u64 v[6:7], v[2:3], 0, v[6:7]
; #define GAS __attribute__((address_space(1)))
; #define LAS __attribute__((address_space(3)))
; #define LDS_WAIT() asm volatile("s_waitcnt lgkmcnt(0)" ::: "memory")
; __device__ __forceinline__ unsigned pk2(float lo, float hi) { unsigned r; asm("v_cvt_pk_bf16_f32 %0, %1, %2" : "=v"(r) : "v"(lo), "v"(hi)); return r; }
; __device__ __forceinline__ void cvt_item(gfp W, int N, bf16* WT, int Kd, int k0, int n0, int drow0, LAS float* scr, int lane, gfp gk) {
;     ...
;     for (int i = 0; i < 32; ++i) { const int kk = 2 * i + (lane >> 5); scr[kk * 33 + (lane & 31)] = W[(size_t)(k0 + kk) * N + n0 + (lane & 31)]; }
;     const int c = lane & 7;
;     f32x4 ga = (f32x4){1.f, 1.f, 1.f, 1.f}, gb = ga;
;     if (gk != nullptr) { ga = *(const GAS f32x4*)(gk + k0 + 8 * c); gb = *(const GAS f32x4*)(gk + k0 + 8 * c + 4); }
;     LDS_WAIT(); asm volatile("" ::: "memory");
; #pragma unroll
;     for (int j = 0; j < 4; ++j) { const int n = (lane >> 3) + 8 * j; const LAS float* s = scr + (8 * c) * 33 + n;
;         v4u o; o.x = pk2(s[0 * 33] * ga[0], s[1 * 33] * ga[1]); o.y = pk2(s[2 * 33] * ga[2], s[3 * 33] * ga[3]); o.z = pk2(s[4 * 33] * gb[0], s[5 * 33] * gb[1]); o.w = pk2(s[6 * 33] * gb[2], s[7 * 33] * gb[3]);
;         *(GAS v4u*)(WT + (size_t)(drow0 + n) * Kd + k0 + 8 * c) = o; }
;     LDS_WAIT(); asm volatile("" ::: "memory");
	v_lshl_add_u64 v[8:9], v[2:3], 0, v[8:9]
	global_load_dword v76, v[56:57], off
	global_load_dword v77, v[4:5], off
	v_lshlrev_b64 v[56:57], 13, v[0:1]
	v_add_u32_e32 v0, s0, v69
	s_add_i32 s30, s30, 28
	v_or_b32_e32 v73, s43, v10
	v_lshl_add_u64 v[46:47], v[2:3], 0, v[46:47]
	v_lshl_add_u64 v[48:49], v[2:3], 0, v[48:49]
	v_lshl_add_u64 v[50:51], v[2:3], 0, v[50:51]
	v_lshl_add_u64 v[52:53], v[2:3], 0, v[52:53]
	v_lshl_add_u64 v[54:55], v[2:3], 0, v[54:55]
	global_load_dword v78, v[58:59], off
	global_load_dword v79, v[6:7], off
	global_load_dword v80, v[8:9], off
	global_load_dword v81, v[46:47], off
	global_load_dword v82, v[48:49], off
	global_load_dword v83, v[50:51], off
	global_load_dword v84, v[52:53], off
	global_load_dword v85, v[54:55], off
	v_lshl_add_u64 v[6:7], v[2:3], 0, v[56:57]
	v_lshlrev_b64 v[8:9], 13, v[0:1]
	v_add_u32_e32 v0, s0, v71
	v_or_b32_e32 v75, s30, v10
	v_lshl_add_u64 v[4:5], v[2:3], 0, v[60:61]
	global_load_dword v86, v[6:7], off
	global_load_dword v87, v[4:5], off
	v_lshlrev_b64 v[6:7], 13, v[0:1]
	v_add_u32_e32 v0, s0, v73
	v_lshl_add_u64 v[4:5], v[2:3], 0, v[8:9]
	v_lshlrev_b64 v[8:9], 13, v[0:1]
	v_add_u32_e32 v0, s0, v75
	v_lshlrev_b64 v[46:47], 13, v[0:1]
	v_lshl_add_u64 v[46:47], v[2:3], 0, v[46:47]
	v_lshl_add_u64 v[6:7], v[2:3], 0, v[6:7]
	v_lshl_add_u64 v[8:9], v[2:3], 0, v[8:9]
	global_load_dword v0, v[46:47], off
	global_load_dword v88, v[8:9], off
	global_load_dword v89, v[6:7], off
	global_load_dword v90, v[4:5], off
	v_mad_u64_u32 v[104:105], s[30:31], v136, s81, v[12:13]
	v_mad_u64_u32 v[106:107], s[30:31], v101, s81, v[12:13]
	v_mad_u64_u32 v[108:109], s[30:31], v127, s81, v[12:13]
	v_mad_u64_u32 v[110:111], s[30:31], v126, s81, v[12:13]
	v_mad_u64_u32 v[112:113], s[30:31], v129, s81, v[12:13]
	v_mad_u64_u32 v[114:115], s[30:31], v128, s81, v[12:13]
	v_mad_u64_u32 v[116:117], s[30:31], v131, s81, v[12:13]
	v_mad_u64_u32 v[118:119], s[30:31], v130, s81, v[12:13]
	v_mad_u64_u32 v[120:121], s[30:31], v133, s81, v[12:13]
	v_mad_u64_u32 v[122:123], s[30:31], v132, s81, v[12:13]
	v_mad_u64_u32 v[124:125], s[30:31], v135, s81, v[12:13]
	v_mad_u64_u32 v[126:127], s[30:31], v134, s81, v[12:13]
	v_mad_u64_u32 v[128:129], s[30:31], v138, s81, v[12:13]
	v_mad_u64_u32 v[130:131], s[30:31], v137, s81, v[12:13]
	v_mad_u64_u32 v[132:133], s[30:31], v140, s81, v[12:13]
	v_mad_u64_u32 v[134:135], s[30:31], v139, s81, v[12:13]
	s_waitcnt vmcnt(31)
	ds_write_b32 v104, v141
	s_waitcnt vmcnt(30)
	ds_write_b32 v106, v142
	s_waitcnt vmcnt(29)
	ds_write_b32 v108, v143
	s_waitcnt vmcnt(28)
	ds_write_b32 v110, v144
	s_waitcnt vmcnt(20)
	ds_write_b32 v112, v152
	ds_write_b32 v114, v145
	ds_write_b32 v116, v151
	ds_write_b32 v118, v146
	s_waitcnt vmcnt(16)
	ds_write_b32 v120, v155
	ds_write_b32 v122, v147
	ds_write_b32 v124, v154
	ds_write_b32 v126, v148
	ds_write_b32 v128, v153
	ds_write_b32 v130, v149
	ds_write_b32 v132, v102
	ds_write_b32 v134, v150
	v_mad_u64_u32 v[4:5], s[30:31], v45, s81, v[12:13]
	v_mad_u64_u32 v[6:7], s[30:31], v39, s81, v[12:13]
	v_mad_u64_u32 v[8:9], s[30:31], v63, s81, v[12:13]
	v_mad_u64_u32 v[46:47], s[30:31], v62, s81, v[12:13]
	v_mad_u64_u32 v[48:49], s[30:31], v65, s81, v[12:13]
	v_mad_u64_u32 v[50:51], s[30:31], v64, s81, v[12:13]
	v_mad_u64_u32 v[52:53], s[30:31], v67, s81, v[12:13]
	v_mad_u64_u32 v[54:55], s[30:31], v66, s81, v[12:13]
	v_mad_u64_u32 v[56:57], s[30:31], v69, s81, v[12:13]
	v_mad_u64_u32 v[58:59], s[30:31], v68, s81, v[12:13]
	v_mad_u64_u32 v[60:61], s[30:31], v71, s81, v[12:13]
	v_mad_u64_u32 v[62:63], s[30:31], v70, s81, v[12:13]
	v_mad_u64_u32 v[64:65], s[30:31], v73, s81, v[12:13]
	v_mad_u64_u32 v[66:67], s[30:31], v72, s81, v[12:13]
	v_mad_u64_u32 v[68:69], s[30:31], v75, s81, v[12:13]
	v_mad_u64_u32 v[70:71], s[30:31], v74, s81, v[12:13]
	s_waitcnt vmcnt(15)
	ds_write_b32 v4, v76
	s_waitcnt vmcnt(14)
	ds_write_b32 v6, v77
	s_waitcnt vmcnt(13)
	ds_write_b32 v8, v78
	s_waitcnt vmcnt(12)
	ds_write_b32 v46, v79
	s_waitcnt vmcnt(4)
	ds_write_b32 v48, v87
	ds_write_b32 v50, v80
	ds_write_b32 v52, v86
	ds_write_b32 v54, v81
	s_waitcnt vmcnt(0)
	ds_write_b32 v56, v90
	ds_write_b32 v58, v82
	ds_write_b32 v60, v89
	ds_write_b32 v62, v83
	ds_write_b32 v64, v88
	ds_write_b32 v66, v84
	ds_write_b32 v68, v0
	ds_write_b32 v70, v85
	s_add_i32 s25, s25, 16
	s_add_i32 s23, s23, 16
	s_add_i32 s26, s26, -16
	s_cmp_lg_u32 s26, 0
	s_waitcnt lgkmcnt(0)
	ds_read2_b32 v[6:7], v41 offset0:33 offset1:41
	ds_read2_b32 v[8:9], v41 offset1:8
	ds_read2_b32 v[46:47], v41 offset0:66 offset1:74
	ds_read2_b32 v[48:49], v41 offset0:99 offset1:107
	ds_read2_b32 v[50:51], v41 offset0:132 offset1:140
	ds_read2_b32 v[52:53], v41 offset0:165 offset1:173
	ds_read2_b32 v[54:55], v41 offset0:198 offset1:206
	ds_read2_b32 v[56:57], v41 offset0:231 offset1:239
	s_lshl_b32 s0, s0, 1
	v_or_b32_e32 v0, s24, v40
	v_lshl_add_u64 v[58:59], v[18:19], 0, s[0:1]
	v_lshlrev_b32_e32 v0, 11, v0
	v_lshl_add_u64 v[60:61], v[58:59], 0, v[0:1]
	s_waitcnt lgkmcnt(6)
	v_cvt_pk_bf16_f32 v2, v8, v6
	s_waitcnt lgkmcnt(4)
	v_cvt_pk_bf16_f32 v3, v46, v48
	s_waitcnt lgkmcnt(2)
	v_cvt_pk_bf16_f32 v4, v50, v52
	s_waitcnt lgkmcnt(0)
	v_cvt_pk_bf16_f32 v5, v54, v56
	global_store_dwordx4 v[60:61], v[2:5], off
	v_or_b32_e32 v0, s24, v42
	v_lshlrev_b32_e32 v0, 11, v0
	v_cvt_pk_bf16_f32 v2, v9, v7
	v_cvt_pk_bf16_f32 v3, v47, v49
	v_cvt_pk_bf16_f32 v4, v51, v53
	v_cvt_pk_bf16_f32 v5, v55, v57
	ds_read2_b32 v[8:9], v41 offset0:16 offset1:24
	ds_read2_b32 v[46:47], v41 offset0:49 offset1:57
	ds_read2_b32 v[48:49], v41 offset0:82 offset1:90
	ds_read2_b32 v[50:51], v41 offset0:115 offset1:123
	ds_read2_b32 v[52:53], v41 offset0:148 offset1:156
	ds_read2_b32 v[54:55], v41 offset0:181 offset1:189
	ds_read2_b32 v[56:57], v41 offset0:214 offset1:222
	ds_read2_b32 v[60:61], v41 offset0:247 offset1:255
	v_lshl_add_u64 v[6:7], v[58:59], 0, v[0:1]
	v_or_b32_e32 v0, s24, v43
	v_lshlrev_b32_e32 v0, 11, v0
	global_store_dwordx4 v[6:7], v[2:5], off
	v_lshl_add_u64 v[6:7], v[58:59], 0, v[0:1]
	v_or_b32_e32 v0, s24, v44
	v_lshlrev_b32_e32 v0, 11, v0
	s_waitcnt lgkmcnt(6)
	v_cvt_pk_bf16_f32 v2, v8, v46
	s_waitcnt lgkmcnt(4)
	v_cvt_pk_bf16_f32 v3, v48, v50
	s_waitcnt lgkmcnt(2)
	v_cvt_pk_bf16_f32 v4, v52, v54
	s_waitcnt lgkmcnt(0)
	v_cvt_pk_bf16_f32 v5, v56, v60
	global_store_dwordx4 v[6:7], v[2:5], off
	v_lshl_add_u64 v[6:7], v[58:59], 0, v[0:1]
	s_nop 0
	v_cvt_pk_bf16_f32 v2, v9, v47
	v_cvt_pk_bf16_f32 v3, v49, v51
	v_cvt_pk_bf16_f32 v4, v53, v55
	v_cvt_pk_bf16_f32 v5, v57, v61
	global_store_dwordx4 v[6:7], v[2:5], off
	s_waitcnt lgkmcnt(0)

; #define LAS __attribute__((address_space(3)))
; __device__ __forceinline__ void cvt_item(gfp W, int N, bf16* WT, int Kd, int k0, int n0, int drow0, LAS float* scr, int lane, gfp gk) {
; #pragma unroll 8
;     for (int i = 0; i < 32; ++i) { const int kk = 2 * i + (lane >> 5); scr[kk * 33 + (lane & 31)] = W[(size_t)(k0 + kk) * N + n0 + (lane & 31)]; }
.LBB0_132:
	v_mov_b32_e32 v103, v1
	s_lshl_b32 s30, s25, 1
	s_lshl_b32 s27, s24, 1
	v_or_b32_e32 v136, s30, v10
	s_add_i32 s33, s30, 4
	s_add_i32 s31, s27, 4
	s_add_i32 s34, s27, 8
	s_add_i32 s35, s30, 8
	v_add_u32_e32 v102, s0, v136
	v_or_b32_e32 v127, s33, v10
	v_or_b32_e32 v101, s27, v11
	s_add_i32 s36, s27, 12
	s_add_i32 s37, s30, 12
	s_add_i32 s38, s27, 16
	s_add_i32 s40, s27, 20
	s_add_i32 s42, s27, 24
	s_add_i32 s27, s27, 28
	v_or_b32_e32 v126, s31, v11
	v_or_b32_e32 v128, s34, v11
	v_or_b32_e32 v129, s35, v10
	v_lshlrev_b64 v[120:121], 13, v[102:103]
	v_add_u32_e32 v102, s0, v127
	v_mov_b32_e32 v105, v103
	v_mov_b32_e32 v107, v103
	v_mov_b32_e32 v109, v103
	s_add_i32 s39, s30, 16
	v_add_u32_e32 v104, s23, v101
	v_or_b32_e32 v130, s36, v11
	v_or_b32_e32 v131, s37, v10
	v_or_b32_e32 v132, s38, v11
	v_or_b32_e32 v134, s40, v11
	v_or_b32_e32 v137, s42, v11
	v_or_b32_e32 v139, s27, v11
	v_add_u32_e32 v106, s23, v126
	v_add_u32_e32 v108, s23, v128
	v_lshlrev_b64 v[122:123], 13, v[102:103]
	v_add_u32_e32 v102, s0, v129
	v_mov_b32_e32 v111, v103
	v_mov_b32_e32 v113, v103
	v_mov_b32_e32 v115, v103
	v_mov_b32_e32 v117, v103
	v_mov_b32_e32 v119, v103
	s_add_i32 s41, s30, 20
	v_or_b32_e32 v133, s39, v10
	v_lshlrev_b64 v[104:105], 13, v[104:105]
	v_add_u32_e32 v110, s23, v130
	v_add_u32_e32 v112, s23, v132
	v_add_u32_e32 v114, s23, v134
	v_add_u32_e32 v116, s23, v137
	v_add_u32_e32 v118, s23, v139
	v_lshl_add_u64 v[120:121], v[2:3], 0, v[120:121]
	v_lshlrev_b64 v[106:107], 13, v[106:107]
	v_lshlrev_b64 v[108:109], 13, v[108:109]
	v_lshlrev_b64 v[124:125], 13, v[102:103]
	v_add_u32_e32 v102, s0, v131
	s_add_i32 s43, s30, 24
	v_or_b32_e32 v135, s41, v10
	v_lshl_add_u64 v[104:105], v[2:3], 0, v[104:105]
	v_lshlrev_b64 v[110:111], 13, v[110:111]
	v_lshlrev_b64 v[112:113], 13, v[112:113]
	v_lshlrev_b64 v[114:115], 13, v[114:115]
	v_lshlrev_b64 v[116:117], 13, v[116:117]
	v_lshlrev_b64 v[118:119], 13, v[118:119]
	v_lshl_add_u64 v[122:123], v[2:3], 0, v[122:123]
	v_lshl_add_u64 v[106:107], v[2:3], 0, v[106:107]
	v_lshl_add_u64 v[108:109], v[2:3], 0, v[108:109]
	global_load_dword v141, v[120:121], off
	global_load_dword v142, v[104:105], off
	v_lshlrev_b64 v[120:121], 13, v[102:103]
	v_add_u32_e32 v102, s0, v133
	s_add_i32 s30, s30, 28
	v_or_b32_e32 v138, s43, v10
	v_lshl_add_u64 v[110:111], v[2:3], 0, v[110:111]
	v_lshl_add_u64 v[112:113], v[2:3], 0, v[112:113]
	v_lshl_add_u64 v[114:115], v[2:3], 0, v[114:115]
	v_lshl_add_u64 v[116:117], v[2:3], 0, v[116:117]
	v_lshl_add_u64 v[118:119], v[2:3], 0, v[118:119]
	global_load_dword v143, v[122:123], off
	global_load_dword v144, v[106:107], off
	global_load_dword v145, v[108:109], off
	global_load_dword v146, v[110:111], off
	global_load_dword v147, v[112:113], off
	global_load_dword v148, v[114:115], off
	global_load_dword v149, v[116:117], off
	global_load_dword v150, v[118:119], off
	v_lshl_add_u64 v[106:107], v[2:3], 0, v[120:121]
	v_lshlrev_b64 v[108:109], 13, v[102:103]
	v_add_u32_e32 v102, s0, v135
	v_or_b32_e32 v140, s30, v10
	v_lshl_add_u64 v[104:105], v[2:3], 0, v[124:125]
	global_load_dword v151, v[106:107], off
	global_load_dword v152, v[104:105], off
	v_lshlrev_b64 v[106:107], 13, v[102:103]
	v_add_u32_e32 v102, s0, v138
	v_lshl_add_u64 v[104:105], v[2:3], 0, v[108:109]
	v_lshlrev_b64 v[108:109], 13, v[102:103]
	v_add_u32_e32 v102, s0, v140
	v_lshlrev_b64 v[110:111], 13, v[102:103]
	v_lshl_add_u64 v[110:111], v[2:3], 0, v[110:111]
	v_lshl_add_u64 v[106:107], v[2:3], 0, v[106:107]
	v_lshl_add_u64 v[108:109], v[2:3], 0, v[108:109]
	global_load_dword v102, v[110:111], off
	global_load_dword v153, v[108:109], off
	global_load_dword v154, v[106:107], off
	global_load_dword v155, v[104:105], off
	s_add_i32 s25, s25, 16
	s_add_i32 s24, s24, 16
	s_add_i32 s26, s26, -16
	s_cmp_lg_u32 s26, 0
	s_lshl_b32 s30, s25, 1
	s_lshl_b32 s27, s24, 1
	v_or_b32_e32 v45, s30, v10
	s_add_i32 s33, s30, 4
	s_add_i32 s31, s27, 4
	s_add_i32 s34, s27, 8
	s_add_i32 s35, s30, 8
	v_add_u32_e32 v0, s0, v45
	v_or_b32_e32 v63, s33, v10
	v_or_b32_e32 v39, s27, v11
	s_add_i32 s36, s27, 12
	s_add_i32 s37, s30, 12
	s_add_i32 s38, s27, 16
	s_add_i32 s40, s27, 20
	s_add_i32 s42, s27, 24
	s_add_i32 s27, s27, 28
	v_or_b32_e32 v62, s31, v11
	v_or_b32_e32 v64, s34, v11
	v_or_b32_e32 v65, s35, v10
	v_lshlrev_b64 v[56:57], 13, v[0:1]
	v_add_u32_e32 v0, s0, v63
	v_mov_b32_e32 v5, v1
	v_mov_b32_e32 v7, v1
	v_mov_b32_e32 v9, v1
	s_add_i32 s39, s30, 16
	v_add_u32_e32 v4, s23, v39
	v_or_b32_e32 v66, s36, v11
	v_or_b32_e32 v67, s37, v10
	v_or_b32_e32 v68, s38, v11
	v_or_b32_e32 v70, s40, v11
	v_or_b32_e32 v72, s42, v11
	v_or_b32_e32 v74, s27, v11
	v_add_u32_e32 v6, s23, v62
	v_add_u32_e32 v8, s23, v64
	v_lshlrev_b64 v[58:59], 13, v[0:1]
	v_add_u32_e32 v0, s0, v65
	v_mov_b32_e32 v47, v1
	v_mov_b32_e32 v49, v1
	v_mov_b32_e32 v51, v1
	v_mov_b32_e32 v53, v1
	v_mov_b32_e32 v55, v1
	s_add_i32 s41, s30, 20
	v_or_b32_e32 v69, s39, v10
	v_lshlrev_b64 v[4:5], 13, v[4:5]
	v_add_u32_e32 v46, s23, v66
	v_add_u32_e32 v48, s23, v68
	v_add_u32_e32 v50, s23, v70
	v_add_u32_e32 v52, s23, v72
	v_add_u32_e32 v54, s23, v74
	v_lshl_add_u64 v[56:57], v[2:3], 0, v[56:57]
	v_lshlrev_b64 v[6:7], 13, v[6:7]
	v_lshlrev_b64 v[8:9], 13, v[8:9]
	v_lshlrev_b64 v[60:61], 13, v[0:1]
	v_add_u32_e32 v0, s0, v67
	s_add_i32 s43, s30, 24
	v_or_b32_e32 v71, s41, v10
	v_lshl_add_u64 v[4:5], v[2:3], 0, v[4:5]
	v_lshlrev_b64 v[46:47], 13, v[46:47]
	v_lshlrev_b64 v[48:49], 13, v[48:49]
	v_lshlrev_b64 v[50:51], 13, v[50:51]
	v_lshlrev_b64 v[52:53], 13, v[52:53]
	v_lshlrev_b64 v[54:55], 13, v[54:55]
	v_lshl_add_u64 v[58:59], v[2:3], 0, v[58:59]
	v_lshl_add_u64 v[6:7], v[2:3], 0, v[6:7]
; #define GAS __attribute__((address_space(1)))
; #define LAS __attribute__((address_space(3)))
; #define LDS_WAIT() asm volatile("s_waitcnt lgkmcnt(0)" ::: "memory")
; __device__ __forceinline__ unsigned pk2(float lo, float hi) { unsigned r; asm("v_cvt_pk_bf16_f32 %0, %1, %2" : "=v"(r) : "v"(lo), "v"(hi)); return r; }
; __device__ __forceinline__ void cvt_item(gfp W, int N, bf16* WT, int Kd, int k0, int n0, int drow0, LAS float* scr, int lane, gfp gk) {
;     ...
;     for (int i = 0; i < 32; ++i) { const int kk = 2 * i + (lane >> 5); scr[kk * 33 + (lane & 31)] = W[(size_t)(k0 + kk) * N + n0 + (lane & 31)]; }
;     const int c = lane & 7;
;     f32x4 ga = (f32x4){1.f, 1.f, 1.f, 1.f}, gb = ga;
;     if (gk != nullptr) { ga = *(const GAS f32x4*)(gk + k0 + 8 * c); gb = *(const GAS f32x4*)(gk + k0 + 8 * c + 4); }
;     LDS_WAIT(); asm volatile("" ::: "memory");
; #pragma unroll
;     for (int j = 0; j < 4; ++j) { const int n = (lane >> 3) + 8 * j; const LAS float* s = scr + (8 * c) * 33 + n;
;         v4u o; o.x = pk2(s[0 * 33] * ga[0], s[1 * 33] * ga[1]); o.y = pk2(s[2 * 33] * ga[2], s[3 * 33] * ga[3]); o.z = pk2(s[4 * 33] * gb[0], s[5 * 33] * gb[1]); o.w = pk2(s[6 * 33] * gb[2], s[7 * 33] * gb[3]);
;         *(GAS v4u*)(WT + (size_t)(drow0 + n) * Kd + k0 + 8 * c) = o; }
;     LDS_WAIT(); asm volatile("" ::: "memory");
	v_lshl_add_u64 v[8:9], v[2:3], 0, v[8:9]
	global_load_dword v76, v[56:57], off
	global_load_dword v77, v[4:5], off
	v_lshlrev_b64 v[56:57], 13, v[0:1]
	v_add_u32_e32 v0, s0, v69
	s_add_i32 s30, s30, 28
	v_or_b32_e32 v73, s43, v10
	v_lshl_add_u64 v[46:47], v[2:3], 0, v[46:47]
	v_lshl_add_u64 v[48:49], v[2:3], 0, v[48:49]
	v_lshl_add_u64 v[50:51], v[2:3], 0, v[50:51]
	v_lshl_add_u64 v[52:53], v[2:3], 0, v[52:53]
	v_lshl_add_u64 v[54:55], v[2:3], 0, v[54:55]
	global_load_dword v78, v[58:59], off
	global_load_dword v79, v[6:7], off
	global_load_dword v80, v[8:9], off
	global_load_dword v81, v[46:47], off
	global_load_dword v82, v[48:49], off
	global_load_dword v83, v[50:51], off
	global_load_dword v84, v[52:53], off
	global_load_dword v85, v[54:55], off
	v_lshl_add_u64 v[6:7], v[2:3], 0, v[56:57]
	v_lshlrev_b64 v[8:9], 13, v[0:1]
	v_add_u32_e32 v0, s0, v71
	v_or_b32_e32 v75, s30, v10
	v_lshl_add_u64 v[4:5], v[2:3], 0, v[60:61]
	global_load_dword v86, v[6:7], off
	global_load_dword v87, v[4:5], off
	v_lshlrev_b64 v[6:7], 13, v[0:1]
	v_add_u32_e32 v0, s0, v73
	v_lshl_add_u64 v[4:5], v[2:3], 0, v[8:9]
	v_lshlrev_b64 v[8:9], 13, v[0:1]
	v_add_u32_e32 v0, s0, v75
	v_lshlrev_b64 v[46:47], 13, v[0:1]
	v_lshl_add_u64 v[46:47], v[2:3], 0, v[46:47]
	v_lshl_add_u64 v[6:7], v[2:3], 0, v[6:7]
	v_lshl_add_u64 v[8:9], v[2:3], 0, v[8:9]
	global_load_dword v0, v[46:47], off
	global_load_dword v88, v[8:9], off
	global_load_dword v89, v[6:7], off
	global_load_dword v90, v[4:5], off
	v_mad_u64_u32 v[104:105], s[30:31], v136, s81, v[12:13]
	v_mad_u64_u32 v[106:107], s[30:31], v101, s81, v[12:13]
	v_mad_u64_u32 v[108:109], s[30:31], v127, s81, v[12:13]
	v_mad_u64_u32 v[110:111], s[30:31], v126, s81, v[12:13]
	v_mad_u64_u32 v[112:113], s[30:31], v129, s81, v[12:13]
	v_mad_u64_u32 v[114:115], s[30:31], v128, s81, v[12:13]
	v_mad_u64_u32 v[116:117], s[30:31], v131, s81, v[12:13]
	v_mad_u64_u32 v[118:119], s[30:31], v130, s81, v[12:13]
	v_mad_u64_u32 v[120:121], s[30:31], v133, s81, v[12:13]
	v_mad_u64_u32 v[122:123], s[30:31], v132, s81, v[12:13]
	v_mad_u64_u32 v[124:125], s[30:31], v135, s81, v[12:13]
	v_mad_u64_u32 v[126:127], s[30:31], v134, s81, v[12:13]
	v_mad_u64_u32 v[128:129], s[30:31], v138, s81, v[12:13]
	v_mad_u64_u32 v[130:131], s[30:31], v137, s81, v[12:13]
	v_mad_u64_u32 v[132:133], s[30:31], v140, s81, v[12:13]
	v_mad_u64_u32 v[134:135], s[30:31], v139, s81, v[12:13]
	s_waitcnt vmcnt(31)
	ds_write_b32 v104, v141
	s_waitcnt vmcnt(30)
	ds_write_b32 v106, v142
	s_waitcnt vmcnt(29)
	ds_write_b32 v108, v143
	s_waitcnt vmcnt(28)
	ds_write_b32 v110, v144
	s_waitcnt vmcnt(20)
	ds_write_b32 v112, v152
	ds_write_b32 v114, v145
	ds_write_b32 v116, v151
	ds_write_b32 v118, v146
	s_waitcnt vmcnt(16)
	ds_write_b32 v120, v155
	ds_write_b32 v122, v147
	ds_write_b32 v124, v154
	ds_write_b32 v126, v148
	ds_write_b32 v128, v153
	ds_write_b32 v130, v149
	ds_write_b32 v132, v102
	ds_write_b32 v134, v150
	v_mad_u64_u32 v[4:5], s[30:31], v45, s81, v[12:13]
	v_mad_u64_u32 v[6:7], s[30:31], v39, s81, v[12:13]
	v_mad_u64_u32 v[8:9], s[30:31], v63, s81, v[12:13]
	v_mad_u64_u32 v[46:47], s[30:31], v62, s81, v[12:13]
	v_mad_u64_u32 v[48:49], s[30:31], v65, s81, v[12:13]
	v_mad_u64_u32 v[50:51], s[30:31], v64, s81, v[12:13]
	v_mad_u64_u32 v[52:53], s[30:31], v67, s81, v[12:13]
	v_mad_u64_u32 v[54:55], s[30:31], v66, s81, v[12:13]
	v_mad_u64_u32 v[56:57], s[30:31], v69, s81, v[12:13]
	v_mad_u64_u32 v[58:59], s[30:31], v68, s81, v[12:13]
	v_mad_u64_u32 v[60:61], s[30:31], v71, s81, v[12:13]
	v_mad_u64_u32 v[62:63], s[30:31], v70, s81, v[12:13]
	v_mad_u64_u32 v[64:65], s[30:31], v73, s81, v[12:13]
	v_mad_u64_u32 v[66:67], s[30:31], v72, s81, v[12:13]
	v_mad_u64_u32 v[68:69], s[30:31], v75, s81, v[12:13]
	v_mad_u64_u32 v[70:71], s[30:31], v74, s81, v[12:13]
	s_waitcnt vmcnt(15)
	ds_write_b32 v4, v76
	s_waitcnt vmcnt(14)
	ds_write_b32 v6, v77
	s_waitcnt vmcnt(13)
	ds_write_b32 v8, v78
	s_waitcnt vmcnt(12)
	ds_write_b32 v46, v79
	s_waitcnt vmcnt(4)
	ds_write_b32 v48, v87
	ds_write_b32 v50, v80
	ds_write_b32 v52, v86
	ds_write_b32 v54, v81
	s_waitcnt vmcnt(0)
	ds_write_b32 v56, v90
	ds_write_b32 v58, v82
	ds_write_b32 v60, v89
	ds_write_b32 v62, v83
	ds_write_b32 v64, v88
	ds_write_b32 v66, v84
	ds_write_b32 v68, v0
	ds_write_b32 v70, v85
	s_add_i32 s25, s25, 16
	s_add_i32 s24, s24, 16
	s_add_i32 s26, s26, -16
	s_cmp_lg_u32 s26, 0
	s_waitcnt lgkmcnt(0)
	ds_read2_b32 v[6:7], v41 offset0:33 offset1:41
	ds_read2_b32 v[8:9], v41 offset1:8
	ds_read2_b32 v[46:47], v41 offset0:66 offset1:74
	ds_read2_b32 v[48:49], v41 offset0:99 offset1:107
	ds_read2_b32 v[50:51], v41 offset0:132 offset1:140
	ds_read2_b32 v[52:53], v41 offset0:165 offset1:173
	ds_read2_b32 v[54:55], v41 offset0:198 offset1:206
	ds_read2_b32 v[56:57], v41 offset0:231 offset1:239
	s_and_b32 s22, 0xffff, s22
	s_lshl_b32 s0, s0, 1
	v_or_b32_e32 v0, s22, v40
	v_lshl_add_u64 v[58:59], v[20:21], 0, s[0:1]
	v_lshlrev_b32_e32 v0, 11, v0
	v_lshl_add_u64 v[60:61], v[58:59], 0, v[0:1]
	s_waitcnt lgkmcnt(6)
	v_cvt_pk_bf16_f32 v2, v8, v6
	s_waitcnt lgkmcnt(4)
	v_cvt_pk_bf16_f32 v3, v46, v48
	s_waitcnt lgkmcnt(2)
	v_cvt_pk_bf16_f32 v4, v50, v52
	s_waitcnt lgkmcnt(0)
	v_cvt_pk_bf16_f32 v5, v54, v56
	global_store_dwordx4 v[60:61], v[2:5], off
	v_or_b32_e32 v0, s22, v42
	v_lshlrev_b32_e32 v0, 11, v0
	v_cvt_pk_bf16_f32 v2, v9, v7
	v_cvt_pk_bf16_f32 v3, v47, v49
	v_cvt_pk_bf16_f32 v4, v51, v53
	v_cvt_pk_bf16_f32 v5, v55, v57
	ds_read2_b32 v[8:9], v41 offset0:16 offset1:24
	ds_read2_b32 v[46:47], v41 offset0:49 offset1:57
	ds_read2_b32 v[48:49], v41 offset0:82 offset1:90
	ds_read2_b32 v[50:51], v41 offset0:115 offset1:123
	ds_read2_b32 v[52:53], v41 offset0:148 offset1:156
	ds_read2_b32 v[54:55], v41 offset0:181 offset1:189
	ds_read2_b32 v[56:57], v41 offset0:214 offset1:222
	ds_read2_b32 v[60:61], v41 offset0:247 offset1:255
	v_lshl_add_u64 v[6:7], v[58:59], 0, v[0:1]
	v_or_b32_e32 v0, s22, v43
	v_lshlrev_b32_e32 v0, 11, v0
	global_store_dwordx4 v[6:7], v[2:5], off
	v_lshl_add_u64 v[6:7], v[58:59], 0, v[0:1]
	v_or_b32_e32 v0, s22, v44
	v_lshlrev_b32_e32 v0, 11, v0
	s_waitcnt lgkmcnt(6)
	v_cvt_pk_bf16_f32 v2, v8, v46
	s_waitcnt lgkmcnt(4)
	v_cvt_pk_bf16_f32 v3, v48, v50
	s_waitcnt lgkmcnt(2)
	v_cvt_pk_bf16_f32 v4, v52, v54
	s_waitcnt lgkmcnt(0)
	v_cvt_pk_bf16_f32 v5, v56, v60
	global_store_dwordx4 v[6:7], v[2:5], off
	v_lshl_add_u64 v[6:7], v[58:59], 0, v[0:1]
	s_nop 0
	v_cvt_pk_bf16_f32 v2, v9, v47
	v_cvt_pk_bf16_f32 v3, v49, v51
	v_cvt_pk_bf16_f32 v4, v53, v55
	v_cvt_pk_bf16_f32 v5, v57, v61
	global_store_dwordx4 v[6:7], v[2:5], off
	s_waitcnt lgkmcnt(0)

; #define LAS __attribute__((address_space(3)))
; __device__ __forceinline__ void cvt_item(gfp W, int N, bf16* WT, int Kd, int k0, int n0, int drow0, LAS float* scr, int lane, gfp gk) {
; #pragma unroll 8
;     for (int i = 0; i < 32; ++i) { const int kk = 2 * i + (lane >> 5); scr[kk * 33 + (lane & 31)] = W[(size_t)(k0 + kk) * N + n0 + (lane & 31)]; }
.LBB0_137:
	v_mov_b32_e32 v103, v1
	s_lshl_b32 s30, s25, 1
	s_lshl_b32 s27, s24, 1
	v_or_b32_e32 v136, s30, v10
	s_add_i32 s33, s30, 4
	s_add_i32 s31, s27, 4
	s_add_i32 s34, s27, 8
	s_add_i32 s35, s30, 8
	v_add_u32_e32 v102, s0, v136
	v_or_b32_e32 v127, s33, v10
	v_or_b32_e32 v101, s27, v11
	s_add_i32 s36, s27, 12
	s_add_i32 s37, s30, 12
	s_add_i32 s38, s27, 16
	s_add_i32 s40, s27, 20
	s_add_i32 s42, s27, 24
	s_add_i32 s27, s27, 28
	v_or_b32_e32 v126, s31, v11
	v_or_b32_e32 v128, s34, v11
	v_or_b32_e32 v129, s35, v10
	v_lshlrev_b64 v[120:121], 13, v[102:103]
	v_add_u32_e32 v102, s0, v127
	v_mov_b32_e32 v105, v103
	v_mov_b32_e32 v107, v103
	v_mov_b32_e32 v109, v103
	s_add_i32 s39, s30, 16
	v_add_u32_e32 v104, s23, v101
	v_or_b32_e32 v130, s36, v11
	v_or_b32_e32 v131, s37, v10
	v_or_b32_e32 v132, s38, v11
	v_or_b32_e32 v134, s40, v11
	v_or_b32_e32 v137, s42, v11
	v_or_b32_e32 v139, s27, v11
	v_add_u32_e32 v106, s23, v126
	v_add_u32_e32 v108, s23, v128
	v_lshlrev_b64 v[122:123], 13, v[102:103]
	v_add_u32_e32 v102, s0, v129
	v_mov_b32_e32 v111, v103
	v_mov_b32_e32 v113, v103
	v_mov_b32_e32 v115, v103
	v_mov_b32_e32 v117, v103
	v_mov_b32_e32 v119, v103
	s_add_i32 s41, s30, 20
	v_or_b32_e32 v133, s39, v10
	v_lshlrev_b64 v[104:105], 13, v[104:105]
	v_add_u32_e32 v110, s23, v130
	v_add_u32_e32 v112, s23, v132
	v_add_u32_e32 v114, s23, v134
	v_add_u32_e32 v116, s23, v137
	v_add_u32_e32 v118, s23, v139
	v_lshl_add_u64 v[120:121], v[2:3], 0, v[120:121]
	v_lshlrev_b64 v[106:107], 13, v[106:107]
	v_lshlrev_b64 v[108:109], 13, v[108:109]
	v_lshlrev_b64 v[124:125], 13, v[102:103]
	v_add_u32_e32 v102, s0, v131
	s_add_i32 s43, s30, 24
	v_or_b32_e32 v135, s41, v10
	v_lshl_add_u64 v[104:105], v[2:3], 0, v[104:105]
	v_lshlrev_b64 v[110:111], 13, v[110:111]
	v_lshlrev_b64 v[112:113], 13, v[112:113]
	v_lshlrev_b64 v[114:115], 13, v[114:115]
	v_lshlrev_b64 v[116:117], 13, v[116:117]
	v_lshlrev_b64 v[118:119], 13, v[118:119]
	v_lshl_add_u64 v[122:123], v[2:3], 0, v[122:123]
	v_lshl_add_u64 v[106:107], v[2:3], 0, v[106:107]
	v_lshl_add_u64 v[108:109], v[2:3], 0, v[108:109]
	global_load_dword v141, v[120:121], off
	global_load_dword v142, v[104:105], off
	v_lshlrev_b64 v[120:121], 13, v[102:103]
	v_add_u32_e32 v102, s0, v133
	s_add_i32 s30, s30, 28
	v_or_b32_e32 v138, s43, v10
	v_lshl_add_u64 v[110:111], v[2:3], 0, v[110:111]
	v_lshl_add_u64 v[112:113], v[2:3], 0, v[112:113]
	v_lshl_add_u64 v[114:115], v[2:3], 0, v[114:115]
	v_lshl_add_u64 v[116:117], v[2:3], 0, v[116:117]
	v_lshl_add_u64 v[118:119], v[2:3], 0, v[118:119]
	global_load_dword v143, v[122:123], off
	global_load_dword v144, v[106:107], off
	global_load_dword v145, v[108:109], off
	global_load_dword v146, v[110:111], off
	global_load_dword v147, v[112:113], off
	global_load_dword v148, v[114:115], off
	global_load_dword v149, v[116:117], off
	global_load_dword v150, v[118:119], off
	v_lshl_add_u64 v[106:107], v[2:3], 0, v[120:121]
	v_lshlrev_b64 v[108:109], 13, v[102:103]
	v_add_u32_e32 v102, s0, v135
	v_or_b32_e32 v140, s30, v10
	v_lshl_add_u64 v[104:105], v[2:3], 0, v[124:125]
	global_load_dword v151, v[106:107], off
	global_load_dword v152, v[104:105], off
	v_lshlrev_b64 v[106:107], 13, v[102:103]
	v_add_u32_e32 v102, s0, v138
	v_lshl_add_u64 v[104:105], v[2:3], 0, v[108:109]
	v_lshlrev_b64 v[108:109], 13, v[102:103]
	v_add_u32_e32 v102, s0, v140
	v_lshlrev_b64 v[110:111], 13, v[102:103]
	v_lshl_add_u64 v[110:111], v[2:3], 0, v[110:111]
	v_lshl_add_u64 v[106:107], v[2:3], 0, v[106:107]
	v_lshl_add_u64 v[108:109], v[2:3], 0, v[108:109]
	global_load_dword v102, v[110:111], off
	global_load_dword v153, v[108:109], off
	global_load_dword v154, v[106:107], off
	global_load_dword v155, v[104:105], off
	s_add_i32 s25, s25, 16
	s_add_i32 s24, s24, 16
	s_add_i32 s26, s26, -16
	s_cmp_lg_u32 s26, 0
	s_lshl_b32 s30, s25, 1
	s_lshl_b32 s27, s24, 1
	v_or_b32_e32 v45, s30, v10
	s_add_i32 s33, s30, 4
	s_add_i32 s31, s27, 4
	s_add_i32 s34, s27, 8
	s_add_i32 s35, s30, 8
	v_add_u32_e32 v0, s0, v45
	v_or_b32_e32 v63, s33, v10
	v_or_b32_e32 v39, s27, v11
	s_add_i32 s36, s27, 12
	s_add_i32 s37, s30, 12
	s_add_i32 s38, s27, 16
	s_add_i32 s40, s27, 20
	s_add_i32 s42, s27, 24
	s_add_i32 s27, s27, 28
	v_or_b32_e32 v62, s31, v11
	v_or_b32_e32 v64, s34, v11
	v_or_b32_e32 v65, s35, v10
	v_lshlrev_b64 v[56:57], 13, v[0:1]
	v_add_u32_e32 v0, s0, v63
	v_mov_b32_e32 v5, v1
	v_mov_b32_e32 v7, v1
	v_mov_b32_e32 v9, v1
	s_add_i32 s39, s30, 16
	v_add_u32_e32 v4, s23, v39
	v_or_b32_e32 v66, s36, v11
	v_or_b32_e32 v67, s37, v10
	v_or_b32_e32 v68, s38, v11
	v_or_b32_e32 v70, s40, v11
	v_or_b32_e32 v72, s42, v11
	v_or_b32_e32 v74, s27, v11
	v_add_u32_e32 v6, s23, v62
	v_add_u32_e32 v8, s23, v64
	v_lshlrev_b64 v[58:59], 13, v[0:1]
	v_add_u32_e32 v0, s0, v65
	v_mov_b32_e32 v47, v1
	v_mov_b32_e32 v49, v1
	v_mov_b32_e32 v51, v1
	v_mov_b32_e32 v53, v1
	v_mov_b32_e32 v55, v1
	s_add_i32 s41, s30, 20
	v_or_b32_e32 v69, s39, v10
	v_lshlrev_b64 v[4:5], 13, v[4:5]
	v_add_u32_e32 v46, s23, v66
	v_add_u32_e32 v48, s23, v68
	v_add_u32_e32 v50, s23, v70
	v_add_u32_e32 v52, s23, v72
	v_add_u32_e32 v54, s23, v74
	v_lshl_add_u64 v[56:57], v[2:3], 0, v[56:57]
	v_lshlrev_b64 v[6:7], 13, v[6:7]
	v_lshlrev_b64 v[8:9], 13, v[8:9]
	v_lshlrev_b64 v[60:61], 13, v[0:1]
	v_add_u32_e32 v0, s0, v67
	s_add_i32 s43, s30, 24
	v_or_b32_e32 v71, s41, v10
	v_lshl_add_u64 v[4:5], v[2:3], 0, v[4:5]
	v_lshlrev_b64 v[46:47], 13, v[46:47]
	v_lshlrev_b64 v[48:49], 13, v[48:49]
	v_lshlrev_b64 v[50:51], 13, v[50:51]
	v_lshlrev_b64 v[52:53], 13, v[52:53]
	v_lshlrev_b64 v[54:55], 13, v[54:55]
	v_lshl_add_u64 v[58:59], v[2:3], 0, v[58:59]
	v_lshl_add_u64 v[6:7], v[2:3], 0, v[6:7]
; #define GAS __attribute__((address_space(1)))
; #define LAS __attribute__((address_space(3)))
; #define LDS_WAIT() asm volatile("s_waitcnt lgkmcnt(0)" ::: "memory")
; __device__ __forceinline__ unsigned pk2(float lo, float hi) { unsigned r; asm("v_cvt_pk_bf16_f32 %0, %1, %2" : "=v"(r) : "v"(lo), "v"(hi)); return r; }
; __device__ __forceinline__ void cvt_item(gfp W, int N, bf16* WT, int Kd, int k0, int n0, int drow0, LAS float* scr, int lane, gfp gk) {
;     ...
;     for (int i = 0; i < 32; ++i) { const int kk = 2 * i + (lane >> 5); scr[kk * 33 + (lane & 31)] = W[(size_t)(k0 + kk) * N + n0 + (lane & 31)]; }
;     const int c = lane & 7;
;     f32x4 ga = (f32x4){1.f, 1.f, 1.f, 1.f}, gb = ga;
;     if (gk != nullptr) { ga = *(const GAS f32x4*)(gk + k0 + 8 * c); gb = *(const GAS f32x4*)(gk + k0 + 8 * c + 4); }
;     LDS_WAIT(); asm volatile("" ::: "memory");
; #pragma unroll
;     for (int j = 0; j < 4; ++j) { const int n = (lane >> 3) + 8 * j; const LAS float* s = scr + (8 * c) * 33 + n;
;         v4u o; o.x = pk2(s[0 * 33] * ga[0], s[1 * 33] * ga[1]); o.y = pk2(s[2 * 33] * ga[2], s[3 * 33] * ga[3]); o.z = pk2(s[4 * 33] * gb[0], s[5 * 33] * gb[1]); o.w = pk2(s[6 * 33] * gb[2], s[7 * 33] * gb[3]);
;         *(GAS v4u*)(WT + (size_t)(drow0 + n) * Kd + k0 + 8 * c) = o; }
;     LDS_WAIT(); asm volatile("" ::: "memory");
	v_lshl_add_u64 v[8:9], v[2:3], 0, v[8:9]
	global_load_dword v76, v[56:57], off
	global_load_dword v77, v[4:5], off
	v_lshlrev_b64 v[56:57], 13, v[0:1]
	v_add_u32_e32 v0, s0, v69
	s_add_i32 s30, s30, 28
	v_or_b32_e32 v73, s43, v10
	v_lshl_add_u64 v[46:47], v[2:3], 0, v[46:47]
	v_lshl_add_u64 v[48:49], v[2:3], 0, v[48:49]
	v_lshl_add_u64 v[50:51], v[2:3], 0, v[50:51]
	v_lshl_add_u64 v[52:53], v[2:3], 0, v[52:53]
	v_lshl_add_u64 v[54:55], v[2:3], 0, v[54:55]
	global_load_dword v78, v[58:59], off
	global_load_dword v79, v[6:7], off
	global_load_dword v80, v[8:9], off
	global_load_dword v81, v[46:47], off
	global_load_dword v82, v[48:49], off
	global_load_dword v83, v[50:51], off
	global_load_dword v84, v[52:53], off
	global_load_dword v85, v[54:55], off
	v_lshl_add_u64 v[6:7], v[2:3], 0, v[56:57]
	v_lshlrev_b64 v[8:9], 13, v[0:1]
	v_add_u32_e32 v0, s0, v71
	v_or_b32_e32 v75, s30, v10
	v_lshl_add_u64 v[4:5], v[2:3], 0, v[60:61]
	global_load_dword v86, v[6:7], off
	global_load_dword v87, v[4:5], off
	v_lshlrev_b64 v[6:7], 13, v[0:1]
	v_add_u32_e32 v0, s0, v73
	v_lshl_add_u64 v[4:5], v[2:3], 0, v[8:9]
	v_lshlrev_b64 v[8:9], 13, v[0:1]
	v_add_u32_e32 v0, s0, v75
	v_lshlrev_b64 v[46:47], 13, v[0:1]
	v_lshl_add_u64 v[46:47], v[2:3], 0, v[46:47]
	v_lshl_add_u64 v[6:7], v[2:3], 0, v[6:7]
	v_lshl_add_u64 v[8:9], v[2:3], 0, v[8:9]
	global_load_dword v0, v[46:47], off
	global_load_dword v88, v[8:9], off
	global_load_dword v89, v[6:7], off
	global_load_dword v90, v[4:5], off
	v_mad_u64_u32 v[104:105], s[30:31], v136, s81, v[12:13]
	v_mad_u64_u32 v[106:107], s[30:31], v101, s81, v[12:13]
	v_mad_u64_u32 v[108:109], s[30:31], v127, s81, v[12:13]
	v_mad_u64_u32 v[110:111], s[30:31], v126, s81, v[12:13]
	v_mad_u64_u32 v[112:113], s[30:31], v129, s81, v[12:13]
	v_mad_u64_u32 v[114:115], s[30:31], v128, s81, v[12:13]
	v_mad_u64_u32 v[116:117], s[30:31], v131, s81, v[12:13]
	v_mad_u64_u32 v[118:119], s[30:31], v130, s81, v[12:13]
	v_mad_u64_u32 v[120:121], s[30:31], v133, s81, v[12:13]
	v_mad_u64_u32 v[122:123], s[30:31], v132, s81, v[12:13]
	v_mad_u64_u32 v[124:125], s[30:31], v135, s81, v[12:13]
	v_mad_u64_u32 v[126:127], s[30:31], v134, s81, v[12:13]
	v_mad_u64_u32 v[128:129], s[30:31], v138, s81, v[12:13]
	v_mad_u64_u32 v[130:131], s[30:31], v137, s81, v[12:13]
	v_mad_u64_u32 v[132:133], s[30:31], v140, s81, v[12:13]
	v_mad_u64_u32 v[134:135], s[30:31], v139, s81, v[12:13]
	s_waitcnt vmcnt(31)
	ds_write_b32 v104, v141
	s_waitcnt vmcnt(30)
	ds_write_b32 v106, v142
	s_waitcnt vmcnt(29)
	ds_write_b32 v108, v143
	s_waitcnt vmcnt(28)
	ds_write_b32 v110, v144
	s_waitcnt vmcnt(20)
	ds_write_b32 v112, v152
	ds_write_b32 v114, v145
	ds_write_b32 v116, v151
	ds_write_b32 v118, v146
	s_waitcnt vmcnt(16)
	ds_write_b32 v120, v155
	ds_write_b32 v122, v147
	ds_write_b32 v124, v154
	ds_write_b32 v126, v148
	ds_write_b32 v128, v153
	ds_write_b32 v130, v149
	ds_write_b32 v132, v102
	ds_write_b32 v134, v150
	v_mad_u64_u32 v[4:5], s[30:31], v45, s81, v[12:13]
	v_mad_u64_u32 v[6:7], s[30:31], v39, s81, v[12:13]
	v_mad_u64_u32 v[8:9], s[30:31], v63, s81, v[12:13]
	v_mad_u64_u32 v[46:47], s[30:31], v62, s81, v[12:13]
	v_mad_u64_u32 v[48:49], s[30:31], v65, s81, v[12:13]
	v_mad_u64_u32 v[50:51], s[30:31], v64, s81, v[12:13]
	v_mad_u64_u32 v[52:53], s[30:31], v67, s81, v[12:13]
	v_mad_u64_u32 v[54:55], s[30:31], v66, s81, v[12:13]
	v_mad_u64_u32 v[56:57], s[30:31], v69, s81, v[12:13]
	v_mad_u64_u32 v[58:59], s[30:31], v68, s81, v[12:13]
	v_mad_u64_u32 v[60:61], s[30:31], v71, s81, v[12:13]
	v_mad_u64_u32 v[62:63], s[30:31], v70, s81, v[12:13]
	v_mad_u64_u32 v[64:65], s[30:31], v73, s81, v[12:13]
	v_mad_u64_u32 v[66:67], s[30:31], v72, s81, v[12:13]
	v_mad_u64_u32 v[68:69], s[30:31], v75, s81, v[12:13]
	v_mad_u64_u32 v[70:71], s[30:31], v74, s81, v[12:13]
	s_waitcnt vmcnt(15)
	ds_write_b32 v4, v76
	s_waitcnt vmcnt(14)
	ds_write_b32 v6, v77
	s_waitcnt vmcnt(13)
	ds_write_b32 v8, v78
	s_waitcnt vmcnt(12)
	ds_write_b32 v46, v79
	s_waitcnt vmcnt(4)
	ds_write_b32 v48, v87
	ds_write_b32 v50, v80
	ds_write_b32 v52, v86
	ds_write_b32 v54, v81
	s_waitcnt vmcnt(0)
	ds_write_b32 v56, v90
	ds_write_b32 v58, v82
	ds_write_b32 v60, v89
	ds_write_b32 v62, v83
	ds_write_b32 v64, v88
	ds_write_b32 v66, v84
	ds_write_b32 v68, v0
	ds_write_b32 v70, v85
	s_add_i32 s25, s25, 16
	s_add_i32 s24, s24, 16
	s_add_i32 s26, s26, -16
	s_cmp_lg_u32 s26, 0
	s_waitcnt lgkmcnt(0)
	ds_read2_b32 v[6:7], v41 offset0:33 offset1:41
	ds_read2_b32 v[8:9], v41 offset1:8
	ds_read2_b32 v[46:47], v41 offset0:66 offset1:74
	ds_read2_b32 v[48:49], v41 offset0:99 offset1:107
	ds_read2_b32 v[50:51], v41 offset0:132 offset1:140
	ds_read2_b32 v[52:53], v41 offset0:165 offset1:173
	ds_read2_b32 v[54:55], v41 offset0:198 offset1:206
	ds_read2_b32 v[56:57], v41 offset0:231 offset1:239
	s_and_b32 s22, 0xffff, s22
	s_lshl_b32 s0, s0, 1
	v_or_b32_e32 v0, s22, v40
	v_lshl_add_u64 v[58:59], v[22:23], 0, s[0:1]
	v_lshlrev_b32_e32 v0, 11, v0
	v_lshl_add_u64 v[60:61], v[58:59], 0, v[0:1]
	s_waitcnt lgkmcnt(6)
	v_cvt_pk_bf16_f32 v2, v8, v6
	s_waitcnt lgkmcnt(4)
	v_cvt_pk_bf16_f32 v3, v46, v48
	s_waitcnt lgkmcnt(2)
	v_cvt_pk_bf16_f32 v4, v50, v52
	s_waitcnt lgkmcnt(0)
	v_cvt_pk_bf16_f32 v5, v54, v56
	global_store_dwordx4 v[60:61], v[2:5], off
	v_or_b32_e32 v0, s22, v42
	v_lshlrev_b32_e32 v0, 11, v0
	v_cvt_pk_bf16_f32 v2, v9, v7
	v_cvt_pk_bf16_f32 v3, v47, v49
	v_cvt_pk_bf16_f32 v4, v51, v53
	v_cvt_pk_bf16_f32 v5, v55, v57
	ds_read2_b32 v[8:9], v41 offset0:16 offset1:24
	ds_read2_b32 v[46:47], v41 offset0:49 offset1:57
	ds_read2_b32 v[48:49], v41 offset0:82 offset1:90
	ds_read2_b32 v[50:51], v41 offset0:115 offset1:123
	ds_read2_b32 v[52:53], v41 offset0:148 offset1:156
	ds_read2_b32 v[54:55], v41 offset0:181 offset1:189
	ds_read2_b32 v[56:57], v41 offset0:214 offset1:222
	ds_read2_b32 v[60:61], v41 offset0:247 offset1:255
	v_lshl_add_u64 v[6:7], v[58:59], 0, v[0:1]
	v_or_b32_e32 v0, s22, v43
	v_lshlrev_b32_e32 v0, 11, v0
	global_store_dwordx4 v[6:7], v[2:5], off
	v_lshl_add_u64 v[6:7], v[58:59], 0, v[0:1]
	v_or_b32_e32 v0, s22, v44
	v_lshlrev_b32_e32 v0, 11, v0
	s_waitcnt lgkmcnt(6)
	v_cvt_pk_bf16_f32 v2, v8, v46
	s_waitcnt lgkmcnt(4)
	v_cvt_pk_bf16_f32 v3, v48, v50
	s_waitcnt lgkmcnt(2)
	v_cvt_pk_bf16_f32 v4, v52, v54
	s_waitcnt lgkmcnt(0)
	v_cvt_pk_bf16_f32 v5, v56, v60
	global_store_dwordx4 v[6:7], v[2:5], off
	v_lshl_add_u64 v[6:7], v[58:59], 0, v[0:1]
	s_nop 0
	v_cvt_pk_bf16_f32 v2, v9, v47
	v_cvt_pk_bf16_f32 v3, v49, v51
	v_cvt_pk_bf16_f32 v4, v53, v55
	v_cvt_pk_bf16_f32 v5, v57, v61
	global_store_dwordx4 v[6:7], v[2:5], off
	s_waitcnt lgkmcnt(0)

; #define LAS __attribute__((address_space(3)))
; __device__ __forceinline__ void cvt_item(gfp W, int N, bf16* WT, int Kd, int k0, int n0, int drow0, LAS float* scr, int lane, gfp gk) {
; #pragma unroll 8
;     for (int i = 0; i < 32; ++i) { const int kk = 2 * i + (lane >> 5); scr[kk * 33 + (lane & 31)] = W[(size_t)(k0 + kk) * N + n0 + (lane & 31)]; }
.LBB0_142:
	v_mov_b32_e32 v103, v1
	s_lshl_b32 s33, s27, 1
	s_lshl_b32 s31, s26, 1
	v_or_b32_e32 v136, s33, v10
	s_add_i32 s35, s33, 4
	s_add_i32 s34, s31, 4
	s_add_i32 s36, s31, 8
	s_add_i32 s37, s33, 8
	v_add_u32_e32 v102, s0, v136
	v_or_b32_e32 v127, s35, v10
	v_or_b32_e32 v101, s31, v11
	s_add_i32 s38, s31, 12
	s_add_i32 s39, s33, 12
	s_add_i32 s40, s31, 16
	s_add_i32 s42, s31, 20
	s_add_i32 s44, s31, 24
	s_add_i32 s31, s31, 28
	v_or_b32_e32 v126, s34, v11
	v_or_b32_e32 v128, s36, v11
	v_or_b32_e32 v129, s37, v10
	v_lshlrev_b64 v[120:121], 13, v[102:103]
	v_add_u32_e32 v102, s0, v127
	v_mov_b32_e32 v105, v103
	v_mov_b32_e32 v107, v103
	v_mov_b32_e32 v109, v103
	s_add_i32 s41, s33, 16
	v_add_u32_e32 v104, s25, v101
	v_or_b32_e32 v130, s38, v11
	v_or_b32_e32 v131, s39, v10
	v_or_b32_e32 v132, s40, v11
	v_or_b32_e32 v134, s42, v11
	v_or_b32_e32 v137, s44, v11
	v_or_b32_e32 v139, s31, v11
	v_add_u32_e32 v106, s25, v126
	v_add_u32_e32 v108, s25, v128
	v_lshlrev_b64 v[122:123], 13, v[102:103]
	v_add_u32_e32 v102, s0, v129
	v_mov_b32_e32 v111, v103
	v_mov_b32_e32 v113, v103
	v_mov_b32_e32 v115, v103
	v_mov_b32_e32 v117, v103
	v_mov_b32_e32 v119, v103
	s_add_i32 s43, s33, 20
	v_or_b32_e32 v133, s41, v10
	v_lshlrev_b64 v[104:105], 13, v[104:105]
	v_add_u32_e32 v110, s25, v130
	v_add_u32_e32 v112, s25, v132
	v_add_u32_e32 v114, s25, v134
	v_add_u32_e32 v116, s25, v137
	v_add_u32_e32 v118, s25, v139
	v_lshl_add_u64 v[120:121], v[2:3], 0, v[120:121]
	v_lshlrev_b64 v[106:107], 13, v[106:107]
	v_lshlrev_b64 v[108:109], 13, v[108:109]
	v_lshlrev_b64 v[124:125], 13, v[102:103]
	v_add_u32_e32 v102, s0, v131
	s_add_i32 s45, s33, 24
	v_or_b32_e32 v135, s43, v10
	v_lshl_add_u64 v[104:105], v[2:3], 0, v[104:105]
	v_lshlrev_b64 v[110:111], 13, v[110:111]
	v_lshlrev_b64 v[112:113], 13, v[112:113]
	v_lshlrev_b64 v[114:115], 13, v[114:115]
	v_lshlrev_b64 v[116:117], 13, v[116:117]
	v_lshlrev_b64 v[118:119], 13, v[118:119]
	v_lshl_add_u64 v[122:123], v[2:3], 0, v[122:123]
	v_lshl_add_u64 v[106:107], v[2:3], 0, v[106:107]
	v_lshl_add_u64 v[108:109], v[2:3], 0, v[108:109]
	global_load_dword v141, v[120:121], off
	global_load_dword v142, v[104:105], off
	v_lshlrev_b64 v[120:121], 13, v[102:103]
	v_add_u32_e32 v102, s0, v133
	s_add_i32 s33, s33, 28
	v_or_b32_e32 v138, s45, v10
	v_lshl_add_u64 v[110:111], v[2:3], 0, v[110:111]
	v_lshl_add_u64 v[112:113], v[2:3], 0, v[112:113]
	v_lshl_add_u64 v[114:115], v[2:3], 0, v[114:115]
	v_lshl_add_u64 v[116:117], v[2:3], 0, v[116:117]
	v_lshl_add_u64 v[118:119], v[2:3], 0, v[118:119]
	global_load_dword v143, v[122:123], off
	global_load_dword v144, v[106:107], off
	global_load_dword v145, v[108:109], off
	global_load_dword v146, v[110:111], off
	global_load_dword v147, v[112:113], off
	global_load_dword v148, v[114:115], off
	global_load_dword v149, v[116:117], off
	global_load_dword v150, v[118:119], off
	v_lshl_add_u64 v[106:107], v[2:3], 0, v[120:121]
	v_lshlrev_b64 v[108:109], 13, v[102:103]
	v_add_u32_e32 v102, s0, v135
	v_or_b32_e32 v140, s33, v10
	v_lshl_add_u64 v[104:105], v[2:3], 0, v[124:125]
	global_load_dword v151, v[106:107], off
	global_load_dword v152, v[104:105], off
	v_lshlrev_b64 v[106:107], 13, v[102:103]
	v_add_u32_e32 v102, s0, v138
	v_lshl_add_u64 v[104:105], v[2:3], 0, v[108:109]
	v_lshlrev_b64 v[108:109], 13, v[102:103]
	v_add_u32_e32 v102, s0, v140
	v_lshlrev_b64 v[110:111], 13, v[102:103]
	v_lshl_add_u64 v[110:111], v[2:3], 0, v[110:111]
	v_lshl_add_u64 v[106:107], v[2:3], 0, v[106:107]
	v_lshl_add_u64 v[108:109], v[2:3], 0, v[108:109]
	global_load_dword v102, v[110:111], off
	global_load_dword v153, v[108:109], off
	global_load_dword v154, v[106:107], off
	global_load_dword v155, v[104:105], off
	s_add_i32 s27, s27, 16
	s_add_i32 s26, s26, 16
	s_add_i32 s30, s30, -16
	s_cmp_lg_u32 s30, 0
	s_lshl_b32 s33, s27, 1
	s_lshl_b32 s31, s26, 1
	v_or_b32_e32 v45, s33, v10
	s_add_i32 s35, s33, 4
	s_add_i32 s34, s31, 4
	s_add_i32 s36, s31, 8
	s_add_i32 s37, s33, 8
	v_add_u32_e32 v0, s0, v45
	v_or_b32_e32 v63, s35, v10
	v_or_b32_e32 v39, s31, v11
	s_add_i32 s38, s31, 12
	s_add_i32 s39, s33, 12
	s_add_i32 s40, s31, 16
	s_add_i32 s42, s31, 20
	s_add_i32 s44, s31, 24
	s_add_i32 s31, s31, 28
	v_or_b32_e32 v62, s34, v11
	v_or_b32_e32 v64, s36, v11
	v_or_b32_e32 v65, s37, v10
	v_lshlrev_b64 v[56:57], 13, v[0:1]
	v_add_u32_e32 v0, s0, v63
	v_mov_b32_e32 v5, v1
	v_mov_b32_e32 v7, v1
	v_mov_b32_e32 v9, v1
	s_add_i32 s41, s33, 16
	v_add_u32_e32 v4, s25, v39
	v_or_b32_e32 v66, s38, v11
	v_or_b32_e32 v67, s39, v10
	v_or_b32_e32 v68, s40, v11
	v_or_b32_e32 v70, s42, v11
	v_or_b32_e32 v72, s44, v11
	v_or_b32_e32 v74, s31, v11
	v_add_u32_e32 v6, s25, v62
	v_add_u32_e32 v8, s25, v64
	v_lshlrev_b64 v[58:59], 13, v[0:1]
	v_add_u32_e32 v0, s0, v65
	v_mov_b32_e32 v47, v1
	v_mov_b32_e32 v49, v1
	v_mov_b32_e32 v51, v1
	v_mov_b32_e32 v53, v1
	v_mov_b32_e32 v55, v1
	s_add_i32 s43, s33, 20
	v_or_b32_e32 v69, s41, v10
	v_lshlrev_b64 v[4:5], 13, v[4:5]
	v_add_u32_e32 v46, s25, v66
	v_add_u32_e32 v48, s25, v68
	v_add_u32_e32 v50, s25, v70
	v_add_u32_e32 v52, s25, v72
	v_add_u32_e32 v54, s25, v74
	v_lshl_add_u64 v[56:57], v[2:3], 0, v[56:57]
	v_lshlrev_b64 v[6:7], 13, v[6:7]
; #define GAS __attribute__((address_space(1)))
; #define LDS_WAIT() asm volatile("s_waitcnt lgkmcnt(0)" ::: "memory")
; __device__ __forceinline__ void cvt_item(gfp W, int N, bf16* WT, int Kd, int k0, int n0, int drow0, LAS float* scr, int lane, gfp gk) {
;     ...
;     for (int i = 0; i < 32; ++i) { const int kk = 2 * i + (lane >> 5); scr[kk * 33 + (lane & 31)] = W[(size_t)(k0 + kk) * N + n0 + (lane & 31)]; }
;     const int c = lane & 7;
;     f32x4 ga = (f32x4){1.f, 1.f, 1.f, 1.f}, gb = ga;
;     if (gk != nullptr) { ga = *(const GAS f32x4*)(gk + k0 + 8 * c); gb = *(const GAS f32x4*)(gk + k0 + 8 * c + 4); }
;     LDS_WAIT(); asm volatile("" ::: "memory");
	v_lshlrev_b64 v[8:9], 13, v[8:9]
	v_lshlrev_b64 v[60:61], 13, v[0:1]
	v_add_u32_e32 v0, s0, v67
	s_add_i32 s45, s33, 24
	v_or_b32_e32 v71, s43, v10
	v_lshl_add_u64 v[4:5], v[2:3], 0, v[4:5]
	v_lshlrev_b64 v[46:47], 13, v[46:47]
	v_lshlrev_b64 v[48:49], 13, v[48:49]
	v_lshlrev_b64 v[50:51], 13, v[50:51]
	v_lshlrev_b64 v[52:53], 13, v[52:53]
	v_lshlrev_b64 v[54:55], 13, v[54:55]
	v_lshl_add_u64 v[58:59], v[2:3], 0, v[58:59]
	v_lshl_add_u64 v[6:7], v[2:3], 0, v[6:7]
	v_lshl_add_u64 v[8:9], v[2:3], 0, v[8:9]
	global_load_dword v76, v[56:57], off
	global_load_dword v77, v[4:5], off
	v_lshlrev_b64 v[56:57], 13, v[0:1]
	v_add_u32_e32 v0, s0, v69
	s_add_i32 s33, s33, 28
	v_or_b32_e32 v73, s45, v10
	v_lshl_add_u64 v[46:47], v[2:3], 0, v[46:47]
	v_lshl_add_u64 v[48:49], v[2:3], 0, v[48:49]
	v_lshl_add_u64 v[50:51], v[2:3], 0, v[50:51]
	v_lshl_add_u64 v[52:53], v[2:3], 0, v[52:53]
	v_lshl_add_u64 v[54:55], v[2:3], 0, v[54:55]
	global_load_dword v78, v[58:59], off
	global_load_dword v79, v[6:7], off
	global_load_dword v80, v[8:9], off
	global_load_dword v81, v[46:47], off
	global_load_dword v82, v[48:49], off
	global_load_dword v83, v[50:51], off
	global_load_dword v84, v[52:53], off
	global_load_dword v85, v[54:55], off
	v_lshl_add_u64 v[6:7], v[2:3], 0, v[56:57]
	v_lshlrev_b64 v[8:9], 13, v[0:1]
	v_add_u32_e32 v0, s0, v71
	v_or_b32_e32 v75, s33, v10
	v_lshl_add_u64 v[4:5], v[2:3], 0, v[60:61]
	global_load_dword v86, v[6:7], off
	global_load_dword v87, v[4:5], off
	v_lshlrev_b64 v[6:7], 13, v[0:1]
	v_add_u32_e32 v0, s0, v73
	v_lshl_add_u64 v[4:5], v[2:3], 0, v[8:9]
	v_lshlrev_b64 v[8:9], 13, v[0:1]
	v_add_u32_e32 v0, s0, v75
	v_lshlrev_b64 v[46:47], 13, v[0:1]
	v_lshl_add_u64 v[46:47], v[2:3], 0, v[46:47]
	v_lshl_add_u64 v[6:7], v[2:3], 0, v[6:7]
	v_lshl_add_u64 v[8:9], v[2:3], 0, v[8:9]
	global_load_dword v0, v[46:47], off
	global_load_dword v88, v[8:9], off
	global_load_dword v89, v[6:7], off
	global_load_dword v90, v[4:5], off
	v_mad_u64_u32 v[104:105], s[34:35], v136, s81, v[12:13]
	v_mad_u64_u32 v[106:107], s[34:35], v101, s81, v[12:13]
	v_mad_u64_u32 v[108:109], s[34:35], v127, s81, v[12:13]
	v_mad_u64_u32 v[110:111], s[34:35], v126, s81, v[12:13]
	v_mad_u64_u32 v[112:113], s[34:35], v129, s81, v[12:13]
	v_mad_u64_u32 v[114:115], s[34:35], v128, s81, v[12:13]
	v_mad_u64_u32 v[116:117], s[34:35], v131, s81, v[12:13]
	v_mad_u64_u32 v[118:119], s[34:35], v130, s81, v[12:13]
	v_mad_u64_u32 v[120:121], s[34:35], v133, s81, v[12:13]
	v_mad_u64_u32 v[122:123], s[34:35], v132, s81, v[12:13]
	v_mad_u64_u32 v[124:125], s[34:35], v135, s81, v[12:13]
	v_mad_u64_u32 v[126:127], s[34:35], v134, s81, v[12:13]
	v_mad_u64_u32 v[128:129], s[34:35], v138, s81, v[12:13]
	v_mad_u64_u32 v[130:131], s[34:35], v137, s81, v[12:13]
	v_mad_u64_u32 v[132:133], s[34:35], v140, s81, v[12:13]
	v_mad_u64_u32 v[134:135], s[34:35], v139, s81, v[12:13]
	s_waitcnt vmcnt(31)
	ds_write_b32 v104, v141
	s_waitcnt vmcnt(30)
	ds_write_b32 v106, v142
	s_waitcnt vmcnt(29)
	ds_write_b32 v108, v143
	s_waitcnt vmcnt(28)
	ds_write_b32 v110, v144
	s_waitcnt vmcnt(20)
	ds_write_b32 v112, v152
	ds_write_b32 v114, v145
	ds_write_b32 v116, v151
	ds_write_b32 v118, v146
	s_waitcnt vmcnt(16)
	ds_write_b32 v120, v155
	ds_write_b32 v122, v147
	ds_write_b32 v124, v154
	ds_write_b32 v126, v148
	ds_write_b32 v128, v153
	ds_write_b32 v130, v149
	ds_write_b32 v132, v102
	ds_write_b32 v134, v150
	v_mad_u64_u32 v[4:5], s[34:35], v45, s81, v[12:13]
	v_mad_u64_u32 v[6:7], s[34:35], v39, s81, v[12:13]
	v_mad_u64_u32 v[8:9], s[34:35], v63, s81, v[12:13]
	v_mad_u64_u32 v[46:47], s[34:35], v62, s81, v[12:13]
	v_mad_u64_u32 v[48:49], s[34:35], v65, s81, v[12:13]
	v_mad_u64_u32 v[50:51], s[34:35], v64, s81, v[12:13]
	v_mad_u64_u32 v[52:53], s[34:35], v67, s81, v[12:13]
	v_mad_u64_u32 v[54:55], s[34:35], v66, s81, v[12:13]
	v_mad_u64_u32 v[56:57], s[34:35], v69, s81, v[12:13]
	v_mad_u64_u32 v[58:59], s[34:35], v68, s81, v[12:13]
	v_mad_u64_u32 v[60:61], s[34:35], v71, s81, v[12:13]
	v_mad_u64_u32 v[62:63], s[34:35], v70, s81, v[12:13]
	v_mad_u64_u32 v[64:65], s[34:35], v73, s81, v[12:13]
	v_mad_u64_u32 v[66:67], s[34:35], v72, s81, v[12:13]
	v_mad_u64_u32 v[68:69], s[34:35], v75, s81, v[12:13]
	v_mad_u64_u32 v[70:71], s[34:35], v74, s81, v[12:13]
	s_waitcnt vmcnt(15)
	ds_write_b32 v4, v76
	s_waitcnt vmcnt(14)
	ds_write_b32 v6, v77
	s_waitcnt vmcnt(13)
	ds_write_b32 v8, v78
	s_waitcnt vmcnt(12)
	ds_write_b32 v46, v79
	s_waitcnt vmcnt(4)
	ds_write_b32 v48, v87
	ds_write_b32 v50, v80
	ds_write_b32 v52, v86
	ds_write_b32 v54, v81
	s_waitcnt vmcnt(0)
	ds_write_b32 v56, v90
	ds_write_b32 v58, v82
	ds_write_b32 v60, v89
	ds_write_b32 v62, v83
	ds_write_b32 v64, v88
	ds_write_b32 v66, v84
	ds_write_b32 v68, v0
	ds_write_b32 v70, v85
	s_add_i32 s27, s27, 16
	s_add_i32 s26, s26, 16
	s_add_i32 s30, s30, -16
	s_cmp_lg_u32 s30, 0
	s_lshl_b64 s[26:27], s[6:7], 2
	s_add_u32 s22, s22, s26
	s_addc_u32 s23, s23, s27
	s_cmp_eq_u64 s[22:23], 0
	s_cbranch_scc1 .LBB0_146
	s_lshl_b32 s25, s0, 2
	s_add_u32 s22, s22, s25
	s_addc_u32 s23, s23, 0
	v_lshlrev_b32_e32 v0, 2, v14
	global_load_dwordx4 v[2:5], v0, s[22:23] offset:16
	global_load_dwordx4 v[6:9], v0, s[22:23]
	s_branch .LBB0_147

; __device__ __forceinline__ void cvt_item(gfp W, int N, bf16* WT, int Kd, int k0, int n0, int drow0, LAS float* scr, int lane, gfp gk) {
; #pragma unroll 8
;     for (int i = 0; i < 32; ++i) { const int kk = 2 * i + (lane >> 5); scr[kk * 33 + (lane & 31)] = W[(size_t)(k0 + kk) * N + n0 + (lane & 31)]; }
.LBB0_151:
	s_lshl_b32 s31, s26, 1
	s_lshl_b32 s33, s27, 1
	v_or_b32_e32 v101, s31, v11
	v_or_b32_e32 v134, s33, v10
	s_add_i32 s34, s31, 4
	s_add_i32 s35, s33, 4
	s_add_i32 s36, s31, 8
	s_add_i32 s37, s33, 8
	s_add_i32 s38, s31, 12
	s_add_i32 s39, s33, 12
	s_add_i32 s40, s31, 16
	s_add_i32 s41, s33, 16
	s_add_i32 s42, s31, 20
	s_add_i32 s43, s33, 20
	s_add_i32 s44, s31, 24
	s_add_i32 s45, s33, 24
	s_add_i32 s31, s31, 28
	s_add_i32 s33, s33, 28
	v_add_u32_e32 v102, s0, v134
	v_or_b32_e32 v135, s34, v11
	v_or_b32_e32 v136, s35, v10
	v_or_b32_e32 v137, s36, v11
	v_or_b32_e32 v138, s37, v10
	v_or_b32_e32 v139, s38, v11
	v_or_b32_e32 v140, s39, v10
	v_or_b32_e32 v141, s40, v11
	v_or_b32_e32 v142, s41, v10
	v_or_b32_e32 v143, s42, v11
	v_or_b32_e32 v144, s43, v10
	v_or_b32_e32 v145, s44, v11
	v_or_b32_e32 v146, s45, v10
	v_or_b32_e32 v147, s31, v11
	v_or_b32_e32 v148, s33, v10
	v_add_u32_e32 v104, s25, v101
	v_mad_u64_u32 v[102:103], s[34:35], v102, s47, v[2:3]
	v_add_u32_e32 v108, s25, v135
	v_add_u32_e32 v106, s0, v136
	v_add_u32_e32 v112, s25, v137
	v_add_u32_e32 v110, s0, v138
	v_add_u32_e32 v116, s25, v139
	v_add_u32_e32 v114, s0, v140
	v_add_u32_e32 v120, s25, v141
	v_add_u32_e32 v118, s0, v142
	v_add_u32_e32 v124, s25, v143
	v_add_u32_e32 v122, s0, v144
	v_add_u32_e32 v128, s25, v145
	v_add_u32_e32 v126, s0, v146
	v_add_u32_e32 v132, s25, v147
	v_add_u32_e32 v130, s0, v148
	v_mad_u64_u32 v[104:105], s[34:35], v104, s47, v[2:3]
	v_mad_u64_u32 v[106:107], s[34:35], v106, s47, v[2:3]
	v_mad_u64_u32 v[108:109], s[34:35], v108, s47, v[2:3]
	v_mad_u64_u32 v[110:111], s[34:35], v110, s47, v[2:3]
	v_mad_u64_u32 v[112:113], s[34:35], v112, s47, v[2:3]
	v_mad_u64_u32 v[114:115], s[34:35], v114, s47, v[2:3]
	v_mad_u64_u32 v[116:117], s[34:35], v116, s47, v[2:3]
	v_mad_u64_u32 v[118:119], s[34:35], v118, s47, v[2:3]
	v_mad_u64_u32 v[120:121], s[34:35], v120, s47, v[2:3]
	v_mad_u64_u32 v[122:123], s[34:35], v122, s47, v[2:3]
	v_mad_u64_u32 v[124:125], s[34:35], v124, s47, v[2:3]
	v_mad_u64_u32 v[126:127], s[34:35], v126, s47, v[2:3]
	v_mad_u64_u32 v[128:129], s[34:35], v128, s47, v[2:3]
	v_mad_u64_u32 v[130:131], s[34:35], v130, s47, v[2:3]
	v_mad_u64_u32 v[132:133], s[34:35], v132, s47, v[2:3]
	global_load_dword v149, v[102:103], off
	global_load_dword v150, v[104:105], off
	global_load_dword v151, v[106:107], off
	global_load_dword v152, v[108:109], off
	global_load_dword v153, v[110:111], off
	global_load_dword v154, v[112:113], off
	global_load_dword v155, v[114:115], off
	global_load_dword v156, v[116:117], off
	global_load_dword v157, v[118:119], off
	global_load_dword v158, v[120:121], off
	global_load_dword v159, v[122:123], off
	global_load_dword v160, v[124:125], off
	global_load_dword v161, v[126:127], off
	global_load_dword v162, v[128:129], off
	global_load_dword v163, v[130:131], off
	global_load_dword v164, v[132:133], off
	s_add_i32 s27, s27, 16
	s_add_i32 s26, s26, 16
	s_add_i32 s30, s30, -16
	s_cmp_lg_u32 s30, 0
	s_lshl_b32 s31, s26, 1
	s_lshl_b32 s33, s27, 1
	v_or_b32_e32 v0, s31, v11
	v_or_b32_e32 v39, s33, v10
	s_add_i32 s34, s31, 4
	s_add_i32 s35, s33, 4
	s_add_i32 s36, s31, 8
	s_add_i32 s37, s33, 8
	s_add_i32 s38, s31, 12
	s_add_i32 s39, s33, 12
	s_add_i32 s40, s31, 16
	s_add_i32 s41, s33, 16
	s_add_i32 s42, s31, 20
	s_add_i32 s43, s33, 20
	s_add_i32 s44, s31, 24
	s_add_i32 s45, s33, 24
	s_add_i32 s31, s31, 28
	s_add_i32 s33, s33, 28
	v_add_u32_e32 v4, s0, v39
	v_or_b32_e32 v45, s34, v11
	v_or_b32_e32 v72, s35, v10
	v_or_b32_e32 v73, s36, v11
	v_or_b32_e32 v74, s37, v10
	v_or_b32_e32 v75, s38, v11
	v_or_b32_e32 v76, s39, v10
	v_or_b32_e32 v77, s40, v11
	v_or_b32_e32 v78, s41, v10
	v_or_b32_e32 v79, s42, v11
	v_or_b32_e32 v80, s43, v10
	v_or_b32_e32 v81, s44, v11
	v_or_b32_e32 v82, s45, v10
	v_or_b32_e32 v83, s31, v11
	v_or_b32_e32 v84, s33, v10
	v_add_u32_e32 v6, s25, v0
	v_mad_u64_u32 v[4:5], s[34:35], v4, s47, v[2:3]
	v_add_u32_e32 v46, s25, v45
	v_add_u32_e32 v8, s0, v72
	v_add_u32_e32 v50, s25, v73
	v_add_u32_e32 v48, s0, v74
	v_add_u32_e32 v54, s25, v75
	v_add_u32_e32 v52, s0, v76
	v_add_u32_e32 v58, s25, v77
	v_add_u32_e32 v56, s0, v78
	v_add_u32_e32 v62, s25, v79
	v_add_u32_e32 v60, s0, v80
	v_add_u32_e32 v66, s25, v81
	v_add_u32_e32 v64, s0, v82
	v_add_u32_e32 v70, s25, v83
	v_add_u32_e32 v68, s0, v84
	v_mad_u64_u32 v[6:7], s[34:35], v6, s47, v[2:3]
	v_mad_u64_u32 v[8:9], s[34:35], v8, s47, v[2:3]
	v_mad_u64_u32 v[46:47], s[34:35], v46, s47, v[2:3]
	v_mad_u64_u32 v[48:49], s[34:35], v48, s47, v[2:3]
	v_mad_u64_u32 v[50:51], s[34:35], v50, s47, v[2:3]
	v_mad_u64_u32 v[52:53], s[34:35], v52, s47, v[2:3]
	v_mad_u64_u32 v[54:55], s[34:35], v54, s47, v[2:3]
	v_mad_u64_u32 v[56:57], s[34:35], v56, s47, v[2:3]
	v_mad_u64_u32 v[58:59], s[34:35], v58, s47, v[2:3]
	v_mad_u64_u32 v[60:61], s[34:35], v60, s47, v[2:3]
	v_mad_u64_u32 v[62:63], s[34:35], v62, s47, v[2:3]
	v_mad_u64_u32 v[64:65], s[34:35], v64, s47, v[2:3]
	v_mad_u64_u32 v[66:67], s[34:35], v66, s47, v[2:3]
	v_mad_u64_u32 v[68:69], s[34:35], v68, s47, v[2:3]
	v_mad_u64_u32 v[70:71], s[34:35], v70, s47, v[2:3]
	global_load_dword v85, v[4:5], off
	global_load_dword v86, v[6:7], off
	global_load_dword v87, v[8:9], off
	global_load_dword v88, v[46:47], off
	global_load_dword v89, v[48:49], off
	global_load_dword v90, v[50:51], off
	global_load_dword v91, v[52:53], off
	global_load_dword v92, v[54:55], off
	global_load_dword v93, v[56:57], off
	global_load_dword v94, v[58:59], off
	global_load_dword v95, v[60:61], off
	global_load_dword v96, v[62:63], off
	global_load_dword v97, v[64:65], off
	global_load_dword v98, v[66:67], off
	global_load_dword v99, v[68:69], off
	global_load_dword v100, v[70:71], off
	v_mad_u64_u32 v[102:103], s[34:35], v134, s81, v[12:13]
	v_mad_u64_u32 v[104:105], s[34:35], v101, s81, v[12:13]
	v_mad_u64_u32 v[106:107], s[34:35], v136, s81, v[12:13]
	v_mad_u64_u32 v[108:109], s[34:35], v135, s81, v[12:13]
	v_mad_u64_u32 v[110:111], s[34:35], v138, s81, v[12:13]
	v_mad_u64_u32 v[112:113], s[34:35], v137, s81, v[12:13]
	v_mad_u64_u32 v[114:115], s[34:35], v140, s81, v[12:13]
	v_mad_u64_u32 v[116:117], s[34:35], v139, s81, v[12:13]
	v_mad_u64_u32 v[118:119], s[34:35], v142, s81, v[12:13]
	v_mad_u64_u32 v[120:121], s[34:35], v141, s81, v[12:13]
	v_mad_u64_u32 v[122:123], s[34:35], v144, s81, v[12:13]
	v_mad_u64_u32 v[124:125], s[34:35], v143, s81, v[12:13]
	v_mad_u64_u32 v[126:127], s[34:35], v146, s81, v[12:13]
	v_mad_u64_u32 v[128:129], s[34:35], v145, s81, v[12:13]
	v_mad_u64_u32 v[130:131], s[34:35], v148, s81, v[12:13]
	v_mad_u64_u32 v[132:133], s[34:35], v147, s81, v[12:13]
	s_waitcnt vmcnt(31)
; #define GAS __attribute__((address_space(1)))
; __device__ __forceinline__ void cvt_item(gfp W, int N, bf16* WT, int Kd, int k0, int n0, int drow0, LAS float* scr, int lane, gfp gk) {
;     ...
;     for (int i = 0; i < 32; ++i) { const int kk = 2 * i + (lane >> 5); scr[kk * 33 + (lane & 31)] = W[(size_t)(k0 + kk) * N + n0 + (lane & 31)]; }
;     const int c = lane & 7;
;     f32x4 ga = (f32x4){1.f, 1.f, 1.f, 1.f}, gb = ga;
;     if (gk != nullptr) { ga = *(const GAS f32x4*)(gk + k0 + 8 * c); gb = *(const GAS f32x4*)(gk + k0 + 8 * c + 4); }
	ds_write_b32 v102, v149
	s_waitcnt vmcnt(30)
	ds_write_b32 v104, v150
	s_waitcnt vmcnt(29)
	ds_write_b32 v106, v151
	s_waitcnt vmcnt(28)
	ds_write_b32 v108, v152
	s_waitcnt vmcnt(27)
	ds_write_b32 v110, v153
	s_waitcnt vmcnt(26)
	ds_write_b32 v112, v154
	s_waitcnt vmcnt(25)
	ds_write_b32 v114, v155
	s_waitcnt vmcnt(24)
	ds_write_b32 v116, v156
	s_waitcnt vmcnt(23)
	ds_write_b32 v118, v157
	s_waitcnt vmcnt(22)
	ds_write_b32 v120, v158
	s_waitcnt vmcnt(21)
	ds_write_b32 v122, v159
	s_waitcnt vmcnt(20)
	ds_write_b32 v124, v160
	s_waitcnt vmcnt(19)
	ds_write_b32 v126, v161
	s_waitcnt vmcnt(18)
	ds_write_b32 v128, v162
	s_waitcnt vmcnt(17)
	ds_write_b32 v130, v163
	s_waitcnt vmcnt(16)
	ds_write_b32 v132, v164
	v_mad_u64_u32 v[4:5], s[34:35], v39, s81, v[12:13]
	v_mad_u64_u32 v[6:7], s[34:35], v0, s81, v[12:13]
	v_mad_u64_u32 v[8:9], s[34:35], v72, s81, v[12:13]
	v_mad_u64_u32 v[46:47], s[34:35], v45, s81, v[12:13]
	v_mad_u64_u32 v[48:49], s[34:35], v74, s81, v[12:13]
	v_mad_u64_u32 v[50:51], s[34:35], v73, s81, v[12:13]
	v_mad_u64_u32 v[52:53], s[34:35], v76, s81, v[12:13]
	v_mad_u64_u32 v[54:55], s[34:35], v75, s81, v[12:13]
	v_mad_u64_u32 v[56:57], s[34:35], v78, s81, v[12:13]
	v_mad_u64_u32 v[58:59], s[34:35], v77, s81, v[12:13]
	v_mad_u64_u32 v[60:61], s[34:35], v80, s81, v[12:13]
	v_mad_u64_u32 v[62:63], s[34:35], v79, s81, v[12:13]
	v_mad_u64_u32 v[64:65], s[34:35], v82, s81, v[12:13]
	v_mad_u64_u32 v[66:67], s[34:35], v81, s81, v[12:13]
	v_mad_u64_u32 v[68:69], s[34:35], v84, s81, v[12:13]
	v_mad_u64_u32 v[70:71], s[34:35], v83, s81, v[12:13]
	s_waitcnt vmcnt(15)
	ds_write_b32 v4, v85
	s_waitcnt vmcnt(14)
	ds_write_b32 v6, v86
	s_waitcnt vmcnt(13)
	ds_write_b32 v8, v87
	s_waitcnt vmcnt(12)
	ds_write_b32 v46, v88
	s_waitcnt vmcnt(11)
	ds_write_b32 v48, v89
	s_waitcnt vmcnt(10)
	ds_write_b32 v50, v90
	s_waitcnt vmcnt(9)
	ds_write_b32 v52, v91
	s_waitcnt vmcnt(8)
	ds_write_b32 v54, v92
	s_waitcnt vmcnt(7)
	ds_write_b32 v56, v93
	s_waitcnt vmcnt(6)
	ds_write_b32 v58, v94
	s_waitcnt vmcnt(5)
	ds_write_b32 v60, v95
	s_waitcnt vmcnt(4)
	ds_write_b32 v62, v96
	s_waitcnt vmcnt(3)
	ds_write_b32 v64, v97
	s_waitcnt vmcnt(2)
	ds_write_b32 v66, v98
	s_waitcnt vmcnt(1)
	ds_write_b32 v68, v99
	s_waitcnt vmcnt(0)
	ds_write_b32 v70, v100
	s_add_i32 s27, s27, 16
	s_add_i32 s26, s26, 16
	s_add_i32 s30, s30, -16
	s_cmp_lg_u32 s30, 0
	s_lshl_b64 s[26:27], s[6:7], 2
	s_add_u32 s22, s22, s26
	s_addc_u32 s23, s23, s27
	s_cmp_eq_u64 s[22:23], 0
	s_cbranch_scc1 .LBB0_154
	s_lshl_b32 s25, s0, 2
	s_add_u32 s22, s22, s25
	s_addc_u32 s23, s23, 0
	v_lshlrev_b32_e32 v0, 2, v14
	global_load_dwordx4 v[2:5], v0, s[22:23] offset:16
	global_load_dwordx4 v[6:9], v0, s[22:23]
	s_branch .LBB0_155

; __device__ __forceinline__ void cvt_item(gfp W, int N, bf16* WT, int Kd, int k0, int n0, int drow0, LAS float* scr, int lane, gfp gk) {
; #pragma unroll 8
;     for (int i = 0; i < 32; ++i) { const int kk = 2 * i + (lane >> 5); scr[kk * 33 + (lane & 31)] = W[(size_t)(k0 + kk) * N + n0 + (lane & 31)]; }
.LBB0_159:
	s_lshl_b32 s31, s26, 1
	s_lshl_b32 s33, s27, 1
	v_or_b32_e32 v101, s31, v11
	v_or_b32_e32 v134, s33, v10
	s_add_i32 s34, s31, 4
	s_add_i32 s35, s33, 4
	s_add_i32 s36, s31, 8
	s_add_i32 s37, s33, 8
	s_add_i32 s38, s31, 12
	s_add_i32 s39, s33, 12
	s_add_i32 s40, s31, 16
	s_add_i32 s41, s33, 16
	s_add_i32 s42, s31, 20
	s_add_i32 s43, s33, 20
	s_add_i32 s44, s31, 24
	s_add_i32 s45, s33, 24
	s_add_i32 s31, s31, 28
	s_add_i32 s33, s33, 28
	v_add_u32_e32 v102, s24, v134
	v_or_b32_e32 v135, s34, v11
	v_or_b32_e32 v136, s35, v10
	v_or_b32_e32 v137, s36, v11
	v_or_b32_e32 v138, s37, v10
	v_or_b32_e32 v139, s38, v11
	v_or_b32_e32 v140, s39, v10
	v_or_b32_e32 v141, s40, v11
	v_or_b32_e32 v142, s41, v10
	v_or_b32_e32 v143, s42, v11
	v_or_b32_e32 v144, s43, v10
	v_or_b32_e32 v145, s44, v11
	v_or_b32_e32 v146, s45, v10
	v_or_b32_e32 v147, s31, v11
	v_or_b32_e32 v148, s33, v10
	v_add_u32_e32 v104, s25, v101
	v_mad_u64_u32 v[102:103], s[34:35], v102, s48, v[2:3]
	v_add_u32_e32 v108, s25, v135
	v_add_u32_e32 v106, s24, v136
	v_add_u32_e32 v112, s25, v137
	v_add_u32_e32 v110, s24, v138
	v_add_u32_e32 v116, s25, v139
	v_add_u32_e32 v114, s24, v140
	v_add_u32_e32 v120, s25, v141
	v_add_u32_e32 v118, s24, v142
	v_add_u32_e32 v124, s25, v143
	v_add_u32_e32 v122, s24, v144
	v_add_u32_e32 v128, s25, v145
	v_add_u32_e32 v126, s24, v146
	v_add_u32_e32 v132, s25, v147
	v_add_u32_e32 v130, s24, v148
	v_mad_u64_u32 v[104:105], s[34:35], v104, s48, v[2:3]
	v_mad_u64_u32 v[106:107], s[34:35], v106, s48, v[2:3]
	v_mad_u64_u32 v[108:109], s[34:35], v108, s48, v[2:3]
	v_mad_u64_u32 v[110:111], s[34:35], v110, s48, v[2:3]
	v_mad_u64_u32 v[112:113], s[34:35], v112, s48, v[2:3]
	v_mad_u64_u32 v[114:115], s[34:35], v114, s48, v[2:3]
	v_mad_u64_u32 v[116:117], s[34:35], v116, s48, v[2:3]
	v_mad_u64_u32 v[118:119], s[34:35], v118, s48, v[2:3]
	v_mad_u64_u32 v[120:121], s[34:35], v120, s48, v[2:3]
	v_mad_u64_u32 v[122:123], s[34:35], v122, s48, v[2:3]
	v_mad_u64_u32 v[124:125], s[34:35], v124, s48, v[2:3]
	v_mad_u64_u32 v[126:127], s[34:35], v126, s48, v[2:3]
	v_mad_u64_u32 v[128:129], s[34:35], v128, s48, v[2:3]
	v_mad_u64_u32 v[130:131], s[34:35], v130, s48, v[2:3]
	v_mad_u64_u32 v[132:133], s[34:35], v132, s48, v[2:3]
	global_load_dword v149, v[102:103], off
	global_load_dword v150, v[104:105], off
	global_load_dword v151, v[106:107], off
	global_load_dword v152, v[108:109], off
	global_load_dword v153, v[110:111], off
	global_load_dword v154, v[112:113], off
	global_load_dword v155, v[114:115], off
	global_load_dword v156, v[116:117], off
	global_load_dword v157, v[118:119], off
	global_load_dword v158, v[120:121], off
	global_load_dword v159, v[122:123], off
	global_load_dword v160, v[124:125], off
	global_load_dword v161, v[126:127], off
	global_load_dword v162, v[128:129], off
	global_load_dword v163, v[130:131], off
	global_load_dword v164, v[132:133], off
	s_add_i32 s27, s27, 16
	s_add_i32 s26, s26, 16
	s_add_i32 s30, s30, -16
	s_cmp_lg_u32 s30, 0
	s_lshl_b32 s31, s26, 1
	s_lshl_b32 s33, s27, 1
	v_or_b32_e32 v0, s31, v11
	v_or_b32_e32 v39, s33, v10
	s_add_i32 s34, s31, 4
	s_add_i32 s35, s33, 4
	s_add_i32 s36, s31, 8
	s_add_i32 s37, s33, 8
	s_add_i32 s38, s31, 12
	s_add_i32 s39, s33, 12
	s_add_i32 s40, s31, 16
	s_add_i32 s41, s33, 16
	s_add_i32 s42, s31, 20
	s_add_i32 s43, s33, 20
	s_add_i32 s44, s31, 24
	s_add_i32 s45, s33, 24
	s_add_i32 s31, s31, 28
	s_add_i32 s33, s33, 28
	v_add_u32_e32 v4, s24, v39
	v_or_b32_e32 v45, s34, v11
	v_or_b32_e32 v72, s35, v10
	v_or_b32_e32 v73, s36, v11
	v_or_b32_e32 v74, s37, v10
	v_or_b32_e32 v75, s38, v11
	v_or_b32_e32 v76, s39, v10
	v_or_b32_e32 v77, s40, v11
	v_or_b32_e32 v78, s41, v10
	v_or_b32_e32 v79, s42, v11
	v_or_b32_e32 v80, s43, v10
	v_or_b32_e32 v81, s44, v11
	v_or_b32_e32 v82, s45, v10
	v_or_b32_e32 v83, s31, v11
	v_or_b32_e32 v84, s33, v10
	v_add_u32_e32 v6, s25, v0
	v_mad_u64_u32 v[4:5], s[34:35], v4, s48, v[2:3]
	v_add_u32_e32 v46, s25, v45
	v_add_u32_e32 v8, s24, v72
	v_add_u32_e32 v50, s25, v73
	v_add_u32_e32 v48, s24, v74
	v_add_u32_e32 v54, s25, v75
	v_add_u32_e32 v52, s24, v76
	v_add_u32_e32 v58, s25, v77
	v_add_u32_e32 v56, s24, v78
	v_add_u32_e32 v62, s25, v79
	v_add_u32_e32 v60, s24, v80
	v_add_u32_e32 v66, s25, v81
	v_add_u32_e32 v64, s24, v82
	v_add_u32_e32 v70, s25, v83
	v_add_u32_e32 v68, s24, v84
	v_mad_u64_u32 v[6:7], s[34:35], v6, s48, v[2:3]
	v_mad_u64_u32 v[8:9], s[34:35], v8, s48, v[2:3]
	v_mad_u64_u32 v[46:47], s[34:35], v46, s48, v[2:3]
	v_mad_u64_u32 v[48:49], s[34:35], v48, s48, v[2:3]
	v_mad_u64_u32 v[50:51], s[34:35], v50, s48, v[2:3]
	v_mad_u64_u32 v[52:53], s[34:35], v52, s48, v[2:3]
	v_mad_u64_u32 v[54:55], s[34:35], v54, s48, v[2:3]
	v_mad_u64_u32 v[56:57], s[34:35], v56, s48, v[2:3]
	v_mad_u64_u32 v[58:59], s[34:35], v58, s48, v[2:3]
	v_mad_u64_u32 v[60:61], s[34:35], v60, s48, v[2:3]
	v_mad_u64_u32 v[62:63], s[34:35], v62, s48, v[2:3]
	v_mad_u64_u32 v[64:65], s[34:35], v64, s48, v[2:3]
	v_mad_u64_u32 v[66:67], s[34:35], v66, s48, v[2:3]
	v_mad_u64_u32 v[68:69], s[34:35], v68, s48, v[2:3]
	v_mad_u64_u32 v[70:71], s[34:35], v70, s48, v[2:3]
	global_load_dword v85, v[4:5], off
	global_load_dword v86, v[6:7], off
	global_load_dword v87, v[8:9], off
	global_load_dword v88, v[46:47], off
	global_load_dword v89, v[48:49], off
	global_load_dword v90, v[50:51], off
	global_load_dword v91, v[52:53], off
	global_load_dword v92, v[54:55], off
	global_load_dword v93, v[56:57], off
	global_load_dword v94, v[58:59], off
	global_load_dword v95, v[60:61], off
	global_load_dword v96, v[62:63], off
	global_load_dword v97, v[64:65], off
	global_load_dword v98, v[66:67], off
	global_load_dword v99, v[68:69], off
	global_load_dword v100, v[70:71], off
	v_mad_u64_u32 v[102:103], s[34:35], v134, s81, v[12:13]
	v_mad_u64_u32 v[104:105], s[34:35], v101, s81, v[12:13]
	v_mad_u64_u32 v[106:107], s[34:35], v136, s81, v[12:13]
	v_mad_u64_u32 v[108:109], s[34:35], v135, s81, v[12:13]
	v_mad_u64_u32 v[110:111], s[34:35], v138, s81, v[12:13]
	v_mad_u64_u32 v[112:113], s[34:35], v137, s81, v[12:13]
	v_mad_u64_u32 v[114:115], s[34:35], v140, s81, v[12:13]
	v_mad_u64_u32 v[116:117], s[34:35], v139, s81, v[12:13]
	v_mad_u64_u32 v[118:119], s[34:35], v142, s81, v[12:13]
	v_mad_u64_u32 v[120:121], s[34:35], v141, s81, v[12:13]
	v_mad_u64_u32 v[122:123], s[34:35], v144, s81, v[12:13]
	v_mad_u64_u32 v[124:125], s[34:35], v143, s81, v[12:13]
	v_mad_u64_u32 v[126:127], s[34:35], v146, s81, v[12:13]
	v_mad_u64_u32 v[128:129], s[34:35], v145, s81, v[12:13]
	v_mad_u64_u32 v[130:131], s[34:35], v148, s81, v[12:13]
	v_mad_u64_u32 v[132:133], s[34:35], v147, s81, v[12:13]
	s_waitcnt vmcnt(31)
; #define GAS __attribute__((address_space(1)))
; __device__ __forceinline__ void cvt_item(gfp W, int N, bf16* WT, int Kd, int k0, int n0, int drow0, LAS float* scr, int lane, gfp gk) {
;     ...
;     for (int i = 0; i < 32; ++i) { const int kk = 2 * i + (lane >> 5); scr[kk * 33 + (lane & 31)] = W[(size_t)(k0 + kk) * N + n0 + (lane & 31)]; }
;     const int c = lane & 7;
;     f32x4 ga = (f32x4){1.f, 1.f, 1.f, 1.f}, gb = ga;
;     if (gk != nullptr) { ga = *(const GAS f32x4*)(gk + k0 + 8 * c); gb = *(const GAS f32x4*)(gk + k0 + 8 * c + 4); }
	ds_write_b32 v102, v149
	s_waitcnt vmcnt(30)
	ds_write_b32 v104, v150
	s_waitcnt vmcnt(29)
	ds_write_b32 v106, v151
	s_waitcnt vmcnt(28)
	ds_write_b32 v108, v152
	s_waitcnt vmcnt(27)
	ds_write_b32 v110, v153
	s_waitcnt vmcnt(26)
	ds_write_b32 v112, v154
	s_waitcnt vmcnt(25)
	ds_write_b32 v114, v155
	s_waitcnt vmcnt(24)
	ds_write_b32 v116, v156
	s_waitcnt vmcnt(23)
	ds_write_b32 v118, v157
	s_waitcnt vmcnt(22)
	ds_write_b32 v120, v158
	s_waitcnt vmcnt(21)
	ds_write_b32 v122, v159
	s_waitcnt vmcnt(20)
	ds_write_b32 v124, v160
	s_waitcnt vmcnt(19)
	ds_write_b32 v126, v161
	s_waitcnt vmcnt(18)
	ds_write_b32 v128, v162
	s_waitcnt vmcnt(17)
	ds_write_b32 v130, v163
	s_waitcnt vmcnt(16)
	ds_write_b32 v132, v164
	v_mad_u64_u32 v[4:5], s[34:35], v39, s81, v[12:13]
	v_mad_u64_u32 v[6:7], s[34:35], v0, s81, v[12:13]
	v_mad_u64_u32 v[8:9], s[34:35], v72, s81, v[12:13]
	v_mad_u64_u32 v[46:47], s[34:35], v45, s81, v[12:13]
	v_mad_u64_u32 v[48:49], s[34:35], v74, s81, v[12:13]
	v_mad_u64_u32 v[50:51], s[34:35], v73, s81, v[12:13]
	v_mad_u64_u32 v[52:53], s[34:35], v76, s81, v[12:13]
	v_mad_u64_u32 v[54:55], s[34:35], v75, s81, v[12:13]
	v_mad_u64_u32 v[56:57], s[34:35], v78, s81, v[12:13]
	v_mad_u64_u32 v[58:59], s[34:35], v77, s81, v[12:13]
	v_mad_u64_u32 v[60:61], s[34:35], v80, s81, v[12:13]
	v_mad_u64_u32 v[62:63], s[34:35], v79, s81, v[12:13]
	v_mad_u64_u32 v[64:65], s[34:35], v82, s81, v[12:13]
	v_mad_u64_u32 v[66:67], s[34:35], v81, s81, v[12:13]
	v_mad_u64_u32 v[68:69], s[34:35], v84, s81, v[12:13]
	v_mad_u64_u32 v[70:71], s[34:35], v83, s81, v[12:13]
	s_waitcnt vmcnt(15)
	ds_write_b32 v4, v85
	s_waitcnt vmcnt(14)
	ds_write_b32 v6, v86
	s_waitcnt vmcnt(13)
	ds_write_b32 v8, v87
	s_waitcnt vmcnt(12)
	ds_write_b32 v46, v88
	s_waitcnt vmcnt(11)
	ds_write_b32 v48, v89
	s_waitcnt vmcnt(10)
	ds_write_b32 v50, v90
	s_waitcnt vmcnt(9)
	ds_write_b32 v52, v91
	s_waitcnt vmcnt(8)
	ds_write_b32 v54, v92
	s_waitcnt vmcnt(7)
	ds_write_b32 v56, v93
	s_waitcnt vmcnt(6)
	ds_write_b32 v58, v94
	s_waitcnt vmcnt(5)
	ds_write_b32 v60, v95
	s_waitcnt vmcnt(4)
	ds_write_b32 v62, v96
	s_waitcnt vmcnt(3)
	ds_write_b32 v64, v97
	s_waitcnt vmcnt(2)
	ds_write_b32 v66, v98
	s_waitcnt vmcnt(1)
	ds_write_b32 v68, v99
	s_waitcnt vmcnt(0)
	ds_write_b32 v70, v100
	s_add_i32 s27, s27, 16
	s_add_i32 s26, s26, 16
	s_add_i32 s30, s30, -16
	s_cmp_lg_u32 s30, 0
	s_lshl_b64 s[26:27], s[8:9], 2
	s_add_u32 s22, s22, s26
	s_addc_u32 s23, s23, s27
	s_and_b32 s24, s24, 0xffff
	s_cmp_eq_u64 s[22:23], 0
	s_cbranch_scc1 .LBB0_162
	s_lshl_b32 s25, s24, 2
	s_add_u32 s22, s22, s25
	s_addc_u32 s23, s23, 0
	v_lshlrev_b32_e32 v0, 2, v14
	global_load_dwordx4 v[2:5], v0, s[22:23] offset:16
	global_load_dwordx4 v[6:9], v0, s[22:23]
	s_branch .LBB0_163

; __device__ __forceinline__ void cvt_item(gfp W, int N, bf16* WT, int Kd, int k0, int n0, int drow0, LAS float* scr, int lane, gfp gk) {
; #pragma unroll 8
;     for (int i = 0; i < 32; ++i) { const int kk = 2 * i + (lane >> 5); scr[kk * 33 + (lane & 31)] = W[(size_t)(k0 + kk) * N + n0 + (lane & 31)]; }
.LBB0_167:
	v_mov_b32_e32 v103, v1
	s_lshl_b32 s30, s25, 1
	s_lshl_b32 s27, s24, 1
	v_or_b32_e32 v136, s30, v10
	s_add_i32 s33, s30, 4
	s_add_i32 s31, s27, 4
	s_add_i32 s34, s27, 8
	s_add_i32 s35, s30, 8
	v_add_u32_e32 v102, s0, v136
	v_or_b32_e32 v127, s33, v10
	v_or_b32_e32 v101, s27, v11
	s_add_i32 s36, s27, 12
	s_add_i32 s37, s30, 12
	s_add_i32 s38, s27, 16
	s_add_i32 s40, s27, 20
	s_add_i32 s42, s27, 24
	s_add_i32 s27, s27, 28
	v_or_b32_e32 v126, s31, v11
	v_or_b32_e32 v128, s34, v11
	v_or_b32_e32 v129, s35, v10
	v_lshlrev_b64 v[120:121], 13, v[102:103]
	v_add_u32_e32 v102, s0, v127
	v_mov_b32_e32 v105, v103
	v_mov_b32_e32 v107, v103
	v_mov_b32_e32 v109, v103
	s_add_i32 s39, s30, 16
	v_add_u32_e32 v104, s23, v101
	v_or_b32_e32 v130, s36, v11
	v_or_b32_e32 v131, s37, v10
	v_or_b32_e32 v132, s38, v11
	v_or_b32_e32 v134, s40, v11
	v_or_b32_e32 v137, s42, v11
	v_or_b32_e32 v139, s27, v11
	v_add_u32_e32 v106, s23, v126
	v_add_u32_e32 v108, s23, v128
	v_lshlrev_b64 v[122:123], 13, v[102:103]
	v_add_u32_e32 v102, s0, v129
	v_mov_b32_e32 v111, v103
	v_mov_b32_e32 v113, v103
	v_mov_b32_e32 v115, v103
	v_mov_b32_e32 v117, v103
	v_mov_b32_e32 v119, v103
	s_add_i32 s41, s30, 20
	v_or_b32_e32 v133, s39, v10
	v_lshlrev_b64 v[104:105], 13, v[104:105]
	v_add_u32_e32 v110, s23, v130
	v_add_u32_e32 v112, s23, v132
	v_add_u32_e32 v114, s23, v134
	v_add_u32_e32 v116, s23, v137
	v_add_u32_e32 v118, s23, v139
	v_lshl_add_u64 v[120:121], v[2:3], 0, v[120:121]
	v_lshlrev_b64 v[106:107], 13, v[106:107]
	v_lshlrev_b64 v[108:109], 13, v[108:109]
	v_lshlrev_b64 v[124:125], 13, v[102:103]
	v_add_u32_e32 v102, s0, v131
	s_add_i32 s43, s30, 24
	v_or_b32_e32 v135, s41, v10
	v_lshl_add_u64 v[104:105], v[2:3], 0, v[104:105]
	v_lshlrev_b64 v[110:111], 13, v[110:111]
	v_lshlrev_b64 v[112:113], 13, v[112:113]
	v_lshlrev_b64 v[114:115], 13, v[114:115]
	v_lshlrev_b64 v[116:117], 13, v[116:117]
	v_lshlrev_b64 v[118:119], 13, v[118:119]
	v_lshl_add_u64 v[122:123], v[2:3], 0, v[122:123]
	v_lshl_add_u64 v[106:107], v[2:3], 0, v[106:107]
	v_lshl_add_u64 v[108:109], v[2:3], 0, v[108:109]
	global_load_dword v141, v[120:121], off
	global_load_dword v142, v[104:105], off
	v_lshlrev_b64 v[120:121], 13, v[102:103]
	v_add_u32_e32 v102, s0, v133
	s_add_i32 s30, s30, 28
	v_or_b32_e32 v138, s43, v10
	v_lshl_add_u64 v[110:111], v[2:3], 0, v[110:111]
	v_lshl_add_u64 v[112:113], v[2:3], 0, v[112:113]
	v_lshl_add_u64 v[114:115], v[2:3], 0, v[114:115]
	v_lshl_add_u64 v[116:117], v[2:3], 0, v[116:117]
	v_lshl_add_u64 v[118:119], v[2:3], 0, v[118:119]
	global_load_dword v143, v[122:123], off
	global_load_dword v144, v[106:107], off
	global_load_dword v145, v[108:109], off
	global_load_dword v146, v[110:111], off
	global_load_dword v147, v[112:113], off
	global_load_dword v148, v[114:115], off
	global_load_dword v149, v[116:117], off
	global_load_dword v150, v[118:119], off
	v_lshl_add_u64 v[106:107], v[2:3], 0, v[120:121]
	v_lshlrev_b64 v[108:109], 13, v[102:103]
	v_add_u32_e32 v102, s0, v135
	v_or_b32_e32 v140, s30, v10
	v_lshl_add_u64 v[104:105], v[2:3], 0, v[124:125]
	global_load_dword v151, v[106:107], off
	global_load_dword v152, v[104:105], off
	v_lshlrev_b64 v[106:107], 13, v[102:103]
	v_add_u32_e32 v102, s0, v138
	v_lshl_add_u64 v[104:105], v[2:3], 0, v[108:109]
	v_lshlrev_b64 v[108:109], 13, v[102:103]
	v_add_u32_e32 v102, s0, v140
	v_lshlrev_b64 v[110:111], 13, v[102:103]
	v_lshl_add_u64 v[110:111], v[2:3], 0, v[110:111]
	v_lshl_add_u64 v[106:107], v[2:3], 0, v[106:107]
	v_lshl_add_u64 v[108:109], v[2:3], 0, v[108:109]
	global_load_dword v102, v[110:111], off
	global_load_dword v153, v[108:109], off
	global_load_dword v154, v[106:107], off
	global_load_dword v155, v[104:105], off
	s_add_i32 s25, s25, 16
	s_add_i32 s24, s24, 16
	s_add_i32 s26, s26, -16
	s_cmp_lg_u32 s26, 0
	s_lshl_b32 s30, s25, 1
	s_lshl_b32 s27, s24, 1
	v_or_b32_e32 v45, s30, v10
	s_add_i32 s33, s30, 4
	s_add_i32 s31, s27, 4
	s_add_i32 s34, s27, 8
	s_add_i32 s35, s30, 8
	v_add_u32_e32 v0, s0, v45
	v_or_b32_e32 v63, s33, v10
	v_or_b32_e32 v39, s27, v11
	s_add_i32 s36, s27, 12
	s_add_i32 s37, s30, 12
	s_add_i32 s38, s27, 16
	s_add_i32 s40, s27, 20
	s_add_i32 s42, s27, 24
	s_add_i32 s27, s27, 28
	v_or_b32_e32 v62, s31, v11
	v_or_b32_e32 v64, s34, v11
	v_or_b32_e32 v65, s35, v10
	v_lshlrev_b64 v[56:57], 13, v[0:1]
	v_add_u32_e32 v0, s0, v63
	v_mov_b32_e32 v5, v1
	v_mov_b32_e32 v7, v1
	v_mov_b32_e32 v9, v1
	s_add_i32 s39, s30, 16
	v_add_u32_e32 v4, s23, v39
	v_or_b32_e32 v66, s36, v11
	v_or_b32_e32 v67, s37, v10
	v_or_b32_e32 v68, s38, v11
	v_or_b32_e32 v70, s40, v11
	v_or_b32_e32 v72, s42, v11
	v_or_b32_e32 v74, s27, v11
	v_add_u32_e32 v6, s23, v62
	v_add_u32_e32 v8, s23, v64
	v_lshlrev_b64 v[58:59], 13, v[0:1]
	v_add_u32_e32 v0, s0, v65
	v_mov_b32_e32 v47, v1
	v_mov_b32_e32 v49, v1
	v_mov_b32_e32 v51, v1
	v_mov_b32_e32 v53, v1
	v_mov_b32_e32 v55, v1
	s_add_i32 s41, s30, 20
	v_or_b32_e32 v69, s39, v10
	v_lshlrev_b64 v[4:5], 13, v[4:5]
	v_add_u32_e32 v46, s23, v66
	v_add_u32_e32 v48, s23, v68
	v_add_u32_e32 v50, s23, v70
	v_add_u32_e32 v52, s23, v72
	v_add_u32_e32 v54, s23, v74
	v_lshl_add_u64 v[56:57], v[2:3], 0, v[56:57]
	v_lshlrev_b64 v[6:7], 13, v[6:7]
	v_lshlrev_b64 v[8:9], 13, v[8:9]
	v_lshlrev_b64 v[60:61], 13, v[0:1]
	v_add_u32_e32 v0, s0, v67
	s_add_i32 s43, s30, 24
	v_or_b32_e32 v71, s41, v10
	v_lshl_add_u64 v[4:5], v[2:3], 0, v[4:5]
	v_lshlrev_b64 v[46:47], 13, v[46:47]
	v_lshlrev_b64 v[48:49], 13, v[48:49]
	v_lshlrev_b64 v[50:51], 13, v[50:51]
	v_lshlrev_b64 v[52:53], 13, v[52:53]
	v_lshlrev_b64 v[54:55], 13, v[54:55]
	v_lshl_add_u64 v[58:59], v[2:3], 0, v[58:59]
	v_lshl_add_u64 v[6:7], v[2:3], 0, v[6:7]
; #define GAS __attribute__((address_space(1)))
; #define LAS __attribute__((address_space(3)))
; #define LDS_WAIT() asm volatile("s_waitcnt lgkmcnt(0)" ::: "memory")
; __device__ __forceinline__ unsigned pk2(float lo, float hi) { unsigned r; asm("v_cvt_pk_bf16_f32 %0, %1, %2" : "=v"(r) : "v"(lo), "v"(hi)); return r; }
; __device__ __forceinline__ void cvt_item(gfp W, int N, bf16* WT, int Kd, int k0, int n0, int drow0, LAS float* scr, int lane, gfp gk) {
;     ...
;     for (int i = 0; i < 32; ++i) { const int kk = 2 * i + (lane >> 5); scr[kk * 33 + (lane & 31)] = W[(size_t)(k0 + kk) * N + n0 + (lane & 31)]; }
;     const int c = lane & 7;
;     f32x4 ga = (f32x4){1.f, 1.f, 1.f, 1.f}, gb = ga;
;     if (gk != nullptr) { ga = *(const GAS f32x4*)(gk + k0 + 8 * c); gb = *(const GAS f32x4*)(gk + k0 + 8 * c + 4); }
;     LDS_WAIT(); asm volatile("" ::: "memory");
; #pragma unroll
;     for (int j = 0; j < 4; ++j) { const int n = (lane >> 3) + 8 * j; const LAS float* s = scr + (8 * c) * 33 + n;
;         v4u o; o.x = pk2(s[0 * 33] * ga[0], s[1 * 33] * ga[1]); o.y = pk2(s[2 * 33] * ga[2], s[3 * 33] * ga[3]); o.z = pk2(s[4 * 33] * gb[0], s[5 * 33] * gb[1]); o.w = pk2(s[6 * 33] * gb[2], s[7 * 33] * gb[3]);
;         *(GAS v4u*)(WT + (size_t)(drow0 + n) * Kd + k0 + 8 * c) = o; }
;     LDS_WAIT(); asm volatile("" ::: "memory");
	v_lshl_add_u64 v[8:9], v[2:3], 0, v[8:9]
	global_load_dword v76, v[56:57], off
	global_load_dword v77, v[4:5], off
	v_lshlrev_b64 v[56:57], 13, v[0:1]
	v_add_u32_e32 v0, s0, v69
	s_add_i32 s30, s30, 28
	v_or_b32_e32 v73, s43, v10
	v_lshl_add_u64 v[46:47], v[2:3], 0, v[46:47]
	v_lshl_add_u64 v[48:49], v[2:3], 0, v[48:49]
	v_lshl_add_u64 v[50:51], v[2:3], 0, v[50:51]
	v_lshl_add_u64 v[52:53], v[2:3], 0, v[52:53]
	v_lshl_add_u64 v[54:55], v[2:3], 0, v[54:55]
	global_load_dword v78, v[58:59], off
	global_load_dword v79, v[6:7], off
	global_load_dword v80, v[8:9], off
	global_load_dword v81, v[46:47], off
	global_load_dword v82, v[48:49], off
	global_load_dword v83, v[50:51], off
	global_load_dword v84, v[52:53], off
	global_load_dword v85, v[54:55], off
	v_lshl_add_u64 v[6:7], v[2:3], 0, v[56:57]
	v_lshlrev_b64 v[8:9], 13, v[0:1]
	v_add_u32_e32 v0, s0, v71
	v_or_b32_e32 v75, s30, v10
	v_lshl_add_u64 v[4:5], v[2:3], 0, v[60:61]
	global_load_dword v86, v[6:7], off
	global_load_dword v87, v[4:5], off
	v_lshlrev_b64 v[6:7], 13, v[0:1]
	v_add_u32_e32 v0, s0, v73
	v_lshl_add_u64 v[4:5], v[2:3], 0, v[8:9]
	v_lshlrev_b64 v[8:9], 13, v[0:1]
	v_add_u32_e32 v0, s0, v75
	v_lshlrev_b64 v[46:47], 13, v[0:1]
	v_lshl_add_u64 v[46:47], v[2:3], 0, v[46:47]
	v_lshl_add_u64 v[6:7], v[2:3], 0, v[6:7]
	v_lshl_add_u64 v[8:9], v[2:3], 0, v[8:9]
	global_load_dword v0, v[46:47], off
	global_load_dword v88, v[8:9], off
	global_load_dword v89, v[6:7], off
	global_load_dword v90, v[4:5], off
	v_mad_u64_u32 v[104:105], s[30:31], v136, s81, v[12:13]
	v_mad_u64_u32 v[106:107], s[30:31], v101, s81, v[12:13]
	v_mad_u64_u32 v[108:109], s[30:31], v127, s81, v[12:13]
	v_mad_u64_u32 v[110:111], s[30:31], v126, s81, v[12:13]
	v_mad_u64_u32 v[112:113], s[30:31], v129, s81, v[12:13]
	v_mad_u64_u32 v[114:115], s[30:31], v128, s81, v[12:13]
	v_mad_u64_u32 v[116:117], s[30:31], v131, s81, v[12:13]
	v_mad_u64_u32 v[118:119], s[30:31], v130, s81, v[12:13]
	v_mad_u64_u32 v[120:121], s[30:31], v133, s81, v[12:13]
	v_mad_u64_u32 v[122:123], s[30:31], v132, s81, v[12:13]
	v_mad_u64_u32 v[124:125], s[30:31], v135, s81, v[12:13]
	v_mad_u64_u32 v[126:127], s[30:31], v134, s81, v[12:13]
	v_mad_u64_u32 v[128:129], s[30:31], v138, s81, v[12:13]
	v_mad_u64_u32 v[130:131], s[30:31], v137, s81, v[12:13]
	v_mad_u64_u32 v[132:133], s[30:31], v140, s81, v[12:13]
	v_mad_u64_u32 v[134:135], s[30:31], v139, s81, v[12:13]
	s_waitcnt vmcnt(31)
	ds_write_b32 v104, v141
	s_waitcnt vmcnt(30)
	ds_write_b32 v106, v142
	s_waitcnt vmcnt(29)
	ds_write_b32 v108, v143
	s_waitcnt vmcnt(28)
	ds_write_b32 v110, v144
	s_waitcnt vmcnt(20)
	ds_write_b32 v112, v152
	ds_write_b32 v114, v145
	ds_write_b32 v116, v151
	ds_write_b32 v118, v146
	s_waitcnt vmcnt(16)
	ds_write_b32 v120, v155
	ds_write_b32 v122, v147
	ds_write_b32 v124, v154
	ds_write_b32 v126, v148
	ds_write_b32 v128, v153
	ds_write_b32 v130, v149
	ds_write_b32 v132, v102
	ds_write_b32 v134, v150
	v_mad_u64_u32 v[4:5], s[30:31], v45, s81, v[12:13]
	v_mad_u64_u32 v[6:7], s[30:31], v39, s81, v[12:13]
	v_mad_u64_u32 v[8:9], s[30:31], v63, s81, v[12:13]
	v_mad_u64_u32 v[46:47], s[30:31], v62, s81, v[12:13]
	v_mad_u64_u32 v[48:49], s[30:31], v65, s81, v[12:13]
	v_mad_u64_u32 v[50:51], s[30:31], v64, s81, v[12:13]
	v_mad_u64_u32 v[52:53], s[30:31], v67, s81, v[12:13]
	v_mad_u64_u32 v[54:55], s[30:31], v66, s81, v[12:13]
	v_mad_u64_u32 v[56:57], s[30:31], v69, s81, v[12:13]
	v_mad_u64_u32 v[58:59], s[30:31], v68, s81, v[12:13]
	v_mad_u64_u32 v[60:61], s[30:31], v71, s81, v[12:13]
	v_mad_u64_u32 v[62:63], s[30:31], v70, s81, v[12:13]
	v_mad_u64_u32 v[64:65], s[30:31], v73, s81, v[12:13]
	v_mad_u64_u32 v[66:67], s[30:31], v72, s81, v[12:13]
	v_mad_u64_u32 v[68:69], s[30:31], v75, s81, v[12:13]
	v_mad_u64_u32 v[70:71], s[30:31], v74, s81, v[12:13]
	s_waitcnt vmcnt(15)
	ds_write_b32 v4, v76
	s_waitcnt vmcnt(14)
	ds_write_b32 v6, v77
	s_waitcnt vmcnt(13)
	ds_write_b32 v8, v78
	s_waitcnt vmcnt(12)
	ds_write_b32 v46, v79
	s_waitcnt vmcnt(4)
	ds_write_b32 v48, v87
	ds_write_b32 v50, v80
	ds_write_b32 v52, v86
	ds_write_b32 v54, v81
	s_waitcnt vmcnt(0)
	ds_write_b32 v56, v90
	ds_write_b32 v58, v82
	ds_write_b32 v60, v89
	ds_write_b32 v62, v83
	ds_write_b32 v64, v88
	ds_write_b32 v66, v84
	ds_write_b32 v68, v0
	ds_write_b32 v70, v85
	s_add_i32 s25, s25, 16
	s_add_i32 s24, s24, 16
	s_add_i32 s26, s26, -16
	s_cmp_lg_u32 s26, 0
	s_and_b32 s22, 0xffff, s22
	s_waitcnt lgkmcnt(0)
	v_or_b32_e32 v0, s22, v40
	s_lshl_b32 s0, s0, 1
	ds_read2_b32 v[6:7], v41 offset0:33 offset1:41
	ds_read2_b32 v[8:9], v41 offset1:8
	ds_read2_b32 v[46:47], v41 offset0:66 offset1:74
	ds_read2_b32 v[48:49], v41 offset0:99 offset1:107
	ds_read2_b32 v[50:51], v41 offset0:132 offset1:140
	ds_read2_b32 v[52:53], v41 offset0:165 offset1:173
	ds_read2_b32 v[54:55], v41 offset0:198 offset1:206
	ds_read2_b32 v[56:57], v41 offset0:231 offset1:239
	v_mul_u32_u24_e32 v0, 0x1600, v0
	v_lshl_add_u64 v[58:59], v[24:25], 0, s[0:1]
	v_lshlrev_b32_e32 v0, 1, v0
	v_lshl_add_u64 v[60:61], v[58:59], 0, v[0:1]
	v_or_b32_e32 v0, s22, v42
	v_mul_u32_u24_e32 v0, 0x1600, v0
	s_waitcnt lgkmcnt(6)
	v_cvt_pk_bf16_f32 v2, v8, v6
	v_lshlrev_b32_e32 v0, 1, v0
	s_waitcnt lgkmcnt(4)
	v_cvt_pk_bf16_f32 v3, v46, v48
	s_waitcnt lgkmcnt(2)
	v_cvt_pk_bf16_f32 v4, v50, v52
	s_waitcnt lgkmcnt(0)
	v_cvt_pk_bf16_f32 v5, v54, v56
	global_store_dwordx4 v[60:61], v[2:5], off
	s_nop 1
	v_cvt_pk_bf16_f32 v2, v9, v7
	v_lshl_add_u64 v[6:7], v[58:59], 0, v[0:1]
	v_or_b32_e32 v0, s22, v43
	v_cvt_pk_bf16_f32 v3, v47, v49
	v_cvt_pk_bf16_f32 v4, v51, v53
	v_cvt_pk_bf16_f32 v5, v55, v57
	ds_read2_b32 v[8:9], v41 offset0:16 offset1:24
	ds_read2_b32 v[46:47], v41 offset0:49 offset1:57
	ds_read2_b32 v[48:49], v41 offset0:82 offset1:90
	ds_read2_b32 v[50:51], v41 offset0:115 offset1:123
	ds_read2_b32 v[52:53], v41 offset0:148 offset1:156
	ds_read2_b32 v[54:55], v41 offset0:181 offset1:189
	ds_read2_b32 v[56:57], v41 offset0:214 offset1:222
	ds_read2_b32 v[60:61], v41 offset0:247 offset1:255
	v_mul_u32_u24_e32 v0, 0x1600, v0
	v_lshlrev_b32_e32 v0, 1, v0
	global_store_dwordx4 v[6:7], v[2:5], off
	v_lshl_add_u64 v[6:7], v[58:59], 0, v[0:1]
	v_or_b32_e32 v0, s22, v44
	v_mul_u32_u24_e32 v0, 0x1600, v0
	v_lshlrev_b32_e32 v0, 1, v0
	s_waitcnt lgkmcnt(6)
	v_cvt_pk_bf16_f32 v2, v8, v46
	s_waitcnt lgkmcnt(4)
	v_cvt_pk_bf16_f32 v3, v48, v50
	s_waitcnt lgkmcnt(2)
	v_cvt_pk_bf16_f32 v4, v52, v54
	s_waitcnt lgkmcnt(0)
	v_cvt_pk_bf16_f32 v5, v56, v60
	global_store_dwordx4 v[6:7], v[2:5], off
	v_lshl_add_u64 v[6:7], v[58:59], 0, v[0:1]
	s_nop 0
	v_cvt_pk_bf16_f32 v2, v9, v47
	v_cvt_pk_bf16_f32 v3, v49, v51
	v_cvt_pk_bf16_f32 v4, v53, v55
	v_cvt_pk_bf16_f32 v5, v57, v61
	global_store_dwordx4 v[6:7], v[2:5], off
	s_waitcnt lgkmcnt(0)

; __device__ __forceinline__ void cvt_item(gfp W, int N, bf16* WT, int Kd, int k0, int n0, int drow0, LAS float* scr, int lane, gfp gk) {
; #pragma unroll 8
;     for (int i = 0; i < 32; ++i) { const int kk = 2 * i + (lane >> 5); scr[kk * 33 + (lane & 31)] = W[(size_t)(k0 + kk) * N + n0 + (lane & 31)]; }
.LBB0_172:
	v_mov_b32_e32 v103, v1
	s_lshl_b32 s30, s25, 1
	s_lshl_b32 s27, s24, 1
	v_or_b32_e32 v136, s30, v10
	s_add_i32 s33, s30, 4
	s_add_i32 s31, s27, 4
	s_add_i32 s34, s27, 8
	s_add_i32 s35, s30, 8
	v_add_u32_e32 v102, s0, v136
	v_or_b32_e32 v127, s33, v10
	v_or_b32_e32 v101, s27, v11
	s_add_i32 s36, s27, 12
	s_add_i32 s37, s30, 12
	s_add_i32 s38, s27, 16
	s_add_i32 s40, s27, 20
	s_add_i32 s42, s27, 24
	s_add_i32 s27, s27, 28
	v_or_b32_e32 v126, s31, v11
	v_or_b32_e32 v128, s34, v11
	v_or_b32_e32 v129, s35, v10
	v_lshlrev_b64 v[120:121], 13, v[102:103]
	v_add_u32_e32 v102, s0, v127
	v_mov_b32_e32 v105, v103
	v_mov_b32_e32 v107, v103
	v_mov_b32_e32 v109, v103
	s_add_i32 s39, s30, 16
	v_add_u32_e32 v104, s23, v101
	v_or_b32_e32 v130, s36, v11
	v_or_b32_e32 v131, s37, v10
	v_or_b32_e32 v132, s38, v11
	v_or_b32_e32 v134, s40, v11
	v_or_b32_e32 v137, s42, v11
	v_or_b32_e32 v139, s27, v11
	v_add_u32_e32 v106, s23, v126
	v_add_u32_e32 v108, s23, v128
	v_lshlrev_b64 v[122:123], 13, v[102:103]
	v_add_u32_e32 v102, s0, v129
	v_mov_b32_e32 v111, v103
	v_mov_b32_e32 v113, v103
	v_mov_b32_e32 v115, v103
	v_mov_b32_e32 v117, v103
	v_mov_b32_e32 v119, v103
	s_add_i32 s41, s30, 20
	v_or_b32_e32 v133, s39, v10
	v_lshlrev_b64 v[104:105], 13, v[104:105]
	v_add_u32_e32 v110, s23, v130
	v_add_u32_e32 v112, s23, v132
	v_add_u32_e32 v114, s23, v134
	v_add_u32_e32 v116, s23, v137
	v_add_u32_e32 v118, s23, v139
	v_lshl_add_u64 v[120:121], v[2:3], 0, v[120:121]
	v_lshlrev_b64 v[106:107], 13, v[106:107]
	v_lshlrev_b64 v[108:109], 13, v[108:109]
	v_lshlrev_b64 v[124:125], 13, v[102:103]
	v_add_u32_e32 v102, s0, v131
	s_add_i32 s43, s30, 24
	v_or_b32_e32 v135, s41, v10
	v_lshl_add_u64 v[104:105], v[2:3], 0, v[104:105]
	v_lshlrev_b64 v[110:111], 13, v[110:111]
	v_lshlrev_b64 v[112:113], 13, v[112:113]
	v_lshlrev_b64 v[114:115], 13, v[114:115]
	v_lshlrev_b64 v[116:117], 13, v[116:117]
	v_lshlrev_b64 v[118:119], 13, v[118:119]
	v_lshl_add_u64 v[122:123], v[2:3], 0, v[122:123]
	v_lshl_add_u64 v[106:107], v[2:3], 0, v[106:107]
	v_lshl_add_u64 v[108:109], v[2:3], 0, v[108:109]
	global_load_dword v141, v[120:121], off
	global_load_dword v142, v[104:105], off
	v_lshlrev_b64 v[120:121], 13, v[102:103]
	v_add_u32_e32 v102, s0, v133
	s_add_i32 s30, s30, 28
	v_or_b32_e32 v138, s43, v10
	v_lshl_add_u64 v[110:111], v[2:3], 0, v[110:111]
	v_lshl_add_u64 v[112:113], v[2:3], 0, v[112:113]
	v_lshl_add_u64 v[114:115], v[2:3], 0, v[114:115]
	v_lshl_add_u64 v[116:117], v[2:3], 0, v[116:117]
	v_lshl_add_u64 v[118:119], v[2:3], 0, v[118:119]
	global_load_dword v143, v[122:123], off
	global_load_dword v144, v[106:107], off
	global_load_dword v145, v[108:109], off
	global_load_dword v146, v[110:111], off
	global_load_dword v147, v[112:113], off
	global_load_dword v148, v[114:115], off
	global_load_dword v149, v[116:117], off
	global_load_dword v150, v[118:119], off
	v_lshl_add_u64 v[106:107], v[2:3], 0, v[120:121]
	v_lshlrev_b64 v[108:109], 13, v[102:103]
	v_add_u32_e32 v102, s0, v135
	v_or_b32_e32 v140, s30, v10
	v_lshl_add_u64 v[104:105], v[2:3], 0, v[124:125]
	global_load_dword v151, v[106:107], off
	global_load_dword v152, v[104:105], off
	v_lshlrev_b64 v[106:107], 13, v[102:103]
	v_add_u32_e32 v102, s0, v138
	v_lshl_add_u64 v[104:105], v[2:3], 0, v[108:109]
	v_lshlrev_b64 v[108:109], 13, v[102:103]
	v_add_u32_e32 v102, s0, v140
	v_lshlrev_b64 v[110:111], 13, v[102:103]
	v_lshl_add_u64 v[110:111], v[2:3], 0, v[110:111]
	v_lshl_add_u64 v[106:107], v[2:3], 0, v[106:107]
	v_lshl_add_u64 v[108:109], v[2:3], 0, v[108:109]
	global_load_dword v102, v[110:111], off
	global_load_dword v153, v[108:109], off
	global_load_dword v154, v[106:107], off
	global_load_dword v155, v[104:105], off
	s_add_i32 s25, s25, 16
	s_add_i32 s24, s24, 16
	s_add_i32 s26, s26, -16
	s_cmp_lg_u32 s26, 0
	s_lshl_b32 s30, s25, 1
	s_lshl_b32 s27, s24, 1
	v_or_b32_e32 v45, s30, v10
	s_add_i32 s33, s30, 4
	s_add_i32 s31, s27, 4
	s_add_i32 s34, s27, 8
	s_add_i32 s35, s30, 8
	v_add_u32_e32 v0, s0, v45
	v_or_b32_e32 v63, s33, v10
	v_or_b32_e32 v39, s27, v11
	s_add_i32 s36, s27, 12
	s_add_i32 s37, s30, 12
	s_add_i32 s38, s27, 16
	s_add_i32 s40, s27, 20
	s_add_i32 s42, s27, 24
	s_add_i32 s27, s27, 28
	v_or_b32_e32 v62, s31, v11
	v_or_b32_e32 v64, s34, v11
	v_or_b32_e32 v65, s35, v10
	v_lshlrev_b64 v[56:57], 13, v[0:1]
	v_add_u32_e32 v0, s0, v63
	v_mov_b32_e32 v5, v1
	v_mov_b32_e32 v7, v1
	v_mov_b32_e32 v9, v1
	s_add_i32 s39, s30, 16
	v_add_u32_e32 v4, s23, v39
	v_or_b32_e32 v66, s36, v11
	v_or_b32_e32 v67, s37, v10
	v_or_b32_e32 v68, s38, v11
	v_or_b32_e32 v70, s40, v11
	v_or_b32_e32 v72, s42, v11
	v_or_b32_e32 v74, s27, v11
	v_add_u32_e32 v6, s23, v62
	v_add_u32_e32 v8, s23, v64
	v_lshlrev_b64 v[58:59], 13, v[0:1]
	v_add_u32_e32 v0, s0, v65
	v_mov_b32_e32 v47, v1
	v_mov_b32_e32 v49, v1
	v_mov_b32_e32 v51, v1
	v_mov_b32_e32 v53, v1
	v_mov_b32_e32 v55, v1
	s_add_i32 s41, s30, 20
	v_or_b32_e32 v69, s39, v10
	v_lshlrev_b64 v[4:5], 13, v[4:5]
	v_add_u32_e32 v46, s23, v66
	v_add_u32_e32 v48, s23, v68
	v_add_u32_e32 v50, s23, v70
	v_add_u32_e32 v52, s23, v72
	v_add_u32_e32 v54, s23, v74
	v_lshl_add_u64 v[56:57], v[2:3], 0, v[56:57]
	v_lshlrev_b64 v[6:7], 13, v[6:7]
	v_lshlrev_b64 v[8:9], 13, v[8:9]
	v_lshlrev_b64 v[60:61], 13, v[0:1]
	v_add_u32_e32 v0, s0, v67
	s_add_i32 s43, s30, 24
	v_or_b32_e32 v71, s41, v10
	v_lshl_add_u64 v[4:5], v[2:3], 0, v[4:5]
	v_lshlrev_b64 v[46:47], 13, v[46:47]
	v_lshlrev_b64 v[48:49], 13, v[48:49]
	v_lshlrev_b64 v[50:51], 13, v[50:51]
	v_lshlrev_b64 v[52:53], 13, v[52:53]
	v_lshlrev_b64 v[54:55], 13, v[54:55]
	v_lshl_add_u64 v[58:59], v[2:3], 0, v[58:59]
	v_lshl_add_u64 v[6:7], v[2:3], 0, v[6:7]
; #define GAS __attribute__((address_space(1)))
; #define LAS __attribute__((address_space(3)))
; #define LDS_WAIT() asm volatile("s_waitcnt lgkmcnt(0)" ::: "memory")
; __device__ __forceinline__ unsigned pk2(float lo, float hi) { unsigned r; asm("v_cvt_pk_bf16_f32 %0, %1, %2" : "=v"(r) : "v"(lo), "v"(hi)); return r; }
; __device__ __forceinline__ void cvt_item(gfp W, int N, bf16* WT, int Kd, int k0, int n0, int drow0, LAS float* scr, int lane, gfp gk) {
;     ...
;     for (int i = 0; i < 32; ++i) { const int kk = 2 * i + (lane >> 5); scr[kk * 33 + (lane & 31)] = W[(size_t)(k0 + kk) * N + n0 + (lane & 31)]; }
;     const int c = lane & 7;
;     f32x4 ga = (f32x4){1.f, 1.f, 1.f, 1.f}, gb = ga;
;     if (gk != nullptr) { ga = *(const GAS f32x4*)(gk + k0 + 8 * c); gb = *(const GAS f32x4*)(gk + k0 + 8 * c + 4); }
;     LDS_WAIT(); asm volatile("" ::: "memory");
; #pragma unroll
;     for (int j = 0; j < 4; ++j) { const int n = (lane >> 3) + 8 * j; const LAS float* s = scr + (8 * c) * 33 + n;
;         v4u o; o.x = pk2(s[0 * 33] * ga[0], s[1 * 33] * ga[1]); o.y = pk2(s[2 * 33] * ga[2], s[3 * 33] * ga[3]); o.z = pk2(s[4 * 33] * gb[0], s[5 * 33] * gb[1]); o.w = pk2(s[6 * 33] * gb[2], s[7 * 33] * gb[3]);
;         *(GAS v4u*)(WT + (size_t)(drow0 + n) * Kd + k0 + 8 * c) = o; }
;     LDS_WAIT(); asm volatile("" ::: "memory");
	v_lshl_add_u64 v[8:9], v[2:3], 0, v[8:9]
	global_load_dword v76, v[56:57], off
	global_load_dword v77, v[4:5], off
	v_lshlrev_b64 v[56:57], 13, v[0:1]
	v_add_u32_e32 v0, s0, v69
	s_add_i32 s30, s30, 28
	v_or_b32_e32 v73, s43, v10
	v_lshl_add_u64 v[46:47], v[2:3], 0, v[46:47]
	v_lshl_add_u64 v[48:49], v[2:3], 0, v[48:49]
	v_lshl_add_u64 v[50:51], v[2:3], 0, v[50:51]
	v_lshl_add_u64 v[52:53], v[2:3], 0, v[52:53]
	v_lshl_add_u64 v[54:55], v[2:3], 0, v[54:55]
	global_load_dword v78, v[58:59], off
	global_load_dword v79, v[6:7], off
	global_load_dword v80, v[8:9], off
	global_load_dword v81, v[46:47], off
	global_load_dword v82, v[48:49], off
	global_load_dword v83, v[50:51], off
	global_load_dword v84, v[52:53], off
	global_load_dword v85, v[54:55], off
	v_lshl_add_u64 v[6:7], v[2:3], 0, v[56:57]
	v_lshlrev_b64 v[8:9], 13, v[0:1]
	v_add_u32_e32 v0, s0, v71
	v_or_b32_e32 v75, s30, v10
	v_lshl_add_u64 v[4:5], v[2:3], 0, v[60:61]
	global_load_dword v86, v[6:7], off
	global_load_dword v87, v[4:5], off
	v_lshlrev_b64 v[6:7], 13, v[0:1]
	v_add_u32_e32 v0, s0, v73
	v_lshl_add_u64 v[4:5], v[2:3], 0, v[8:9]
	v_lshlrev_b64 v[8:9], 13, v[0:1]
	v_add_u32_e32 v0, s0, v75
	v_lshlrev_b64 v[46:47], 13, v[0:1]
	v_lshl_add_u64 v[46:47], v[2:3], 0, v[46:47]
	v_lshl_add_u64 v[6:7], v[2:3], 0, v[6:7]
	v_lshl_add_u64 v[8:9], v[2:3], 0, v[8:9]
	global_load_dword v0, v[46:47], off
	global_load_dword v88, v[8:9], off
	global_load_dword v89, v[6:7], off
	global_load_dword v90, v[4:5], off
	v_mad_u64_u32 v[104:105], s[30:31], v136, s81, v[12:13]
	v_mad_u64_u32 v[106:107], s[30:31], v101, s81, v[12:13]
	v_mad_u64_u32 v[108:109], s[30:31], v127, s81, v[12:13]
	v_mad_u64_u32 v[110:111], s[30:31], v126, s81, v[12:13]
	v_mad_u64_u32 v[112:113], s[30:31], v129, s81, v[12:13]
	v_mad_u64_u32 v[114:115], s[30:31], v128, s81, v[12:13]
	v_mad_u64_u32 v[116:117], s[30:31], v131, s81, v[12:13]
	v_mad_u64_u32 v[118:119], s[30:31], v130, s81, v[12:13]
	v_mad_u64_u32 v[120:121], s[30:31], v133, s81, v[12:13]
	v_mad_u64_u32 v[122:123], s[30:31], v132, s81, v[12:13]
	v_mad_u64_u32 v[124:125], s[30:31], v135, s81, v[12:13]
	v_mad_u64_u32 v[126:127], s[30:31], v134, s81, v[12:13]
	v_mad_u64_u32 v[128:129], s[30:31], v138, s81, v[12:13]
	v_mad_u64_u32 v[130:131], s[30:31], v137, s81, v[12:13]
	v_mad_u64_u32 v[132:133], s[30:31], v140, s81, v[12:13]
	v_mad_u64_u32 v[134:135], s[30:31], v139, s81, v[12:13]
	s_waitcnt vmcnt(31)
	ds_write_b32 v104, v141
	s_waitcnt vmcnt(30)
	ds_write_b32 v106, v142
	s_waitcnt vmcnt(29)
	ds_write_b32 v108, v143
	s_waitcnt vmcnt(28)
	ds_write_b32 v110, v144
	s_waitcnt vmcnt(20)
	ds_write_b32 v112, v152
	ds_write_b32 v114, v145
	ds_write_b32 v116, v151
	ds_write_b32 v118, v146
	s_waitcnt vmcnt(16)
	ds_write_b32 v120, v155
	ds_write_b32 v122, v147
	ds_write_b32 v124, v154
	ds_write_b32 v126, v148
	ds_write_b32 v128, v153
	ds_write_b32 v130, v149
	ds_write_b32 v132, v102
	ds_write_b32 v134, v150
	v_mad_u64_u32 v[4:5], s[30:31], v45, s81, v[12:13]
	v_mad_u64_u32 v[6:7], s[30:31], v39, s81, v[12:13]
	v_mad_u64_u32 v[8:9], s[30:31], v63, s81, v[12:13]
	v_mad_u64_u32 v[46:47], s[30:31], v62, s81, v[12:13]
	v_mad_u64_u32 v[48:49], s[30:31], v65, s81, v[12:13]
	v_mad_u64_u32 v[50:51], s[30:31], v64, s81, v[12:13]
	v_mad_u64_u32 v[52:53], s[30:31], v67, s81, v[12:13]
	v_mad_u64_u32 v[54:55], s[30:31], v66, s81, v[12:13]
	v_mad_u64_u32 v[56:57], s[30:31], v69, s81, v[12:13]
	v_mad_u64_u32 v[58:59], s[30:31], v68, s81, v[12:13]
	v_mad_u64_u32 v[60:61], s[30:31], v71, s81, v[12:13]
	v_mad_u64_u32 v[62:63], s[30:31], v70, s81, v[12:13]
	v_mad_u64_u32 v[64:65], s[30:31], v73, s81, v[12:13]
	v_mad_u64_u32 v[66:67], s[30:31], v72, s81, v[12:13]
	v_mad_u64_u32 v[68:69], s[30:31], v75, s81, v[12:13]
	v_mad_u64_u32 v[70:71], s[30:31], v74, s81, v[12:13]
	s_waitcnt vmcnt(15)
	ds_write_b32 v4, v76
	s_waitcnt vmcnt(14)
	ds_write_b32 v6, v77
	s_waitcnt vmcnt(13)
	ds_write_b32 v8, v78
	s_waitcnt vmcnt(12)
	ds_write_b32 v46, v79
	s_waitcnt vmcnt(4)
	ds_write_b32 v48, v87
	ds_write_b32 v50, v80
	ds_write_b32 v52, v86
	ds_write_b32 v54, v81
	s_waitcnt vmcnt(0)
	ds_write_b32 v56, v90
	ds_write_b32 v58, v82
	ds_write_b32 v60, v89
	ds_write_b32 v62, v83
	ds_write_b32 v64, v88
	ds_write_b32 v66, v84
	ds_write_b32 v68, v0
	ds_write_b32 v70, v85
	s_add_i32 s25, s25, 16
	s_add_i32 s24, s24, 16
	s_add_i32 s26, s26, -16
	s_cmp_lg_u32 s26, 0
	s_and_b32 s22, 0xffff, s22
	s_waitcnt lgkmcnt(0)
	v_or_b32_e32 v0, s22, v40
	s_lshl_b32 s0, s0, 1
	ds_read2_b32 v[6:7], v41 offset0:33 offset1:41
	ds_read2_b32 v[8:9], v41 offset1:8
	ds_read2_b32 v[46:47], v41 offset0:66 offset1:74
	ds_read2_b32 v[48:49], v41 offset0:99 offset1:107
	ds_read2_b32 v[50:51], v41 offset0:132 offset1:140
	ds_read2_b32 v[52:53], v41 offset0:165 offset1:173
	ds_read2_b32 v[54:55], v41 offset0:198 offset1:206
	ds_read2_b32 v[56:57], v41 offset0:231 offset1:239
	v_mul_u32_u24_e32 v0, 0x1600, v0
	v_lshl_add_u64 v[58:59], v[26:27], 0, s[0:1]
	v_lshlrev_b32_e32 v0, 1, v0
	v_lshl_add_u64 v[60:61], v[58:59], 0, v[0:1]
	v_or_b32_e32 v0, s22, v42
	v_mul_u32_u24_e32 v0, 0x1600, v0
	s_waitcnt lgkmcnt(6)
	v_cvt_pk_bf16_f32 v2, v8, v6
	v_lshlrev_b32_e32 v0, 1, v0
	s_waitcnt lgkmcnt(4)
	v_cvt_pk_bf16_f32 v3, v46, v48
	s_waitcnt lgkmcnt(2)
	v_cvt_pk_bf16_f32 v4, v50, v52
	s_waitcnt lgkmcnt(0)
	v_cvt_pk_bf16_f32 v5, v54, v56
	global_store_dwordx4 v[60:61], v[2:5], off
	s_nop 1
	v_cvt_pk_bf16_f32 v2, v9, v7
	v_lshl_add_u64 v[6:7], v[58:59], 0, v[0:1]
	v_or_b32_e32 v0, s22, v43
	v_cvt_pk_bf16_f32 v3, v47, v49
	v_cvt_pk_bf16_f32 v4, v51, v53
	v_cvt_pk_bf16_f32 v5, v55, v57
	ds_read2_b32 v[8:9], v41 offset0:16 offset1:24
	ds_read2_b32 v[46:47], v41 offset0:49 offset1:57
	ds_read2_b32 v[48:49], v41 offset0:82 offset1:90
	ds_read2_b32 v[50:51], v41 offset0:115 offset1:123
	ds_read2_b32 v[52:53], v41 offset0:148 offset1:156
	ds_read2_b32 v[54:55], v41 offset0:181 offset1:189
	ds_read2_b32 v[56:57], v41 offset0:214 offset1:222
	ds_read2_b32 v[60:61], v41 offset0:247 offset1:255
	v_mul_u32_u24_e32 v0, 0x1600, v0
	v_lshlrev_b32_e32 v0, 1, v0
	global_store_dwordx4 v[6:7], v[2:5], off
	v_lshl_add_u64 v[6:7], v[58:59], 0, v[0:1]
	v_or_b32_e32 v0, s22, v44
	v_mul_u32_u24_e32 v0, 0x1600, v0
	v_lshlrev_b32_e32 v0, 1, v0
	s_waitcnt lgkmcnt(6)
	v_cvt_pk_bf16_f32 v2, v8, v46
	s_waitcnt lgkmcnt(4)
	v_cvt_pk_bf16_f32 v3, v48, v50
	s_waitcnt lgkmcnt(2)
	v_cvt_pk_bf16_f32 v4, v52, v54
	s_waitcnt lgkmcnt(0)
	v_cvt_pk_bf16_f32 v5, v56, v60
	global_store_dwordx4 v[6:7], v[2:5], off
	v_lshl_add_u64 v[6:7], v[58:59], 0, v[0:1]
	s_nop 0
	v_cvt_pk_bf16_f32 v2, v9, v47
	v_cvt_pk_bf16_f32 v3, v49, v51
	v_cvt_pk_bf16_f32 v4, v53, v55
	v_cvt_pk_bf16_f32 v5, v57, v61
	global_store_dwordx4 v[6:7], v[2:5], off
	s_waitcnt lgkmcnt(0)

; __device__ __forceinline__ void cvt_item(gfp W, int N, bf16* WT, int Kd, int k0, int n0, int drow0, LAS float* scr, int lane, gfp gk) {
; #pragma unroll 8
;     for (int i = 0; i < 32; ++i) { const int kk = 2 * i + (lane >> 5); scr[kk * 33 + (lane & 31)] = W[(size_t)(k0 + kk) * N + n0 + (lane & 31)]; }
.LBB0_177:
	s_lshl_b32 s33, s27, 1
	s_lshl_b32 s34, s30, 1
	v_or_b32_e32 v101, s33, v11
	v_or_b32_e32 v134, s34, v10
	s_add_i32 s35, s33, 4
	s_add_i32 s36, s34, 4
	s_add_i32 s37, s33, 8
	s_add_i32 s38, s34, 8
	s_add_i32 s39, s33, 12
	s_add_i32 s40, s34, 12
	s_add_i32 s41, s33, 16
	s_add_i32 s42, s34, 16
	s_add_i32 s43, s33, 20
	s_add_i32 s44, s34, 20
	s_add_i32 s45, s33, 24
	s_add_i32 s46, s34, 24
	s_add_i32 s33, s33, 28
	s_add_i32 s34, s34, 28
	v_add_u32_e32 v102, s25, v134
	v_or_b32_e32 v135, s35, v11
	v_or_b32_e32 v136, s36, v10
	v_or_b32_e32 v137, s37, v11
	v_or_b32_e32 v138, s38, v10
	v_or_b32_e32 v139, s39, v11
	v_or_b32_e32 v140, s40, v10
	v_or_b32_e32 v141, s41, v11
	v_or_b32_e32 v142, s42, v10
	v_or_b32_e32 v143, s43, v11
	v_or_b32_e32 v144, s44, v10
	v_or_b32_e32 v145, s45, v11
	v_or_b32_e32 v146, s46, v10
	v_or_b32_e32 v147, s33, v11
	v_or_b32_e32 v148, s34, v10
	v_add_u32_e32 v104, s26, v101
	v_mad_u64_u32 v[102:103], s[34:35], v102, s74, v[2:3]
	v_add_u32_e32 v108, s26, v135
	v_add_u32_e32 v106, s25, v136
	v_add_u32_e32 v112, s26, v137
	v_add_u32_e32 v110, s25, v138
	v_add_u32_e32 v116, s26, v139
	v_add_u32_e32 v114, s25, v140
	v_add_u32_e32 v120, s26, v141
	v_add_u32_e32 v118, s25, v142
	v_add_u32_e32 v124, s26, v143
	v_add_u32_e32 v122, s25, v144
	v_add_u32_e32 v128, s26, v145
	v_add_u32_e32 v126, s25, v146
	v_add_u32_e32 v132, s26, v147
	v_add_u32_e32 v130, s25, v148
	v_mad_u64_u32 v[104:105], s[34:35], v104, s74, v[2:3]
	v_mad_u64_u32 v[106:107], s[34:35], v106, s74, v[2:3]
	v_mad_u64_u32 v[108:109], s[34:35], v108, s74, v[2:3]
	v_mad_u64_u32 v[110:111], s[34:35], v110, s74, v[2:3]
	v_mad_u64_u32 v[112:113], s[34:35], v112, s74, v[2:3]
	v_mad_u64_u32 v[114:115], s[34:35], v114, s74, v[2:3]
	v_mad_u64_u32 v[116:117], s[34:35], v116, s74, v[2:3]
	v_mad_u64_u32 v[118:119], s[34:35], v118, s74, v[2:3]
	v_mad_u64_u32 v[120:121], s[34:35], v120, s74, v[2:3]
	v_mad_u64_u32 v[122:123], s[34:35], v122, s74, v[2:3]
	v_mad_u64_u32 v[124:125], s[34:35], v124, s74, v[2:3]
	v_mad_u64_u32 v[126:127], s[34:35], v126, s74, v[2:3]
	v_mad_u64_u32 v[128:129], s[34:35], v128, s74, v[2:3]
	v_mad_u64_u32 v[130:131], s[34:35], v130, s74, v[2:3]
	v_mad_u64_u32 v[132:133], s[34:35], v132, s74, v[2:3]
	global_load_dword v149, v[102:103], off
	global_load_dword v150, v[104:105], off
	global_load_dword v151, v[106:107], off
	global_load_dword v152, v[108:109], off
	global_load_dword v153, v[110:111], off
	global_load_dword v154, v[112:113], off
	global_load_dword v155, v[114:115], off
	global_load_dword v156, v[116:117], off
	global_load_dword v157, v[118:119], off
	global_load_dword v158, v[120:121], off
	global_load_dword v159, v[122:123], off
	global_load_dword v160, v[124:125], off
	global_load_dword v161, v[126:127], off
	global_load_dword v162, v[128:129], off
	global_load_dword v163, v[130:131], off
	global_load_dword v164, v[132:133], off
	s_add_i32 s30, s30, 16
	s_add_i32 s27, s27, 16
	s_add_i32 s31, s31, -16
	s_cmp_lg_u32 s31, 0
	s_lshl_b32 s33, s27, 1
	s_lshl_b32 s34, s30, 1
	v_or_b32_e32 v0, s33, v11
	v_or_b32_e32 v39, s34, v10
	s_add_i32 s35, s33, 4
	s_add_i32 s36, s34, 4
	s_add_i32 s37, s33, 8
	s_add_i32 s38, s34, 8
	s_add_i32 s39, s33, 12
	s_add_i32 s40, s34, 12
	s_add_i32 s41, s33, 16
	s_add_i32 s42, s34, 16
	s_add_i32 s43, s33, 20
	s_add_i32 s44, s34, 20
	s_add_i32 s45, s33, 24
	s_add_i32 s46, s34, 24
	s_add_i32 s33, s33, 28
	s_add_i32 s34, s34, 28
	v_add_u32_e32 v4, s25, v39
	v_or_b32_e32 v45, s35, v11
	v_or_b32_e32 v72, s36, v10
	v_or_b32_e32 v73, s37, v11
	v_or_b32_e32 v74, s38, v10
	v_or_b32_e32 v75, s39, v11
	v_or_b32_e32 v76, s40, v10
	v_or_b32_e32 v77, s41, v11
	v_or_b32_e32 v78, s42, v10
	v_or_b32_e32 v79, s43, v11
	v_or_b32_e32 v80, s44, v10
	v_or_b32_e32 v81, s45, v11
	v_or_b32_e32 v82, s46, v10
	v_or_b32_e32 v83, s33, v11
	v_or_b32_e32 v84, s34, v10
	v_add_u32_e32 v6, s26, v0
	v_mad_u64_u32 v[4:5], s[34:35], v4, s74, v[2:3]
	v_add_u32_e32 v46, s26, v45
	v_add_u32_e32 v8, s25, v72
	v_add_u32_e32 v50, s26, v73
	v_add_u32_e32 v48, s25, v74
	v_add_u32_e32 v54, s26, v75
	v_add_u32_e32 v52, s25, v76
	v_add_u32_e32 v58, s26, v77
	v_add_u32_e32 v56, s25, v78
	v_add_u32_e32 v62, s26, v79
	v_add_u32_e32 v60, s25, v80
	v_add_u32_e32 v66, s26, v81
	v_add_u32_e32 v64, s25, v82
	v_add_u32_e32 v70, s26, v83
	v_add_u32_e32 v68, s25, v84
	v_mad_u64_u32 v[6:7], s[34:35], v6, s74, v[2:3]
	v_mad_u64_u32 v[8:9], s[34:35], v8, s74, v[2:3]
	v_mad_u64_u32 v[46:47], s[34:35], v46, s74, v[2:3]
	v_mad_u64_u32 v[48:49], s[34:35], v48, s74, v[2:3]
	v_mad_u64_u32 v[50:51], s[34:35], v50, s74, v[2:3]
	v_mad_u64_u32 v[52:53], s[34:35], v52, s74, v[2:3]
	v_mad_u64_u32 v[54:55], s[34:35], v54, s74, v[2:3]
	v_mad_u64_u32 v[56:57], s[34:35], v56, s74, v[2:3]
	v_mad_u64_u32 v[58:59], s[34:35], v58, s74, v[2:3]
	v_mad_u64_u32 v[60:61], s[34:35], v60, s74, v[2:3]
	v_mad_u64_u32 v[62:63], s[34:35], v62, s74, v[2:3]
	v_mad_u64_u32 v[64:65], s[34:35], v64, s74, v[2:3]
	v_mad_u64_u32 v[66:67], s[34:35], v66, s74, v[2:3]
	v_mad_u64_u32 v[68:69], s[34:35], v68, s74, v[2:3]
	v_mad_u64_u32 v[70:71], s[34:35], v70, s74, v[2:3]
	global_load_dword v85, v[4:5], off
	global_load_dword v86, v[6:7], off
	global_load_dword v87, v[8:9], off
	global_load_dword v88, v[46:47], off
	global_load_dword v89, v[48:49], off
	global_load_dword v90, v[50:51], off
	global_load_dword v91, v[52:53], off
	global_load_dword v92, v[54:55], off
	global_load_dword v93, v[56:57], off
	global_load_dword v94, v[58:59], off
	global_load_dword v95, v[60:61], off
	global_load_dword v96, v[62:63], off
	global_load_dword v97, v[64:65], off
	global_load_dword v98, v[66:67], off
	global_load_dword v99, v[68:69], off
	global_load_dword v100, v[70:71], off
	v_mad_u64_u32 v[102:103], s[34:35], v134, s81, v[12:13]
	v_mad_u64_u32 v[104:105], s[34:35], v101, s81, v[12:13]
	v_mad_u64_u32 v[106:107], s[34:35], v136, s81, v[12:13]
	v_mad_u64_u32 v[108:109], s[34:35], v135, s81, v[12:13]
	v_mad_u64_u32 v[110:111], s[34:35], v138, s81, v[12:13]
	v_mad_u64_u32 v[112:113], s[34:35], v137, s81, v[12:13]
	v_mad_u64_u32 v[114:115], s[34:35], v140, s81, v[12:13]
	v_mad_u64_u32 v[116:117], s[34:35], v139, s81, v[12:13]
	v_mad_u64_u32 v[118:119], s[34:35], v142, s81, v[12:13]
	v_mad_u64_u32 v[120:121], s[34:35], v141, s81, v[12:13]
	v_mad_u64_u32 v[122:123], s[34:35], v144, s81, v[12:13]
	v_mad_u64_u32 v[124:125], s[34:35], v143, s81, v[12:13]
	v_mad_u64_u32 v[126:127], s[34:35], v146, s81, v[12:13]
	v_mad_u64_u32 v[128:129], s[34:35], v145, s81, v[12:13]
	v_mad_u64_u32 v[130:131], s[34:35], v148, s81, v[12:13]
	v_mad_u64_u32 v[132:133], s[34:35], v147, s81, v[12:13]
	s_waitcnt vmcnt(31)
; #define GAS __attribute__((address_space(1)))
; __device__ __forceinline__ void cvt_item(gfp W, int N, bf16* WT, int Kd, int k0, int n0, int drow0, LAS float* scr, int lane, gfp gk) {
;     ...
;     for (int i = 0; i < 32; ++i) { const int kk = 2 * i + (lane >> 5); scr[kk * 33 + (lane & 31)] = W[(size_t)(k0 + kk) * N + n0 + (lane & 31)]; }
;     const int c = lane & 7;
;     f32x4 ga = (f32x4){1.f, 1.f, 1.f, 1.f}, gb = ga;
;     if (gk != nullptr) { ga = *(const GAS f32x4*)(gk + k0 + 8 * c); gb = *(const GAS f32x4*)(gk + k0 + 8 * c + 4); }
	ds_write_b32 v102, v149
	s_waitcnt vmcnt(30)
	ds_write_b32 v104, v150
	s_waitcnt vmcnt(29)
	ds_write_b32 v106, v151
	s_waitcnt vmcnt(28)
	ds_write_b32 v108, v152
	s_waitcnt vmcnt(27)
	ds_write_b32 v110, v153
	s_waitcnt vmcnt(26)
	ds_write_b32 v112, v154
	s_waitcnt vmcnt(25)
	ds_write_b32 v114, v155
	s_waitcnt vmcnt(24)
	ds_write_b32 v116, v156
	s_waitcnt vmcnt(23)
	ds_write_b32 v118, v157
	s_waitcnt vmcnt(22)
	ds_write_b32 v120, v158
	s_waitcnt vmcnt(21)
	ds_write_b32 v122, v159
	s_waitcnt vmcnt(20)
	ds_write_b32 v124, v160
	s_waitcnt vmcnt(19)
	ds_write_b32 v126, v161
	s_waitcnt vmcnt(18)
	ds_write_b32 v128, v162
	s_waitcnt vmcnt(17)
	ds_write_b32 v130, v163
	s_waitcnt vmcnt(16)
	ds_write_b32 v132, v164
	v_mad_u64_u32 v[4:5], s[34:35], v39, s81, v[12:13]
	v_mad_u64_u32 v[6:7], s[34:35], v0, s81, v[12:13]
	v_mad_u64_u32 v[8:9], s[34:35], v72, s81, v[12:13]
	v_mad_u64_u32 v[46:47], s[34:35], v45, s81, v[12:13]
	v_mad_u64_u32 v[48:49], s[34:35], v74, s81, v[12:13]
	v_mad_u64_u32 v[50:51], s[34:35], v73, s81, v[12:13]
	v_mad_u64_u32 v[52:53], s[34:35], v76, s81, v[12:13]
	v_mad_u64_u32 v[54:55], s[34:35], v75, s81, v[12:13]
	v_mad_u64_u32 v[56:57], s[34:35], v78, s81, v[12:13]
	v_mad_u64_u32 v[58:59], s[34:35], v77, s81, v[12:13]
	v_mad_u64_u32 v[60:61], s[34:35], v80, s81, v[12:13]
	v_mad_u64_u32 v[62:63], s[34:35], v79, s81, v[12:13]
	v_mad_u64_u32 v[64:65], s[34:35], v82, s81, v[12:13]
	v_mad_u64_u32 v[66:67], s[34:35], v81, s81, v[12:13]
	v_mad_u64_u32 v[68:69], s[34:35], v84, s81, v[12:13]
	v_mad_u64_u32 v[70:71], s[34:35], v83, s81, v[12:13]
	s_waitcnt vmcnt(15)
	ds_write_b32 v4, v85
	s_waitcnt vmcnt(14)
	ds_write_b32 v6, v86
	s_waitcnt vmcnt(13)
	ds_write_b32 v8, v87
	s_waitcnt vmcnt(12)
	ds_write_b32 v46, v88
	s_waitcnt vmcnt(11)
	ds_write_b32 v48, v89
	s_waitcnt vmcnt(10)
	ds_write_b32 v50, v90
	s_waitcnt vmcnt(9)
	ds_write_b32 v52, v91
	s_waitcnt vmcnt(8)
	ds_write_b32 v54, v92
	s_waitcnt vmcnt(7)
	ds_write_b32 v56, v93
	s_waitcnt vmcnt(6)
	ds_write_b32 v58, v94
	s_waitcnt vmcnt(5)
	ds_write_b32 v60, v95
	s_waitcnt vmcnt(4)
	ds_write_b32 v62, v96
	s_waitcnt vmcnt(3)
	ds_write_b32 v64, v97
	s_waitcnt vmcnt(2)
	ds_write_b32 v66, v98
	s_waitcnt vmcnt(1)
	ds_write_b32 v68, v99
	s_waitcnt vmcnt(0)
	ds_write_b32 v70, v100
	s_add_i32 s30, s30, 16
	s_add_i32 s27, s27, 16
	s_add_i32 s31, s31, -16
	s_cmp_lg_u32 s31, 0
	s_lshl_b64 s[26:27], s[8:9], 2
	s_add_u32 s22, s22, s26
	s_addc_u32 s23, s23, s27
	s_and_b32 s25, s25, 0xffff
	s_cmp_eq_u64 s[22:23], 0
	s_cbranch_scc1 .LBB0_180
	s_lshl_b32 s26, s25, 2
	s_add_u32 s22, s22, s26
	s_addc_u32 s23, s23, 0
	v_lshlrev_b32_e32 v0, 2, v14
	global_load_dwordx4 v[2:5], v0, s[22:23] offset:16
	global_load_dwordx4 v[6:9], v0, s[22:23]
	s_branch .LBB0_181

; __device__ __forceinline__ void cvt_item(gfp W, int N, bf16* WT, int Kd, int k0, int n0, int drow0, LAS float* scr, int lane, gfp gk) {
; #pragma unroll 8
;     for (int i = 0; i < 32; ++i) { const int kk = 2 * i + (lane >> 5); scr[kk * 33 + (lane & 31)] = W[(size_t)(k0 + kk) * N + n0 + (lane & 31)]; }
.LBB0_200:
	s_lshl_b32 s33, s26, 1
	s_lshl_b32 s34, s30, 1
	v_or_b32_e32 v101, s33, v11
	v_or_b32_e32 v134, s34, v10
	s_add_i32 s35, s33, 4
	s_add_i32 s36, s34, 4
	s_add_i32 s37, s33, 8
	s_add_i32 s38, s34, 8
	s_add_i32 s39, s33, 12
	s_add_i32 s40, s34, 12
	s_add_i32 s41, s33, 16
	s_add_i32 s42, s34, 16
	s_add_i32 s43, s33, 20
	s_add_i32 s44, s34, 20
	s_add_i32 s45, s33, 24
	s_add_i32 s46, s34, 24
	s_add_i32 s33, s33, 28
	s_add_i32 s34, s34, 28
	v_add_u32_e32 v102, s22, v134
	v_or_b32_e32 v135, s35, v11
	v_or_b32_e32 v136, s36, v10
	v_or_b32_e32 v137, s37, v11
	v_or_b32_e32 v138, s38, v10
	v_or_b32_e32 v139, s39, v11
	v_or_b32_e32 v140, s40, v10
	v_or_b32_e32 v141, s41, v11
	v_or_b32_e32 v142, s42, v10
	v_or_b32_e32 v143, s43, v11
	v_or_b32_e32 v144, s44, v10
	v_or_b32_e32 v145, s45, v11
	v_or_b32_e32 v146, s46, v10
	v_or_b32_e32 v147, s33, v11
	v_or_b32_e32 v148, s34, v10
	v_add_u32_e32 v104, s25, v101
	v_mad_i64_i32 v[102:103], s[34:35], v102, s74, v[2:3]
	v_add_u32_e32 v108, s25, v135
	v_add_u32_e32 v106, s22, v136
	v_add_u32_e32 v112, s25, v137
	v_add_u32_e32 v110, s22, v138
	v_add_u32_e32 v116, s25, v139
	v_add_u32_e32 v114, s22, v140
	v_add_u32_e32 v120, s25, v141
	v_add_u32_e32 v118, s22, v142
	v_add_u32_e32 v124, s25, v143
	v_add_u32_e32 v122, s22, v144
	v_add_u32_e32 v128, s25, v145
	v_add_u32_e32 v126, s22, v146
	v_add_u32_e32 v132, s25, v147
	v_add_u32_e32 v130, s22, v148
	v_mad_i64_i32 v[104:105], s[34:35], v104, s74, v[2:3]
	v_mad_i64_i32 v[106:107], s[34:35], v106, s74, v[2:3]
	v_mad_i64_i32 v[108:109], s[34:35], v108, s74, v[2:3]
	v_mad_i64_i32 v[110:111], s[34:35], v110, s74, v[2:3]
	v_mad_i64_i32 v[112:113], s[34:35], v112, s74, v[2:3]
	v_mad_i64_i32 v[114:115], s[34:35], v114, s74, v[2:3]
	v_mad_i64_i32 v[116:117], s[34:35], v116, s74, v[2:3]
	v_mad_i64_i32 v[118:119], s[34:35], v118, s74, v[2:3]
	v_mad_i64_i32 v[120:121], s[34:35], v120, s74, v[2:3]
	v_mad_i64_i32 v[122:123], s[34:35], v122, s74, v[2:3]
	v_mad_i64_i32 v[124:125], s[34:35], v124, s74, v[2:3]
	v_mad_i64_i32 v[126:127], s[34:35], v126, s74, v[2:3]
	v_mad_i64_i32 v[128:129], s[34:35], v128, s74, v[2:3]
	v_mad_i64_i32 v[130:131], s[34:35], v130, s74, v[2:3]
	v_mad_i64_i32 v[132:133], s[34:35], v132, s74, v[2:3]
	global_load_dword v149, v[102:103], off
	global_load_dword v150, v[104:105], off
	global_load_dword v151, v[106:107], off
	global_load_dword v152, v[108:109], off
	global_load_dword v153, v[110:111], off
	global_load_dword v154, v[112:113], off
	global_load_dword v155, v[114:115], off
	global_load_dword v156, v[116:117], off
	global_load_dword v157, v[118:119], off
	global_load_dword v158, v[120:121], off
	global_load_dword v159, v[122:123], off
	global_load_dword v160, v[124:125], off
	global_load_dword v161, v[126:127], off
	global_load_dword v162, v[128:129], off
	global_load_dword v163, v[130:131], off
	global_load_dword v164, v[132:133], off
	s_add_i32 s30, s30, 16
	s_add_i32 s26, s26, 16
	s_add_i32 s31, s31, -16
	s_cmp_lg_u32 s31, 0
	s_lshl_b32 s33, s26, 1
	s_lshl_b32 s34, s30, 1
	v_or_b32_e32 v0, s33, v11
	v_or_b32_e32 v39, s34, v10
	s_add_i32 s35, s33, 4
	s_add_i32 s36, s34, 4
	s_add_i32 s37, s33, 8
	s_add_i32 s38, s34, 8
	s_add_i32 s39, s33, 12
	s_add_i32 s40, s34, 12
	s_add_i32 s41, s33, 16
	s_add_i32 s42, s34, 16
	s_add_i32 s43, s33, 20
	s_add_i32 s44, s34, 20
	s_add_i32 s45, s33, 24
	s_add_i32 s46, s34, 24
	s_add_i32 s33, s33, 28
	s_add_i32 s34, s34, 28
	v_add_u32_e32 v4, s22, v39
	v_or_b32_e32 v45, s35, v11
	v_or_b32_e32 v72, s36, v10
	v_or_b32_e32 v73, s37, v11
	v_or_b32_e32 v74, s38, v10
	v_or_b32_e32 v75, s39, v11
	v_or_b32_e32 v76, s40, v10
	v_or_b32_e32 v77, s41, v11
	v_or_b32_e32 v78, s42, v10
	v_or_b32_e32 v79, s43, v11
	v_or_b32_e32 v80, s44, v10
	v_or_b32_e32 v81, s45, v11
	v_or_b32_e32 v82, s46, v10
	v_or_b32_e32 v83, s33, v11
	v_or_b32_e32 v84, s34, v10
	v_add_u32_e32 v6, s25, v0
	v_mad_i64_i32 v[4:5], s[34:35], v4, s74, v[2:3]
	v_add_u32_e32 v46, s25, v45
	v_add_u32_e32 v8, s22, v72
	v_add_u32_e32 v50, s25, v73
	v_add_u32_e32 v48, s22, v74
	v_add_u32_e32 v54, s25, v75
	v_add_u32_e32 v52, s22, v76
	v_add_u32_e32 v58, s25, v77
	v_add_u32_e32 v56, s22, v78
	v_add_u32_e32 v62, s25, v79
	v_add_u32_e32 v60, s22, v80
	v_add_u32_e32 v66, s25, v81
	v_add_u32_e32 v64, s22, v82
	v_add_u32_e32 v70, s25, v83
	v_add_u32_e32 v68, s22, v84
	v_mad_i64_i32 v[6:7], s[34:35], v6, s74, v[2:3]
	v_mad_i64_i32 v[8:9], s[34:35], v8, s74, v[2:3]
	v_mad_i64_i32 v[46:47], s[34:35], v46, s74, v[2:3]
	v_mad_i64_i32 v[48:49], s[34:35], v48, s74, v[2:3]
	v_mad_i64_i32 v[50:51], s[34:35], v50, s74, v[2:3]
	v_mad_i64_i32 v[52:53], s[34:35], v52, s74, v[2:3]
	v_mad_i64_i32 v[54:55], s[34:35], v54, s74, v[2:3]
	v_mad_i64_i32 v[56:57], s[34:35], v56, s74, v[2:3]
	v_mad_i64_i32 v[58:59], s[34:35], v58, s74, v[2:3]
	v_mad_i64_i32 v[60:61], s[34:35], v60, s74, v[2:3]
	v_mad_i64_i32 v[62:63], s[34:35], v62, s74, v[2:3]
	v_mad_i64_i32 v[64:65], s[34:35], v64, s74, v[2:3]
	v_mad_i64_i32 v[66:67], s[34:35], v66, s74, v[2:3]
	v_mad_i64_i32 v[68:69], s[34:35], v68, s74, v[2:3]
	v_mad_i64_i32 v[70:71], s[34:35], v70, s74, v[2:3]
	global_load_dword v85, v[4:5], off
	global_load_dword v86, v[6:7], off
	global_load_dword v87, v[8:9], off
	global_load_dword v88, v[46:47], off
	global_load_dword v89, v[48:49], off
	global_load_dword v90, v[50:51], off
	global_load_dword v91, v[52:53], off
	global_load_dword v92, v[54:55], off
	global_load_dword v93, v[56:57], off
	global_load_dword v94, v[58:59], off
	global_load_dword v95, v[60:61], off
	global_load_dword v96, v[62:63], off
	global_load_dword v97, v[64:65], off
	global_load_dword v98, v[66:67], off
	global_load_dword v99, v[68:69], off
	global_load_dword v100, v[70:71], off
	v_mad_u64_u32 v[102:103], s[34:35], v134, s81, v[12:13]
	v_mad_u64_u32 v[104:105], s[34:35], v101, s81, v[12:13]
	v_mad_u64_u32 v[106:107], s[34:35], v136, s81, v[12:13]
	v_mad_u64_u32 v[108:109], s[34:35], v135, s81, v[12:13]
	v_mad_u64_u32 v[110:111], s[34:35], v138, s81, v[12:13]
	v_mad_u64_u32 v[112:113], s[34:35], v137, s81, v[12:13]
	v_mad_u64_u32 v[114:115], s[34:35], v140, s81, v[12:13]
	v_mad_u64_u32 v[116:117], s[34:35], v139, s81, v[12:13]
	v_mad_u64_u32 v[118:119], s[34:35], v142, s81, v[12:13]
	v_mad_u64_u32 v[120:121], s[34:35], v141, s81, v[12:13]
	v_mad_u64_u32 v[122:123], s[34:35], v144, s81, v[12:13]
	v_mad_u64_u32 v[124:125], s[34:35], v143, s81, v[12:13]
	v_mad_u64_u32 v[126:127], s[34:35], v146, s81, v[12:13]
	v_mad_u64_u32 v[128:129], s[34:35], v145, s81, v[12:13]
	v_mad_u64_u32 v[130:131], s[34:35], v148, s81, v[12:13]
	v_mad_u64_u32 v[132:133], s[34:35], v147, s81, v[12:13]
	s_waitcnt vmcnt(31)
; #define GAS __attribute__((address_space(1)))
; __device__ __forceinline__ void cvt_item(gfp W, int N, bf16* WT, int Kd, int k0, int n0, int drow0, LAS float* scr, int lane, gfp gk) {
;     ...
;     for (int i = 0; i < 32; ++i) { const int kk = 2 * i + (lane >> 5); scr[kk * 33 + (lane & 31)] = W[(size_t)(k0 + kk) * N + n0 + (lane & 31)]; }
;     const int c = lane & 7;
;     f32x4 ga = (f32x4){1.f, 1.f, 1.f, 1.f}, gb = ga;
;     if (gk != nullptr) { ga = *(const GAS f32x4*)(gk + k0 + 8 * c); gb = *(const GAS f32x4*)(gk + k0 + 8 * c + 4); }
	ds_write_b32 v102, v149
	s_waitcnt vmcnt(30)
	ds_write_b32 v104, v150
	s_waitcnt vmcnt(29)
	ds_write_b32 v106, v151
	s_waitcnt vmcnt(28)
	ds_write_b32 v108, v152
	s_waitcnt vmcnt(27)
	ds_write_b32 v110, v153
	s_waitcnt vmcnt(26)
	ds_write_b32 v112, v154
	s_waitcnt vmcnt(25)
	ds_write_b32 v114, v155
	s_waitcnt vmcnt(24)
	ds_write_b32 v116, v156
	s_waitcnt vmcnt(23)
	ds_write_b32 v118, v157
	s_waitcnt vmcnt(22)
	ds_write_b32 v120, v158
	s_waitcnt vmcnt(21)
	ds_write_b32 v122, v159
	s_waitcnt vmcnt(20)
	ds_write_b32 v124, v160
	s_waitcnt vmcnt(19)
	ds_write_b32 v126, v161
	s_waitcnt vmcnt(18)
	ds_write_b32 v128, v162
	s_waitcnt vmcnt(17)
	ds_write_b32 v130, v163
	s_waitcnt vmcnt(16)
	ds_write_b32 v132, v164
	v_mad_u64_u32 v[4:5], s[34:35], v39, s81, v[12:13]
	v_mad_u64_u32 v[6:7], s[34:35], v0, s81, v[12:13]
	v_mad_u64_u32 v[8:9], s[34:35], v72, s81, v[12:13]
	v_mad_u64_u32 v[46:47], s[34:35], v45, s81, v[12:13]
	v_mad_u64_u32 v[48:49], s[34:35], v74, s81, v[12:13]
	v_mad_u64_u32 v[50:51], s[34:35], v73, s81, v[12:13]
	v_mad_u64_u32 v[52:53], s[34:35], v76, s81, v[12:13]
	v_mad_u64_u32 v[54:55], s[34:35], v75, s81, v[12:13]
	v_mad_u64_u32 v[56:57], s[34:35], v78, s81, v[12:13]
	v_mad_u64_u32 v[58:59], s[34:35], v77, s81, v[12:13]
	v_mad_u64_u32 v[60:61], s[34:35], v80, s81, v[12:13]
	v_mad_u64_u32 v[62:63], s[34:35], v79, s81, v[12:13]
	v_mad_u64_u32 v[64:65], s[34:35], v82, s81, v[12:13]
	v_mad_u64_u32 v[66:67], s[34:35], v81, s81, v[12:13]
	v_mad_u64_u32 v[68:69], s[34:35], v84, s81, v[12:13]
	v_mad_u64_u32 v[70:71], s[34:35], v83, s81, v[12:13]
	s_waitcnt vmcnt(15)
	ds_write_b32 v4, v85
	s_waitcnt vmcnt(14)
	ds_write_b32 v6, v86
	s_waitcnt vmcnt(13)
	ds_write_b32 v8, v87
	s_waitcnt vmcnt(12)
	ds_write_b32 v46, v88
	s_waitcnt vmcnt(11)
	ds_write_b32 v48, v89
	s_waitcnt vmcnt(10)
	ds_write_b32 v50, v90
	s_waitcnt vmcnt(9)
	ds_write_b32 v52, v91
	s_waitcnt vmcnt(8)
	ds_write_b32 v54, v92
	s_waitcnt vmcnt(7)
	ds_write_b32 v56, v93
	s_waitcnt vmcnt(6)
	ds_write_b32 v58, v94
	s_waitcnt vmcnt(5)
	ds_write_b32 v60, v95
	s_waitcnt vmcnt(4)
	ds_write_b32 v62, v96
	s_waitcnt vmcnt(3)
	ds_write_b32 v64, v97
	s_waitcnt vmcnt(2)
	ds_write_b32 v66, v98
	s_waitcnt vmcnt(1)
	ds_write_b32 v68, v99
	s_waitcnt vmcnt(0)
	ds_write_b32 v70, v100
	s_add_i32 s30, s30, 16
	s_add_i32 s26, s26, 16
	s_add_i32 s31, s31, -16
	s_cmp_lg_u32 s31, 0
	s_lshl_b64 s[30:31], s[8:9], 2
	s_add_u32 s26, s23, s30
	s_addc_u32 s27, s27, s31
	s_ashr_i32 s23, s22, 31
	s_cmp_eq_u64 s[26:27], 0
	s_cbranch_scc0 .LBB0_107
	v_mov_b32_e32 v2, 1.0
	v_mov_b32_e32 v3, 1.0
	v_mov_b32_e32 v4, 1.0
	v_mov_b32_e32 v5, 1.0
	v_mov_b32_e32 v6, 1.0
	v_mov_b32_e32 v7, 1.0
	v_mov_b32_e32 v8, 1.0
	v_mov_b32_e32 v9, 1.0
	s_branch .LBB0_108
